# P15 hand-written: 8-byte coalesced accesses, K~^T tile stores as complete 32-byte sectors (two back-to-back 16-byte stores per channel per 16 tokens)
# speedup vs baseline: 1.0136x; 1.0024x over previous
; DEV int tidx() { return tidx_full() & 255; }
; #define VBID ((int)blockIdx.x * 2 + vhalf())
; DEV void phase_p15(const Params& p, int g) {
;     ...
;   for (int it = VBID; it < 1024; it += NVB) {
;     const int tid = tidx();
;     const int cidx = it >> 1, dir = it & 1;
;     u16* Qp = QK + (size_t)(2 * dir) * NTOK * 512;
;     u16* Kp = Qp + (size_t)NTOK * 512;
;     float lb[2], G[2];
; #pragma unroll
;     for (int cc = 0; cc < 2; ++cc) {
;       const int c = tid + 256 * cc;
;       const float a0 = p.in[I_LB][(0 * 2 + dir) * 512 + c];
;       const float a1 = p.in[I_LB][(1 * 2 + dir) * 512 + c];
;       lb[cc] = 1.f / (1.f + __expf(a1 - a0));
;       G[cc] = 0.f;
;     }
;     u16 xr[3][2][8], qr[3][2][8];
;     ...
;     P15_LOAD(0, 0);
;     P15_LOAD(1, 1);
.LBB0_617:
	v_readfirstlane_b32 s16, v202
	v_readlane_b32 s19, v251, 62
	v_readlane_b32 s0, v251, 41
	v_readlane_b32 s1, v251, 42
	v_readlane_b32 s2, v252, 19
	v_readlane_b32 s3, v252, 20
	v_readlane_b32 s4, v251, 54
	v_readlane_b32 s5, v251, 55
	v_readlane_b32 s12, v249, 22
	v_readlane_b32 s13, v249, 23
	s_bfe_u32 s17, s16, 0x10008
	s_bfe_u32 s18, s16, 0x20006
	s_lshr_b32 s19, s19, 1
	s_lshr_b32 s8, s18, 1
	s_and_b32 s18, s18, 1
	s_lshl_b32 s8, s8, 8
	s_add_u32 s20, s19, s8
	s_mov_b32 s30, 0x800000
	s_mov_b32 s31, 0x3f317217
	s_mov_b32 s34, 0x7f800000
	v_and_b32_e32 v112, 63, v202
	v_lshlrev_b32_e32 v112, 2, v112
	s_lshl_b32 s8, s18, 8
	v_add_u32_e32 v112, s8, v112
	v_lshlrev_b32_e32 v115, 7, v112
	v_lshlrev_b32_e32 v92, 2, v112
	v_lshlrev_b32_e32 v112, 1, v112
	s_lshl_b32 s8, s17, 10
	s_add_u32 s8, s8, 0x800
	v_add_u32_e32 v113, s8, v112
	v_add_u32_e32 v114, 0x2000000, v112
	s_lshl_b32 s8, s17, 11
	v_add_u32_e32 v93, s8, v92
	v_add_u32_e32 v94, 0x1000, v93
	global_load_dwordx4 v[96:99], v93, s[12:13]
	global_load_dwordx4 v[100:103], v94, s[12:13]
	v_mov_b32_e32 v104, v92
	s_lshl_b32 s8, s17, 9
	s_add_u32 s8, s8, s20
	s_lshl_b32 s8, s8, 11
	s_add_u32 s6, s4, s8
	s_addc_u32 s7, s5, 0
	s_add_u32 s6, s6, 0x3b4c100
	s_addc_u32 s7, s7, 0
	s_lshl_b32 s8, s20, 1
	s_add_u32 s8, s8, s17
	s_lshl_b32 s8, s8, 16
	s_add_u32 s4, s4, s8
	s_addc_u32 s5, s5, 0
	s_add_u32 s4, s4, 0x3d4c100
	s_addc_u32 s5, s5, 0
	s_mul_i32 s8, s17, 0x60
	s_add_u32 s4, s4, s8
	s_addc_u32 s5, s5, 0
	s_lshl_b32 s8, s20, 6
	s_mul_i32 s9, s17, 63
	s_add_u32 s8, s8, s9
	s_mul_i32 s9, s8, 0x1400
	s_add_u32 s0, s0, s9
	s_addc_u32 s1, s1, 0
	s_lshl_b32 s9, s8, 10
	s_add_u32 s2, s2, s9
	s_addc_u32 s3, s3, 0
	s_lshl_b32 s9, s17, 26
	s_add_u32 s2, s2, s9
	s_addc_u32 s3, s3, 0
	s_waitcnt vmcnt(0)
	v_sub_f32_e32 v92, v100, v96
	v_mul_f32_e32 v92, 0x3fb8aa3b, v92
	v_exp_f32_e32 v92, v92
	s_nop 0
	v_add_f32_e32 v92, 1.0, v92
	v_div_scale_f32 v76, s[8:9], v92, v92, 1.0
	v_rcp_f32_e32 v77, v76
	s_nop 0
	v_fma_f32 v78, -v76, v77, 1.0
	v_fmac_f32_e32 v77, v78, v77
	v_div_scale_f32 v78, vcc, 1.0, v92, 1.0
	v_mul_f32_e32 v79, v78, v77
	v_fma_f32 v80, -v76, v79, v78
	v_fmac_f32_e32 v79, v80, v77
	v_fma_f32 v76, -v76, v79, v78
	v_div_fmas_f32 v76, v76, v77, v79
	v_div_fixup_f32 v68, v76, v92, 1.0
	v_sub_f32_e32 v72, 1.0, v68
	v_mov_b32_e32 v64, 0
	v_sub_f32_e32 v93, v101, v97
	v_mul_f32_e32 v93, 0x3fb8aa3b, v93
	v_exp_f32_e32 v93, v93
	s_nop 0
	v_add_f32_e32 v93, 1.0, v93
	v_div_scale_f32 v76, s[8:9], v93, v93, 1.0
	v_rcp_f32_e32 v77, v76
	s_nop 0
	v_fma_f32 v78, -v76, v77, 1.0
	v_fmac_f32_e32 v77, v78, v77
	v_div_scale_f32 v78, vcc, 1.0, v93, 1.0
	v_mul_f32_e32 v79, v78, v77
	v_fma_f32 v80, -v76, v79, v78
	v_fmac_f32_e32 v79, v80, v77
	v_fma_f32 v76, -v76, v79, v78
	v_div_fmas_f32 v76, v76, v77, v79
	v_div_fixup_f32 v69, v76, v93, 1.0
	v_sub_f32_e32 v73, 1.0, v69
	v_mov_b32_e32 v65, 0
	v_sub_f32_e32 v94, v102, v98
	v_mul_f32_e32 v94, 0x3fb8aa3b, v94
	v_exp_f32_e32 v94, v94
	s_nop 0
	v_add_f32_e32 v94, 1.0, v94
	v_div_scale_f32 v76, s[8:9], v94, v94, 1.0
	v_rcp_f32_e32 v77, v76
	s_nop 0
	v_fma_f32 v78, -v76, v77, 1.0
	v_fmac_f32_e32 v77, v78, v77
	v_div_scale_f32 v78, vcc, 1.0, v94, 1.0
	v_mul_f32_e32 v79, v78, v77
	v_fma_f32 v80, -v76, v79, v78
	v_fmac_f32_e32 v79, v80, v77
	v_fma_f32 v76, -v76, v79, v78
	v_div_fmas_f32 v76, v76, v77, v79
	v_div_fixup_f32 v70, v76, v94, 1.0
	v_sub_f32_e32 v74, 1.0, v70
	v_mov_b32_e32 v66, 0
	v_sub_f32_e32 v95, v103, v99
	v_mul_f32_e32 v95, 0x3fb8aa3b, v95
	v_exp_f32_e32 v95, v95
	s_nop 0
	v_add_f32_e32 v95, 1.0, v95
	v_div_scale_f32 v76, s[8:9], v95, v95, 1.0
	v_rcp_f32_e32 v77, v76
	s_nop 0
	v_fma_f32 v78, -v76, v77, 1.0
	v_fmac_f32_e32 v77, v78, v77
	v_div_scale_f32 v78, vcc, 1.0, v95, 1.0
	v_mul_f32_e32 v79, v78, v77
	v_fma_f32 v80, -v76, v79, v78
	v_fmac_f32_e32 v79, v80, v77
	v_fma_f32 v76, -v76, v79, v78
	v_div_fmas_f32 v76, v76, v77, v79
	v_div_fixup_f32 v71, v76, v95, 1.0
	v_sub_f32_e32 v75, 1.0, v71
	v_mov_b32_e32 v67, 0
	v_mov_b32_e32 v115, v115
	v_mov_b32_e32 v109, v104
	v_mov_b32_e32 v164, v104
	s_cmp_eq_u32 s17, 0
	s_cbranch_scc0 .Lp15_d1
	global_load_dwordx2 v[0:1], v113, s[0:1]
	global_load_dwordx2 v[2:3], v112, s[0:1]
	s_add_u32 s0, s0, 0x1400
	s_addc_u32 s1, s1, 0
	global_load_dwordx2 v[4:5], v113, s[0:1]
	global_load_dwordx2 v[6:7], v112, s[0:1]
	s_add_u32 s0, s0, 0x1400
	s_addc_u32 s1, s1, 0
	global_load_dwordx2 v[8:9], v113, s[0:1]
	global_load_dwordx2 v[10:11], v112, s[0:1]
	s_add_u32 s0, s0, 0x1400
	s_addc_u32 s1, s1, 0
	global_load_dwordx2 v[12:13], v113, s[0:1]
	global_load_dwordx2 v[14:15], v112, s[0:1]
	s_add_u32 s0, s0, 0x1400
	s_addc_u32 s1, s1, 0
	global_load_dwordx2 v[16:17], v113, s[0:1]
	global_load_dwordx2 v[18:19], v112, s[0:1]
	s_add_u32 s0, s0, 0x1400
	s_addc_u32 s1, s1, 0
	global_load_dwordx2 v[20:21], v113, s[0:1]
	global_load_dwordx2 v[22:23], v112, s[0:1]
	s_add_u32 s0, s0, 0x1400
	s_addc_u32 s1, s1, 0
	global_load_dwordx2 v[24:25], v113, s[0:1]
	global_load_dwordx2 v[26:27], v112, s[0:1]
	s_add_u32 s0, s0, 0x1400
	s_addc_u32 s1, s1, 0
	global_load_dwordx2 v[28:29], v113, s[0:1]
	global_load_dwordx2 v[30:31], v112, s[0:1]
	s_add_u32 s0, s0, 0x1400
	s_addc_u32 s1, s1, 0
	global_load_dwordx2 v[32:33], v113, s[0:1]
	global_load_dwordx2 v[34:35], v112, s[0:1]
	s_add_u32 s0, s0, 0x1400
	s_addc_u32 s1, s1, 0
	global_load_dwordx2 v[36:37], v113, s[0:1]
	global_load_dwordx2 v[38:39], v112, s[0:1]
	s_add_u32 s0, s0, 0x1400
	s_addc_u32 s1, s1, 0
	global_load_dwordx2 v[40:41], v113, s[0:1]
	global_load_dwordx2 v[42:43], v112, s[0:1]
	s_add_u32 s0, s0, 0x1400
	s_addc_u32 s1, s1, 0
	global_load_dwordx2 v[44:45], v113, s[0:1]
	global_load_dwordx2 v[46:47], v112, s[0:1]
	s_add_u32 s0, s0, 0x1400
	s_addc_u32 s1, s1, 0
	global_load_dwordx2 v[48:49], v113, s[0:1]
	global_load_dwordx2 v[50:51], v112, s[0:1]
	s_add_u32 s0, s0, 0x1400
	s_addc_u32 s1, s1, 0
	global_load_dwordx2 v[52:53], v113, s[0:1]
	global_load_dwordx2 v[54:55], v112, s[0:1]
	s_add_u32 s0, s0, 0x1400
	s_addc_u32 s1, s1, 0
	global_load_dwordx2 v[56:57], v113, s[0:1]
	global_load_dwordx2 v[58:59], v112, s[0:1]
	s_add_u32 s0, s0, 0x1400
	s_addc_u32 s1, s1, 0
	global_load_dwordx2 v[60:61], v113, s[0:1]
	global_load_dwordx2 v[62:63], v112, s[0:1]
	s_add_u32 s0, s0, 0x1400
	s_addc_u32 s1, s1, 0
	s_mov_b32 s35, 0
	s_waitcnt vmcnt(16)
; DEV u16 f2bf(float f) { return (u16)(pack2(f, f) & 0xffffu); }
; DEV float bf2f(u16 h) { return __uint_as_float(((unsigned)h) << 16); }
; DEV float sigmoid_f(float x) { return __builtin_amdgcn_rcpf(1.f + __expf(-x)); }
; DEV void phase_p15(const Params& p, int g) {
;     ...
;       for (int cc = 0; cc < 2; ++cc) {
;         const int c = tid + 256 * cc;
;         unsigned kb[8];
; #pragma unroll
;         for (int e = 0; e < 8; ++e) {
;           const int jj = j8 * 8 + e;
;           const int j = dir ? 63 - jj : jj;
;           const size_t tok = (size_t)cidx * 64 + j;
;           const float f = lb[cc] + (1.f - lb[cc]) * sigmoid_f(bf2f(xr[st][cc][e]));
;           G[cc] += __logf(f);
;           const float eg = __expf(G[cc]), ig = __expf(-G[cc]);
;           Qp[tok * 512 + c] = f2bf(bf2f(qr[st][cc][e]) * eg);
;           const u16 kk = f2bf((1.f - f) * ig);
;           Kp[tok * 512 + c] = kk;
;           kb[e] = kk;
;         }
;         const int s0 = dir ? 56 - 8 * j8 : 8 * j8;
;         uint4 w;
;         w.x = dir ? (kb[7] | (kb[6] << 16)) : (kb[0] | (kb[1] << 16));
;         w.y = dir ? (kb[5] | (kb[4] << 16)) : (kb[2] | (kb[3] << 16));
;         w.z = dir ? (kb[3] | (kb[2] << 16)) : (kb[4] | (kb[5] << 16));
;         w.w = dir ? (kb[1] | (kb[0] << 16)) : (kb[6] | (kb[7] << 16));
;         *(uint4*)(KT + (((size_t)cidx * 2 + dir) * 512 + c) * 64 + s0) = w;
.Lp15_d0_loop:
	s_waitcnt vmcnt(40)
	v_lshlrev_b32_e32 v92, 16, v0
	v_and_b32_e32 v93, 0xffff0000, v0
	v_lshlrev_b32_e32 v94, 16, v1
	v_and_b32_e32 v95, 0xffff0000, v1
	v_mul_f32_e32 v92, 0xbfb8aa3b, v92
	v_mul_f32_e32 v93, 0xbfb8aa3b, v93
	v_mul_f32_e32 v94, 0xbfb8aa3b, v94
	v_mul_f32_e32 v95, 0xbfb8aa3b, v95
	v_exp_f32_e32 v92, v92
	v_exp_f32_e32 v93, v93
	v_exp_f32_e32 v94, v94
	v_exp_f32_e32 v95, v95
	v_add_f32_e32 v92, 1.0, v92
	v_add_f32_e32 v93, 1.0, v93
	v_add_f32_e32 v94, 1.0, v94
	v_add_f32_e32 v95, 1.0, v95
	v_rcp_f32_e32 v92, v92
	v_rcp_f32_e32 v93, v93
	v_rcp_f32_e32 v94, v94
	v_rcp_f32_e32 v95, v95
	v_fma_f32 v96, v72, v92, v68
	v_fma_f32 v97, v73, v93, v69
	v_fma_f32 v98, v74, v94, v70
	v_fma_f32 v99, v75, v95, v71
	v_cmp_gt_f32_e64 s[22:23], s30, v96
	v_cmp_gt_f32_e64 s[24:25], s30, v97
	v_cmp_gt_f32_e64 s[26:27], s30, v98
	v_cmp_gt_f32_e64 s[28:29], s30, v99
	v_cndmask_b32_e64 v92, 0, 32, s[22:23]
	v_cndmask_b32_e64 v93, 0, 32, s[24:25]
	v_cndmask_b32_e64 v94, 0, 32, s[26:27]
	v_cndmask_b32_e64 v95, 0, 32, s[28:29]
	v_ldexp_f32 v92, v96, v92
	v_ldexp_f32 v93, v97, v93
	v_ldexp_f32 v94, v98, v94
	v_ldexp_f32 v95, v99, v95
	v_log_f32_e32 v92, v92
	v_log_f32_e32 v93, v93
	v_log_f32_e32 v94, v94
	v_log_f32_e32 v95, v95
	v_mul_f32_e32 v100, 0x3f317217, v92
	v_mul_f32_e32 v101, 0x3f317217, v93
	v_mul_f32_e32 v102, 0x3f317217, v94
	v_mul_f32_e32 v103, 0x3f317217, v95
	v_fma_f32 v100, v92, s31, -v100
	v_fma_f32 v101, v93, s31, -v101
	v_fma_f32 v102, v94, s31, -v102
	v_fma_f32 v103, v95, s31, -v103
	v_fmac_f32_e32 v100, 0x3377d1cf, v92
	v_fmac_f32_e32 v101, 0x3377d1cf, v93
	v_fmac_f32_e32 v102, 0x3377d1cf, v94
	v_fmac_f32_e32 v103, 0x3377d1cf, v95
	v_fmac_f32_e32 v100, 0x3f317217, v92
	v_fmac_f32_e32 v101, 0x3f317217, v93
	v_fmac_f32_e32 v102, 0x3f317217, v94
	v_fmac_f32_e32 v103, 0x3f317217, v95
	v_cmp_lt_f32_e64 vcc, |v92|, s34
	v_cndmask_b32_e32 v92, v92, v100, vcc
	v_cmp_lt_f32_e64 vcc, |v93|, s34
	v_cndmask_b32_e32 v93, v93, v101, vcc
	v_cmp_lt_f32_e64 vcc, |v94|, s34
	v_cndmask_b32_e32 v94, v94, v102, vcc
	v_cmp_lt_f32_e64 vcc, |v95|, s34
	v_cndmask_b32_e32 v95, v95, v103, vcc
	v_cndmask_b32_e64 v100, 0, v213, s[22:23]
	v_cndmask_b32_e64 v101, 0, v213, s[24:25]
	v_cndmask_b32_e64 v102, 0, v213, s[26:27]
	v_cndmask_b32_e64 v103, 0, v213, s[28:29]
	v_sub_f32_e32 v92, v92, v100
	v_sub_f32_e32 v93, v93, v101
	v_sub_f32_e32 v94, v94, v102
	v_sub_f32_e32 v95, v95, v103
	v_add_f32_e32 v64, v64, v92
	v_add_f32_e32 v65, v65, v93
	v_add_f32_e32 v66, v66, v94
	v_add_f32_e32 v67, v67, v95
	v_mul_f32_e32 v92, 0xbfb8aa3b, v64
	v_mul_f32_e32 v93, 0xbfb8aa3b, v65
	v_mul_f32_e32 v94, 0xbfb8aa3b, v66
	v_mul_f32_e32 v95, 0xbfb8aa3b, v67
	v_mul_f32_e32 v100, 0x3fb8aa3b, v64
	v_mul_f32_e32 v101, 0x3fb8aa3b, v65
	v_mul_f32_e32 v102, 0x3fb8aa3b, v66
	v_mul_f32_e32 v103, 0x3fb8aa3b, v67
	v_exp_f32_e32 v92, v92
	v_exp_f32_e32 v93, v93
	v_exp_f32_e32 v94, v94
	v_exp_f32_e32 v95, v95
	v_exp_f32_e32 v100, v100
	v_exp_f32_e32 v101, v101
	v_exp_f32_e32 v102, v102
	v_exp_f32_e32 v103, v103
	v_sub_f32_e32 v96, 1.0, v96
	v_sub_f32_e32 v97, 1.0, v97
	v_sub_f32_e32 v98, 1.0, v98
	v_sub_f32_e32 v99, 1.0, v99
	v_mul_f32_e32 v96, v96, v92
	v_mul_f32_e32 v97, v97, v93
	v_mul_f32_e32 v98, v98, v94
	v_mul_f32_e32 v99, v99, v95
	v_lshlrev_b32_e32 v92, 16, v2
	v_and_b32_e32 v93, 0xffff0000, v2
	v_lshlrev_b32_e32 v94, 16, v3
	v_and_b32_e32 v95, 0xffff0000, v3
	v_mul_f32_e32 v92, v92, v100
	v_mul_f32_e32 v93, v93, v101
	v_mul_f32_e32 v94, v94, v102
	v_mul_f32_e32 v95, v95, v103
	v_cvt_pk_bf16_f32 v108, v92, v93
	v_cvt_pk_bf16_f32 v109, v94, v95
	v_cvt_pk_bf16_f32 v110, v96, v97
	v_cvt_pk_bf16_f32 v111, v98, v99
	global_store_dwordx2 v112, v[108:109], s[2:3]
	global_store_dwordx2 v114, v[110:111], s[2:3]
	s_add_u32 s2, s2, 0x400
	s_addc_u32 s3, s3, 0
	v_mov_b32_e32 v104, v96
	v_mov_b32_e32 v105, v97
	v_mov_b32_e32 v106, v98
	v_mov_b32_e32 v107, v99
	v_lshlrev_b32_e32 v92, 16, v4
	v_and_b32_e32 v93, 0xffff0000, v4
	v_lshlrev_b32_e32 v94, 16, v5
	v_and_b32_e32 v95, 0xffff0000, v5
	v_mul_f32_e32 v92, 0xbfb8aa3b, v92
	v_mul_f32_e32 v93, 0xbfb8aa3b, v93
	v_mul_f32_e32 v94, 0xbfb8aa3b, v94
	v_mul_f32_e32 v95, 0xbfb8aa3b, v95
	v_exp_f32_e32 v92, v92
	v_exp_f32_e32 v93, v93
	v_exp_f32_e32 v94, v94
	v_exp_f32_e32 v95, v95
	v_add_f32_e32 v92, 1.0, v92
	v_add_f32_e32 v93, 1.0, v93
	v_add_f32_e32 v94, 1.0, v94
	v_add_f32_e32 v95, 1.0, v95
	v_rcp_f32_e32 v92, v92
	v_rcp_f32_e32 v93, v93
	v_rcp_f32_e32 v94, v94
	v_rcp_f32_e32 v95, v95
	v_fma_f32 v96, v72, v92, v68
	v_fma_f32 v97, v73, v93, v69
	v_fma_f32 v98, v74, v94, v70
	v_fma_f32 v99, v75, v95, v71
	v_cmp_gt_f32_e64 s[22:23], s30, v96
	v_cmp_gt_f32_e64 s[24:25], s30, v97
	v_cmp_gt_f32_e64 s[26:27], s30, v98
	v_cmp_gt_f32_e64 s[28:29], s30, v99
	v_cndmask_b32_e64 v92, 0, 32, s[22:23]
	v_cndmask_b32_e64 v93, 0, 32, s[24:25]
	v_cndmask_b32_e64 v94, 0, 32, s[26:27]
	v_cndmask_b32_e64 v95, 0, 32, s[28:29]
	v_ldexp_f32 v92, v96, v92
	v_ldexp_f32 v93, v97, v93
	v_ldexp_f32 v94, v98, v94
	v_ldexp_f32 v95, v99, v95
	v_log_f32_e32 v92, v92
	v_log_f32_e32 v93, v93
	v_log_f32_e32 v94, v94
	v_log_f32_e32 v95, v95
	v_mul_f32_e32 v100, 0x3f317217, v92
	v_mul_f32_e32 v101, 0x3f317217, v93
	v_mul_f32_e32 v102, 0x3f317217, v94
	v_mul_f32_e32 v103, 0x3f317217, v95
	v_fma_f32 v100, v92, s31, -v100
	v_fma_f32 v101, v93, s31, -v101
	v_fma_f32 v102, v94, s31, -v102
	v_fma_f32 v103, v95, s31, -v103
	v_fmac_f32_e32 v100, 0x3377d1cf, v92
	v_fmac_f32_e32 v101, 0x3377d1cf, v93
	v_fmac_f32_e32 v102, 0x3377d1cf, v94
	v_fmac_f32_e32 v103, 0x3377d1cf, v95
	v_fmac_f32_e32 v100, 0x3f317217, v92
	v_fmac_f32_e32 v101, 0x3f317217, v93
	v_fmac_f32_e32 v102, 0x3f317217, v94
; DEV u16 f2bf(float f) { return (u16)(pack2(f, f) & 0xffffu); }
; DEV float bf2f(u16 h) { return __uint_as_float(((unsigned)h) << 16); }
; DEV float sigmoid_f(float x) { return __builtin_amdgcn_rcpf(1.f + __expf(-x)); }
; DEV void phase_p15(const Params& p, int g) {
;     ...
;       for (int cc = 0; cc < 2; ++cc) {
;         const int c = tid + 256 * cc;
;         unsigned kb[8];
; #pragma unroll
;         for (int e = 0; e < 8; ++e) {
;           const int jj = j8 * 8 + e;
;           const int j = dir ? 63 - jj : jj;
;           const size_t tok = (size_t)cidx * 64 + j;
;           const float f = lb[cc] + (1.f - lb[cc]) * sigmoid_f(bf2f(xr[st][cc][e]));
;           G[cc] += __logf(f);
;           const float eg = __expf(G[cc]), ig = __expf(-G[cc]);
;           Qp[tok * 512 + c] = f2bf(bf2f(qr[st][cc][e]) * eg);
;           const u16 kk = f2bf((1.f - f) * ig);
;           Kp[tok * 512 + c] = kk;
;           kb[e] = kk;
;         }
;         const int s0 = dir ? 56 - 8 * j8 : 8 * j8;
;         uint4 w;
;         w.x = dir ? (kb[7] | (kb[6] << 16)) : (kb[0] | (kb[1] << 16));
;         w.y = dir ? (kb[5] | (kb[4] << 16)) : (kb[2] | (kb[3] << 16));
;         w.z = dir ? (kb[3] | (kb[2] << 16)) : (kb[4] | (kb[5] << 16));
;         w.w = dir ? (kb[1] | (kb[0] << 16)) : (kb[6] | (kb[7] << 16));
;         *(uint4*)(KT + (((size_t)cidx * 2 + dir) * 512 + c) * 64 + s0) = w;
	v_fmac_f32_e32 v103, 0x3f317217, v95
	v_cmp_lt_f32_e64 vcc, |v92|, s34
	v_cndmask_b32_e32 v92, v92, v100, vcc
	v_cmp_lt_f32_e64 vcc, |v93|, s34
	v_cndmask_b32_e32 v93, v93, v101, vcc
	v_cmp_lt_f32_e64 vcc, |v94|, s34
	v_cndmask_b32_e32 v94, v94, v102, vcc
	v_cmp_lt_f32_e64 vcc, |v95|, s34
	v_cndmask_b32_e32 v95, v95, v103, vcc
	v_cndmask_b32_e64 v100, 0, v213, s[22:23]
	v_cndmask_b32_e64 v101, 0, v213, s[24:25]
	v_cndmask_b32_e64 v102, 0, v213, s[26:27]
	v_cndmask_b32_e64 v103, 0, v213, s[28:29]
	v_sub_f32_e32 v92, v92, v100
	v_sub_f32_e32 v93, v93, v101
	v_sub_f32_e32 v94, v94, v102
	v_sub_f32_e32 v95, v95, v103
	v_add_f32_e32 v64, v64, v92
	v_add_f32_e32 v65, v65, v93
	v_add_f32_e32 v66, v66, v94
	v_add_f32_e32 v67, v67, v95
	v_mul_f32_e32 v92, 0xbfb8aa3b, v64
	v_mul_f32_e32 v93, 0xbfb8aa3b, v65
	v_mul_f32_e32 v94, 0xbfb8aa3b, v66
	v_mul_f32_e32 v95, 0xbfb8aa3b, v67
	v_mul_f32_e32 v100, 0x3fb8aa3b, v64
	v_mul_f32_e32 v101, 0x3fb8aa3b, v65
	v_mul_f32_e32 v102, 0x3fb8aa3b, v66
	v_mul_f32_e32 v103, 0x3fb8aa3b, v67
	v_exp_f32_e32 v92, v92
	v_exp_f32_e32 v93, v93
	v_exp_f32_e32 v94, v94
	v_exp_f32_e32 v95, v95
	v_exp_f32_e32 v100, v100
	v_exp_f32_e32 v101, v101
	v_exp_f32_e32 v102, v102
	v_exp_f32_e32 v103, v103
	v_sub_f32_e32 v96, 1.0, v96
	v_sub_f32_e32 v97, 1.0, v97
	v_sub_f32_e32 v98, 1.0, v98
	v_sub_f32_e32 v99, 1.0, v99
	v_mul_f32_e32 v96, v96, v92
	v_mul_f32_e32 v97, v97, v93
	v_mul_f32_e32 v98, v98, v94
	v_mul_f32_e32 v99, v99, v95
	v_lshlrev_b32_e32 v92, 16, v6
	v_and_b32_e32 v93, 0xffff0000, v6
	v_lshlrev_b32_e32 v94, 16, v7
	v_and_b32_e32 v95, 0xffff0000, v7
	v_mul_f32_e32 v92, v92, v100
	v_mul_f32_e32 v93, v93, v101
	v_mul_f32_e32 v94, v94, v102
	v_mul_f32_e32 v95, v95, v103
	v_cvt_pk_bf16_f32 v108, v92, v93
	v_cvt_pk_bf16_f32 v109, v94, v95
	v_cvt_pk_bf16_f32 v110, v96, v97
	v_cvt_pk_bf16_f32 v111, v98, v99
	global_store_dwordx2 v112, v[108:109], s[2:3]
	global_store_dwordx2 v114, v[110:111], s[2:3]
	s_add_u32 s2, s2, 0x400
	s_addc_u32 s3, s3, 0
	v_cvt_pk_bf16_f32 v116, v104, v96
	v_cvt_pk_bf16_f32 v124, v105, v97
	v_cvt_pk_bf16_f32 v132, v106, v98
	v_cvt_pk_bf16_f32 v140, v107, v99
	v_lshlrev_b32_e32 v92, 16, v8
	v_and_b32_e32 v93, 0xffff0000, v8
	v_lshlrev_b32_e32 v94, 16, v9
	v_and_b32_e32 v95, 0xffff0000, v9
	v_mul_f32_e32 v92, 0xbfb8aa3b, v92
	v_mul_f32_e32 v93, 0xbfb8aa3b, v93
	v_mul_f32_e32 v94, 0xbfb8aa3b, v94
	v_mul_f32_e32 v95, 0xbfb8aa3b, v95
	v_exp_f32_e32 v92, v92
	v_exp_f32_e32 v93, v93
	v_exp_f32_e32 v94, v94
	v_exp_f32_e32 v95, v95
	v_add_f32_e32 v92, 1.0, v92
	v_add_f32_e32 v93, 1.0, v93
	v_add_f32_e32 v94, 1.0, v94
	v_add_f32_e32 v95, 1.0, v95
	v_rcp_f32_e32 v92, v92
	v_rcp_f32_e32 v93, v93
	v_rcp_f32_e32 v94, v94
	v_rcp_f32_e32 v95, v95
	v_fma_f32 v96, v72, v92, v68
	v_fma_f32 v97, v73, v93, v69
	v_fma_f32 v98, v74, v94, v70
	v_fma_f32 v99, v75, v95, v71
	v_cmp_gt_f32_e64 s[22:23], s30, v96
	v_cmp_gt_f32_e64 s[24:25], s30, v97
	v_cmp_gt_f32_e64 s[26:27], s30, v98
	v_cmp_gt_f32_e64 s[28:29], s30, v99
	v_cndmask_b32_e64 v92, 0, 32, s[22:23]
	v_cndmask_b32_e64 v93, 0, 32, s[24:25]
	v_cndmask_b32_e64 v94, 0, 32, s[26:27]
	v_cndmask_b32_e64 v95, 0, 32, s[28:29]
	v_ldexp_f32 v92, v96, v92
	v_ldexp_f32 v93, v97, v93
	v_ldexp_f32 v94, v98, v94
	v_ldexp_f32 v95, v99, v95
	v_log_f32_e32 v92, v92
	v_log_f32_e32 v93, v93
	v_log_f32_e32 v94, v94
	v_log_f32_e32 v95, v95
	v_mul_f32_e32 v100, 0x3f317217, v92
	v_mul_f32_e32 v101, 0x3f317217, v93
	v_mul_f32_e32 v102, 0x3f317217, v94
	v_mul_f32_e32 v103, 0x3f317217, v95
	v_fma_f32 v100, v92, s31, -v100
	v_fma_f32 v101, v93, s31, -v101
	v_fma_f32 v102, v94, s31, -v102
	v_fma_f32 v103, v95, s31, -v103
	v_fmac_f32_e32 v100, 0x3377d1cf, v92
	v_fmac_f32_e32 v101, 0x3377d1cf, v93
	v_fmac_f32_e32 v102, 0x3377d1cf, v94
	v_fmac_f32_e32 v103, 0x3377d1cf, v95
	v_fmac_f32_e32 v100, 0x3f317217, v92
	v_fmac_f32_e32 v101, 0x3f317217, v93
	v_fmac_f32_e32 v102, 0x3f317217, v94
	v_fmac_f32_e32 v103, 0x3f317217, v95
	v_cmp_lt_f32_e64 vcc, |v92|, s34
	v_cndmask_b32_e32 v92, v92, v100, vcc
	v_cmp_lt_f32_e64 vcc, |v93|, s34
	v_cndmask_b32_e32 v93, v93, v101, vcc
	v_cmp_lt_f32_e64 vcc, |v94|, s34
	v_cndmask_b32_e32 v94, v94, v102, vcc
	v_cmp_lt_f32_e64 vcc, |v95|, s34
	v_cndmask_b32_e32 v95, v95, v103, vcc
	v_cndmask_b32_e64 v100, 0, v213, s[22:23]
	v_cndmask_b32_e64 v101, 0, v213, s[24:25]
	v_cndmask_b32_e64 v102, 0, v213, s[26:27]
	v_cndmask_b32_e64 v103, 0, v213, s[28:29]
	v_sub_f32_e32 v92, v92, v100
	v_sub_f32_e32 v93, v93, v101
	v_sub_f32_e32 v94, v94, v102
	v_sub_f32_e32 v95, v95, v103
	v_add_f32_e32 v64, v64, v92
	v_add_f32_e32 v65, v65, v93
	v_add_f32_e32 v66, v66, v94
	v_add_f32_e32 v67, v67, v95
	v_mul_f32_e32 v92, 0xbfb8aa3b, v64
	v_mul_f32_e32 v93, 0xbfb8aa3b, v65
	v_mul_f32_e32 v94, 0xbfb8aa3b, v66
	v_mul_f32_e32 v95, 0xbfb8aa3b, v67
	v_mul_f32_e32 v100, 0x3fb8aa3b, v64
	v_mul_f32_e32 v101, 0x3fb8aa3b, v65
	v_mul_f32_e32 v102, 0x3fb8aa3b, v66
	v_mul_f32_e32 v103, 0x3fb8aa3b, v67
	v_exp_f32_e32 v92, v92
	v_exp_f32_e32 v93, v93
	v_exp_f32_e32 v94, v94
	v_exp_f32_e32 v95, v95
	v_exp_f32_e32 v100, v100
	v_exp_f32_e32 v101, v101
	v_exp_f32_e32 v102, v102
	v_exp_f32_e32 v103, v103
	v_sub_f32_e32 v96, 1.0, v96
	v_sub_f32_e32 v97, 1.0, v97
	v_sub_f32_e32 v98, 1.0, v98
	v_sub_f32_e32 v99, 1.0, v99
	v_mul_f32_e32 v96, v96, v92
	v_mul_f32_e32 v97, v97, v93
	v_mul_f32_e32 v98, v98, v94
	v_mul_f32_e32 v99, v99, v95
	v_lshlrev_b32_e32 v92, 16, v10
	v_and_b32_e32 v93, 0xffff0000, v10
	v_lshlrev_b32_e32 v94, 16, v11
	v_and_b32_e32 v95, 0xffff0000, v11
	v_mul_f32_e32 v92, v92, v100
	v_mul_f32_e32 v93, v93, v101
	v_mul_f32_e32 v94, v94, v102
	v_mul_f32_e32 v95, v95, v103
	v_cvt_pk_bf16_f32 v108, v92, v93
; DEV u16 f2bf(float f) { return (u16)(pack2(f, f) & 0xffffu); }
; DEV float bf2f(u16 h) { return __uint_as_float(((unsigned)h) << 16); }
; DEV float sigmoid_f(float x) { return __builtin_amdgcn_rcpf(1.f + __expf(-x)); }
; DEV void phase_p15(const Params& p, int g) {
;     ...
;       for (int cc = 0; cc < 2; ++cc) {
;         const int c = tid + 256 * cc;
;         unsigned kb[8];
; #pragma unroll
;         for (int e = 0; e < 8; ++e) {
;           const int jj = j8 * 8 + e;
;           const int j = dir ? 63 - jj : jj;
;           const size_t tok = (size_t)cidx * 64 + j;
;           const float f = lb[cc] + (1.f - lb[cc]) * sigmoid_f(bf2f(xr[st][cc][e]));
;           G[cc] += __logf(f);
;           const float eg = __expf(G[cc]), ig = __expf(-G[cc]);
;           Qp[tok * 512 + c] = f2bf(bf2f(qr[st][cc][e]) * eg);
;           const u16 kk = f2bf((1.f - f) * ig);
;           Kp[tok * 512 + c] = kk;
;           kb[e] = kk;
;         }
;         const int s0 = dir ? 56 - 8 * j8 : 8 * j8;
;         uint4 w;
;         w.x = dir ? (kb[7] | (kb[6] << 16)) : (kb[0] | (kb[1] << 16));
;         w.y = dir ? (kb[5] | (kb[4] << 16)) : (kb[2] | (kb[3] << 16));
;         w.z = dir ? (kb[3] | (kb[2] << 16)) : (kb[4] | (kb[5] << 16));
;         w.w = dir ? (kb[1] | (kb[0] << 16)) : (kb[6] | (kb[7] << 16));
;         *(uint4*)(KT + (((size_t)cidx * 2 + dir) * 512 + c) * 64 + s0) = w;
	v_cvt_pk_bf16_f32 v109, v94, v95
	v_cvt_pk_bf16_f32 v110, v96, v97
	v_cvt_pk_bf16_f32 v111, v98, v99
	global_store_dwordx2 v112, v[108:109], s[2:3]
	global_store_dwordx2 v114, v[110:111], s[2:3]
	s_add_u32 s2, s2, 0x400
	s_addc_u32 s3, s3, 0
	v_mov_b32_e32 v104, v96
	v_mov_b32_e32 v105, v97
	v_mov_b32_e32 v106, v98
	v_mov_b32_e32 v107, v99
	v_lshlrev_b32_e32 v92, 16, v12
	v_and_b32_e32 v93, 0xffff0000, v12
	v_lshlrev_b32_e32 v94, 16, v13
	v_and_b32_e32 v95, 0xffff0000, v13
	v_mul_f32_e32 v92, 0xbfb8aa3b, v92
	v_mul_f32_e32 v93, 0xbfb8aa3b, v93
	v_mul_f32_e32 v94, 0xbfb8aa3b, v94
	v_mul_f32_e32 v95, 0xbfb8aa3b, v95
	v_exp_f32_e32 v92, v92
	v_exp_f32_e32 v93, v93
	v_exp_f32_e32 v94, v94
	v_exp_f32_e32 v95, v95
	v_add_f32_e32 v92, 1.0, v92
	v_add_f32_e32 v93, 1.0, v93
	v_add_f32_e32 v94, 1.0, v94
	v_add_f32_e32 v95, 1.0, v95
	v_rcp_f32_e32 v92, v92
	v_rcp_f32_e32 v93, v93
	v_rcp_f32_e32 v94, v94
	v_rcp_f32_e32 v95, v95
	v_fma_f32 v96, v72, v92, v68
	v_fma_f32 v97, v73, v93, v69
	v_fma_f32 v98, v74, v94, v70
	v_fma_f32 v99, v75, v95, v71
	v_cmp_gt_f32_e64 s[22:23], s30, v96
	v_cmp_gt_f32_e64 s[24:25], s30, v97
	v_cmp_gt_f32_e64 s[26:27], s30, v98
	v_cmp_gt_f32_e64 s[28:29], s30, v99
	v_cndmask_b32_e64 v92, 0, 32, s[22:23]
	v_cndmask_b32_e64 v93, 0, 32, s[24:25]
	v_cndmask_b32_e64 v94, 0, 32, s[26:27]
	v_cndmask_b32_e64 v95, 0, 32, s[28:29]
	v_ldexp_f32 v92, v96, v92
	v_ldexp_f32 v93, v97, v93
	v_ldexp_f32 v94, v98, v94
	v_ldexp_f32 v95, v99, v95
	v_log_f32_e32 v92, v92
	v_log_f32_e32 v93, v93
	v_log_f32_e32 v94, v94
	v_log_f32_e32 v95, v95
	v_mul_f32_e32 v100, 0x3f317217, v92
	v_mul_f32_e32 v101, 0x3f317217, v93
	v_mul_f32_e32 v102, 0x3f317217, v94
	v_mul_f32_e32 v103, 0x3f317217, v95
	v_fma_f32 v100, v92, s31, -v100
	v_fma_f32 v101, v93, s31, -v101
	v_fma_f32 v102, v94, s31, -v102
	v_fma_f32 v103, v95, s31, -v103
	v_fmac_f32_e32 v100, 0x3377d1cf, v92
	v_fmac_f32_e32 v101, 0x3377d1cf, v93
	v_fmac_f32_e32 v102, 0x3377d1cf, v94
	v_fmac_f32_e32 v103, 0x3377d1cf, v95
	v_fmac_f32_e32 v100, 0x3f317217, v92
	v_fmac_f32_e32 v101, 0x3f317217, v93
	v_fmac_f32_e32 v102, 0x3f317217, v94
	v_fmac_f32_e32 v103, 0x3f317217, v95
	v_cmp_lt_f32_e64 vcc, |v92|, s34
	v_cndmask_b32_e32 v92, v92, v100, vcc
	v_cmp_lt_f32_e64 vcc, |v93|, s34
	v_cndmask_b32_e32 v93, v93, v101, vcc
	v_cmp_lt_f32_e64 vcc, |v94|, s34
	v_cndmask_b32_e32 v94, v94, v102, vcc
	v_cmp_lt_f32_e64 vcc, |v95|, s34
	v_cndmask_b32_e32 v95, v95, v103, vcc
	v_cndmask_b32_e64 v100, 0, v213, s[22:23]
	v_cndmask_b32_e64 v101, 0, v213, s[24:25]
	v_cndmask_b32_e64 v102, 0, v213, s[26:27]
	v_cndmask_b32_e64 v103, 0, v213, s[28:29]
	v_sub_f32_e32 v92, v92, v100
	v_sub_f32_e32 v93, v93, v101
	v_sub_f32_e32 v94, v94, v102
	v_sub_f32_e32 v95, v95, v103
	v_add_f32_e32 v64, v64, v92
	v_add_f32_e32 v65, v65, v93
	v_add_f32_e32 v66, v66, v94
	v_add_f32_e32 v67, v67, v95
	v_mul_f32_e32 v92, 0xbfb8aa3b, v64
	v_mul_f32_e32 v93, 0xbfb8aa3b, v65
	v_mul_f32_e32 v94, 0xbfb8aa3b, v66
	v_mul_f32_e32 v95, 0xbfb8aa3b, v67
	v_mul_f32_e32 v100, 0x3fb8aa3b, v64
	v_mul_f32_e32 v101, 0x3fb8aa3b, v65
	v_mul_f32_e32 v102, 0x3fb8aa3b, v66
	v_mul_f32_e32 v103, 0x3fb8aa3b, v67
	v_exp_f32_e32 v92, v92
	v_exp_f32_e32 v93, v93
	v_exp_f32_e32 v94, v94
	v_exp_f32_e32 v95, v95
	v_exp_f32_e32 v100, v100
	v_exp_f32_e32 v101, v101
	v_exp_f32_e32 v102, v102
	v_exp_f32_e32 v103, v103
	v_sub_f32_e32 v96, 1.0, v96
	v_sub_f32_e32 v97, 1.0, v97
	v_sub_f32_e32 v98, 1.0, v98
	v_sub_f32_e32 v99, 1.0, v99
	v_mul_f32_e32 v96, v96, v92
	v_mul_f32_e32 v97, v97, v93
	v_mul_f32_e32 v98, v98, v94
	v_mul_f32_e32 v99, v99, v95
	v_lshlrev_b32_e32 v92, 16, v14
	v_and_b32_e32 v93, 0xffff0000, v14
	v_lshlrev_b32_e32 v94, 16, v15
	v_and_b32_e32 v95, 0xffff0000, v15
	v_mul_f32_e32 v92, v92, v100
	v_mul_f32_e32 v93, v93, v101
	v_mul_f32_e32 v94, v94, v102
	v_mul_f32_e32 v95, v95, v103
	v_cvt_pk_bf16_f32 v108, v92, v93
	v_cvt_pk_bf16_f32 v109, v94, v95
	v_cvt_pk_bf16_f32 v110, v96, v97
	v_cvt_pk_bf16_f32 v111, v98, v99
	global_store_dwordx2 v112, v[108:109], s[2:3]
	global_store_dwordx2 v114, v[110:111], s[2:3]
	s_add_u32 s2, s2, 0x400
	s_addc_u32 s3, s3, 0
	v_cvt_pk_bf16_f32 v117, v104, v96
	v_cvt_pk_bf16_f32 v125, v105, v97
	v_cvt_pk_bf16_f32 v133, v106, v98
	v_cvt_pk_bf16_f32 v141, v107, v99
	v_lshlrev_b32_e32 v92, 16, v16
	v_and_b32_e32 v93, 0xffff0000, v16
	v_lshlrev_b32_e32 v94, 16, v17
	v_and_b32_e32 v95, 0xffff0000, v17
	v_mul_f32_e32 v92, 0xbfb8aa3b, v92
	v_mul_f32_e32 v93, 0xbfb8aa3b, v93
	v_mul_f32_e32 v94, 0xbfb8aa3b, v94
	v_mul_f32_e32 v95, 0xbfb8aa3b, v95
	v_exp_f32_e32 v92, v92
	v_exp_f32_e32 v93, v93
	v_exp_f32_e32 v94, v94
	v_exp_f32_e32 v95, v95
	v_add_f32_e32 v92, 1.0, v92
	v_add_f32_e32 v93, 1.0, v93
	v_add_f32_e32 v94, 1.0, v94
	v_add_f32_e32 v95, 1.0, v95
	v_rcp_f32_e32 v92, v92
	v_rcp_f32_e32 v93, v93
	v_rcp_f32_e32 v94, v94
	v_rcp_f32_e32 v95, v95
	v_fma_f32 v96, v72, v92, v68
	v_fma_f32 v97, v73, v93, v69
	v_fma_f32 v98, v74, v94, v70
	v_fma_f32 v99, v75, v95, v71
	v_cmp_gt_f32_e64 s[22:23], s30, v96
	v_cmp_gt_f32_e64 s[24:25], s30, v97
	v_cmp_gt_f32_e64 s[26:27], s30, v98
	v_cmp_gt_f32_e64 s[28:29], s30, v99
	v_cndmask_b32_e64 v92, 0, 32, s[22:23]
	v_cndmask_b32_e64 v93, 0, 32, s[24:25]
	v_cndmask_b32_e64 v94, 0, 32, s[26:27]
	v_cndmask_b32_e64 v95, 0, 32, s[28:29]
	v_ldexp_f32 v92, v96, v92
	v_ldexp_f32 v93, v97, v93
	v_ldexp_f32 v94, v98, v94
	v_ldexp_f32 v95, v99, v95
	v_log_f32_e32 v92, v92
	v_log_f32_e32 v93, v93
	v_log_f32_e32 v94, v94
	v_log_f32_e32 v95, v95
	v_mul_f32_e32 v100, 0x3f317217, v92
	v_mul_f32_e32 v101, 0x3f317217, v93
	v_mul_f32_e32 v102, 0x3f317217, v94
	v_mul_f32_e32 v103, 0x3f317217, v95
	v_fma_f32 v100, v92, s31, -v100
; DEV u16 f2bf(float f) { return (u16)(pack2(f, f) & 0xffffu); }
; DEV float bf2f(u16 h) { return __uint_as_float(((unsigned)h) << 16); }
; DEV float sigmoid_f(float x) { return __builtin_amdgcn_rcpf(1.f + __expf(-x)); }
; DEV void phase_p15(const Params& p, int g) {
;     ...
;       for (int cc = 0; cc < 2; ++cc) {
;         const int c = tid + 256 * cc;
;         unsigned kb[8];
; #pragma unroll
;         for (int e = 0; e < 8; ++e) {
;           const int jj = j8 * 8 + e;
;           const int j = dir ? 63 - jj : jj;
;           const size_t tok = (size_t)cidx * 64 + j;
;           const float f = lb[cc] + (1.f - lb[cc]) * sigmoid_f(bf2f(xr[st][cc][e]));
;           G[cc] += __logf(f);
;           const float eg = __expf(G[cc]), ig = __expf(-G[cc]);
;           Qp[tok * 512 + c] = f2bf(bf2f(qr[st][cc][e]) * eg);
;           const u16 kk = f2bf((1.f - f) * ig);
;           Kp[tok * 512 + c] = kk;
;           kb[e] = kk;
;         }
;         const int s0 = dir ? 56 - 8 * j8 : 8 * j8;
;         uint4 w;
;         w.x = dir ? (kb[7] | (kb[6] << 16)) : (kb[0] | (kb[1] << 16));
;         w.y = dir ? (kb[5] | (kb[4] << 16)) : (kb[2] | (kb[3] << 16));
;         w.z = dir ? (kb[3] | (kb[2] << 16)) : (kb[4] | (kb[5] << 16));
;         w.w = dir ? (kb[1] | (kb[0] << 16)) : (kb[6] | (kb[7] << 16));
;         *(uint4*)(KT + (((size_t)cidx * 2 + dir) * 512 + c) * 64 + s0) = w;
	v_fma_f32 v101, v93, s31, -v101
	v_fma_f32 v102, v94, s31, -v102
	v_fma_f32 v103, v95, s31, -v103
	v_fmac_f32_e32 v100, 0x3377d1cf, v92
	v_fmac_f32_e32 v101, 0x3377d1cf, v93
	v_fmac_f32_e32 v102, 0x3377d1cf, v94
	v_fmac_f32_e32 v103, 0x3377d1cf, v95
	v_fmac_f32_e32 v100, 0x3f317217, v92
	v_fmac_f32_e32 v101, 0x3f317217, v93
	v_fmac_f32_e32 v102, 0x3f317217, v94
	v_fmac_f32_e32 v103, 0x3f317217, v95
	v_cmp_lt_f32_e64 vcc, |v92|, s34
	v_cndmask_b32_e32 v92, v92, v100, vcc
	v_cmp_lt_f32_e64 vcc, |v93|, s34
	v_cndmask_b32_e32 v93, v93, v101, vcc
	v_cmp_lt_f32_e64 vcc, |v94|, s34
	v_cndmask_b32_e32 v94, v94, v102, vcc
	v_cmp_lt_f32_e64 vcc, |v95|, s34
	v_cndmask_b32_e32 v95, v95, v103, vcc
	v_cndmask_b32_e64 v100, 0, v213, s[22:23]
	v_cndmask_b32_e64 v101, 0, v213, s[24:25]
	v_cndmask_b32_e64 v102, 0, v213, s[26:27]
	v_cndmask_b32_e64 v103, 0, v213, s[28:29]
	v_sub_f32_e32 v92, v92, v100
	v_sub_f32_e32 v93, v93, v101
	v_sub_f32_e32 v94, v94, v102
	v_sub_f32_e32 v95, v95, v103
	v_add_f32_e32 v64, v64, v92
	v_add_f32_e32 v65, v65, v93
	v_add_f32_e32 v66, v66, v94
	v_add_f32_e32 v67, v67, v95
	v_mul_f32_e32 v92, 0xbfb8aa3b, v64
	v_mul_f32_e32 v93, 0xbfb8aa3b, v65
	v_mul_f32_e32 v94, 0xbfb8aa3b, v66
	v_mul_f32_e32 v95, 0xbfb8aa3b, v67
	v_mul_f32_e32 v100, 0x3fb8aa3b, v64
	v_mul_f32_e32 v101, 0x3fb8aa3b, v65
	v_mul_f32_e32 v102, 0x3fb8aa3b, v66
	v_mul_f32_e32 v103, 0x3fb8aa3b, v67
	v_exp_f32_e32 v92, v92
	v_exp_f32_e32 v93, v93
	v_exp_f32_e32 v94, v94
	v_exp_f32_e32 v95, v95
	v_exp_f32_e32 v100, v100
	v_exp_f32_e32 v101, v101
	v_exp_f32_e32 v102, v102
	v_exp_f32_e32 v103, v103
	v_sub_f32_e32 v96, 1.0, v96
	v_sub_f32_e32 v97, 1.0, v97
	v_sub_f32_e32 v98, 1.0, v98
	v_sub_f32_e32 v99, 1.0, v99
	v_mul_f32_e32 v96, v96, v92
	v_mul_f32_e32 v97, v97, v93
	v_mul_f32_e32 v98, v98, v94
	v_mul_f32_e32 v99, v99, v95
	v_lshlrev_b32_e32 v92, 16, v18
	v_and_b32_e32 v93, 0xffff0000, v18
	v_lshlrev_b32_e32 v94, 16, v19
	v_and_b32_e32 v95, 0xffff0000, v19
	v_mul_f32_e32 v92, v92, v100
	v_mul_f32_e32 v93, v93, v101
	v_mul_f32_e32 v94, v94, v102
	v_mul_f32_e32 v95, v95, v103
	v_cvt_pk_bf16_f32 v108, v92, v93
	v_cvt_pk_bf16_f32 v109, v94, v95
	v_cvt_pk_bf16_f32 v110, v96, v97
	v_cvt_pk_bf16_f32 v111, v98, v99
	global_store_dwordx2 v112, v[108:109], s[2:3]
	global_store_dwordx2 v114, v[110:111], s[2:3]
	s_add_u32 s2, s2, 0x400
	s_addc_u32 s3, s3, 0
	v_mov_b32_e32 v104, v96
	v_mov_b32_e32 v105, v97
	v_mov_b32_e32 v106, v98
	v_mov_b32_e32 v107, v99
	v_lshlrev_b32_e32 v92, 16, v20
	v_and_b32_e32 v93, 0xffff0000, v20
	v_lshlrev_b32_e32 v94, 16, v21
	v_and_b32_e32 v95, 0xffff0000, v21
	v_mul_f32_e32 v92, 0xbfb8aa3b, v92
	v_mul_f32_e32 v93, 0xbfb8aa3b, v93
	v_mul_f32_e32 v94, 0xbfb8aa3b, v94
	v_mul_f32_e32 v95, 0xbfb8aa3b, v95
	v_exp_f32_e32 v92, v92
	v_exp_f32_e32 v93, v93
	v_exp_f32_e32 v94, v94
	v_exp_f32_e32 v95, v95
	v_add_f32_e32 v92, 1.0, v92
	v_add_f32_e32 v93, 1.0, v93
	v_add_f32_e32 v94, 1.0, v94
	v_add_f32_e32 v95, 1.0, v95
	v_rcp_f32_e32 v92, v92
	v_rcp_f32_e32 v93, v93
	v_rcp_f32_e32 v94, v94
	v_rcp_f32_e32 v95, v95
	v_fma_f32 v96, v72, v92, v68
	v_fma_f32 v97, v73, v93, v69
	v_fma_f32 v98, v74, v94, v70
	v_fma_f32 v99, v75, v95, v71
	v_cmp_gt_f32_e64 s[22:23], s30, v96
	v_cmp_gt_f32_e64 s[24:25], s30, v97
	v_cmp_gt_f32_e64 s[26:27], s30, v98
	v_cmp_gt_f32_e64 s[28:29], s30, v99
	v_cndmask_b32_e64 v92, 0, 32, s[22:23]
	v_cndmask_b32_e64 v93, 0, 32, s[24:25]
	v_cndmask_b32_e64 v94, 0, 32, s[26:27]
	v_cndmask_b32_e64 v95, 0, 32, s[28:29]
	v_ldexp_f32 v92, v96, v92
	v_ldexp_f32 v93, v97, v93
	v_ldexp_f32 v94, v98, v94
	v_ldexp_f32 v95, v99, v95
	v_log_f32_e32 v92, v92
	v_log_f32_e32 v93, v93
	v_log_f32_e32 v94, v94
	v_log_f32_e32 v95, v95
	v_mul_f32_e32 v100, 0x3f317217, v92
	v_mul_f32_e32 v101, 0x3f317217, v93
	v_mul_f32_e32 v102, 0x3f317217, v94
	v_mul_f32_e32 v103, 0x3f317217, v95
	v_fma_f32 v100, v92, s31, -v100
	v_fma_f32 v101, v93, s31, -v101
	v_fma_f32 v102, v94, s31, -v102
	v_fma_f32 v103, v95, s31, -v103
	v_fmac_f32_e32 v100, 0x3377d1cf, v92
	v_fmac_f32_e32 v101, 0x3377d1cf, v93
	v_fmac_f32_e32 v102, 0x3377d1cf, v94
	v_fmac_f32_e32 v103, 0x3377d1cf, v95
	v_fmac_f32_e32 v100, 0x3f317217, v92
	v_fmac_f32_e32 v101, 0x3f317217, v93
	v_fmac_f32_e32 v102, 0x3f317217, v94
	v_fmac_f32_e32 v103, 0x3f317217, v95
	v_cmp_lt_f32_e64 vcc, |v92|, s34
	v_cndmask_b32_e32 v92, v92, v100, vcc
	v_cmp_lt_f32_e64 vcc, |v93|, s34
	v_cndmask_b32_e32 v93, v93, v101, vcc
	v_cmp_lt_f32_e64 vcc, |v94|, s34
	v_cndmask_b32_e32 v94, v94, v102, vcc
	v_cmp_lt_f32_e64 vcc, |v95|, s34
	v_cndmask_b32_e32 v95, v95, v103, vcc
	v_cndmask_b32_e64 v100, 0, v213, s[22:23]
	v_cndmask_b32_e64 v101, 0, v213, s[24:25]
	v_cndmask_b32_e64 v102, 0, v213, s[26:27]
	v_cndmask_b32_e64 v103, 0, v213, s[28:29]
	v_sub_f32_e32 v92, v92, v100
	v_sub_f32_e32 v93, v93, v101
	v_sub_f32_e32 v94, v94, v102
	v_sub_f32_e32 v95, v95, v103
	v_add_f32_e32 v64, v64, v92
	v_add_f32_e32 v65, v65, v93
	v_add_f32_e32 v66, v66, v94
	v_add_f32_e32 v67, v67, v95
	v_mul_f32_e32 v92, 0xbfb8aa3b, v64
	v_mul_f32_e32 v93, 0xbfb8aa3b, v65
	v_mul_f32_e32 v94, 0xbfb8aa3b, v66
	v_mul_f32_e32 v95, 0xbfb8aa3b, v67
	v_mul_f32_e32 v100, 0x3fb8aa3b, v64
	v_mul_f32_e32 v101, 0x3fb8aa3b, v65
	v_mul_f32_e32 v102, 0x3fb8aa3b, v66
	v_mul_f32_e32 v103, 0x3fb8aa3b, v67
	v_exp_f32_e32 v92, v92
	v_exp_f32_e32 v93, v93
	v_exp_f32_e32 v94, v94
	v_exp_f32_e32 v95, v95
	v_exp_f32_e32 v100, v100
	v_exp_f32_e32 v101, v101
	v_exp_f32_e32 v102, v102
	v_exp_f32_e32 v103, v103
	v_sub_f32_e32 v96, 1.0, v96
	v_sub_f32_e32 v97, 1.0, v97
	v_sub_f32_e32 v98, 1.0, v98
	v_sub_f32_e32 v99, 1.0, v99
	v_mul_f32_e32 v96, v96, v92
	v_mul_f32_e32 v97, v97, v93
; DEV u16 f2bf(float f) { return (u16)(pack2(f, f) & 0xffffu); }
; DEV float bf2f(u16 h) { return __uint_as_float(((unsigned)h) << 16); }
; DEV float sigmoid_f(float x) { return __builtin_amdgcn_rcpf(1.f + __expf(-x)); }
; DEV void phase_p15(const Params& p, int g) {
;     ...
;       for (int cc = 0; cc < 2; ++cc) {
;         const int c = tid + 256 * cc;
;         unsigned kb[8];
; #pragma unroll
;         for (int e = 0; e < 8; ++e) {
;           const int jj = j8 * 8 + e;
;           const int j = dir ? 63 - jj : jj;
;           const size_t tok = (size_t)cidx * 64 + j;
;           const float f = lb[cc] + (1.f - lb[cc]) * sigmoid_f(bf2f(xr[st][cc][e]));
;           G[cc] += __logf(f);
;           const float eg = __expf(G[cc]), ig = __expf(-G[cc]);
;           Qp[tok * 512 + c] = f2bf(bf2f(qr[st][cc][e]) * eg);
;           const u16 kk = f2bf((1.f - f) * ig);
;           Kp[tok * 512 + c] = kk;
;           kb[e] = kk;
;         }
;         const int s0 = dir ? 56 - 8 * j8 : 8 * j8;
;         uint4 w;
;         w.x = dir ? (kb[7] | (kb[6] << 16)) : (kb[0] | (kb[1] << 16));
;         w.y = dir ? (kb[5] | (kb[4] << 16)) : (kb[2] | (kb[3] << 16));
;         w.z = dir ? (kb[3] | (kb[2] << 16)) : (kb[4] | (kb[5] << 16));
;         w.w = dir ? (kb[1] | (kb[0] << 16)) : (kb[6] | (kb[7] << 16));
;         *(uint4*)(KT + (((size_t)cidx * 2 + dir) * 512 + c) * 64 + s0) = w;
	v_mul_f32_e32 v98, v98, v94
	v_mul_f32_e32 v99, v99, v95
	v_lshlrev_b32_e32 v92, 16, v22
	v_and_b32_e32 v93, 0xffff0000, v22
	v_lshlrev_b32_e32 v94, 16, v23
	v_and_b32_e32 v95, 0xffff0000, v23
	v_mul_f32_e32 v92, v92, v100
	v_mul_f32_e32 v93, v93, v101
	v_mul_f32_e32 v94, v94, v102
	v_mul_f32_e32 v95, v95, v103
	v_cvt_pk_bf16_f32 v108, v92, v93
	v_cvt_pk_bf16_f32 v109, v94, v95
	v_cvt_pk_bf16_f32 v110, v96, v97
	v_cvt_pk_bf16_f32 v111, v98, v99
	global_store_dwordx2 v112, v[108:109], s[2:3]
	global_store_dwordx2 v114, v[110:111], s[2:3]
	s_add_u32 s2, s2, 0x400
	s_addc_u32 s3, s3, 0
	v_cvt_pk_bf16_f32 v118, v104, v96
	v_cvt_pk_bf16_f32 v126, v105, v97
	v_cvt_pk_bf16_f32 v134, v106, v98
	v_cvt_pk_bf16_f32 v142, v107, v99
	v_lshlrev_b32_e32 v92, 16, v24
	v_and_b32_e32 v93, 0xffff0000, v24
	v_lshlrev_b32_e32 v94, 16, v25
	v_and_b32_e32 v95, 0xffff0000, v25
	v_mul_f32_e32 v92, 0xbfb8aa3b, v92
	v_mul_f32_e32 v93, 0xbfb8aa3b, v93
	v_mul_f32_e32 v94, 0xbfb8aa3b, v94
	v_mul_f32_e32 v95, 0xbfb8aa3b, v95
	v_exp_f32_e32 v92, v92
	v_exp_f32_e32 v93, v93
	v_exp_f32_e32 v94, v94
	v_exp_f32_e32 v95, v95
	v_add_f32_e32 v92, 1.0, v92
	v_add_f32_e32 v93, 1.0, v93
	v_add_f32_e32 v94, 1.0, v94
	v_add_f32_e32 v95, 1.0, v95
	v_rcp_f32_e32 v92, v92
	v_rcp_f32_e32 v93, v93
	v_rcp_f32_e32 v94, v94
	v_rcp_f32_e32 v95, v95
	v_fma_f32 v96, v72, v92, v68
	v_fma_f32 v97, v73, v93, v69
	v_fma_f32 v98, v74, v94, v70
	v_fma_f32 v99, v75, v95, v71
	v_cmp_gt_f32_e64 s[22:23], s30, v96
	v_cmp_gt_f32_e64 s[24:25], s30, v97
	v_cmp_gt_f32_e64 s[26:27], s30, v98
	v_cmp_gt_f32_e64 s[28:29], s30, v99
	v_cndmask_b32_e64 v92, 0, 32, s[22:23]
	v_cndmask_b32_e64 v93, 0, 32, s[24:25]
	v_cndmask_b32_e64 v94, 0, 32, s[26:27]
	v_cndmask_b32_e64 v95, 0, 32, s[28:29]
	v_ldexp_f32 v92, v96, v92
	v_ldexp_f32 v93, v97, v93
	v_ldexp_f32 v94, v98, v94
	v_ldexp_f32 v95, v99, v95
	v_log_f32_e32 v92, v92
	v_log_f32_e32 v93, v93
	v_log_f32_e32 v94, v94
	v_log_f32_e32 v95, v95
	v_mul_f32_e32 v100, 0x3f317217, v92
	v_mul_f32_e32 v101, 0x3f317217, v93
	v_mul_f32_e32 v102, 0x3f317217, v94
	v_mul_f32_e32 v103, 0x3f317217, v95
	v_fma_f32 v100, v92, s31, -v100
	v_fma_f32 v101, v93, s31, -v101
	v_fma_f32 v102, v94, s31, -v102
	v_fma_f32 v103, v95, s31, -v103
	v_fmac_f32_e32 v100, 0x3377d1cf, v92
	v_fmac_f32_e32 v101, 0x3377d1cf, v93
	v_fmac_f32_e32 v102, 0x3377d1cf, v94
	v_fmac_f32_e32 v103, 0x3377d1cf, v95
	v_fmac_f32_e32 v100, 0x3f317217, v92
	v_fmac_f32_e32 v101, 0x3f317217, v93
	v_fmac_f32_e32 v102, 0x3f317217, v94
	v_fmac_f32_e32 v103, 0x3f317217, v95
	v_cmp_lt_f32_e64 vcc, |v92|, s34
	v_cndmask_b32_e32 v92, v92, v100, vcc
	v_cmp_lt_f32_e64 vcc, |v93|, s34
	v_cndmask_b32_e32 v93, v93, v101, vcc
	v_cmp_lt_f32_e64 vcc, |v94|, s34
	v_cndmask_b32_e32 v94, v94, v102, vcc
	v_cmp_lt_f32_e64 vcc, |v95|, s34
	v_cndmask_b32_e32 v95, v95, v103, vcc
	v_cndmask_b32_e64 v100, 0, v213, s[22:23]
	v_cndmask_b32_e64 v101, 0, v213, s[24:25]
	v_cndmask_b32_e64 v102, 0, v213, s[26:27]
	v_cndmask_b32_e64 v103, 0, v213, s[28:29]
	v_sub_f32_e32 v92, v92, v100
	v_sub_f32_e32 v93, v93, v101
	v_sub_f32_e32 v94, v94, v102
	v_sub_f32_e32 v95, v95, v103
	v_add_f32_e32 v64, v64, v92
	v_add_f32_e32 v65, v65, v93
	v_add_f32_e32 v66, v66, v94
	v_add_f32_e32 v67, v67, v95
	v_mul_f32_e32 v92, 0xbfb8aa3b, v64
	v_mul_f32_e32 v93, 0xbfb8aa3b, v65
	v_mul_f32_e32 v94, 0xbfb8aa3b, v66
	v_mul_f32_e32 v95, 0xbfb8aa3b, v67
	v_mul_f32_e32 v100, 0x3fb8aa3b, v64
	v_mul_f32_e32 v101, 0x3fb8aa3b, v65
	v_mul_f32_e32 v102, 0x3fb8aa3b, v66
	v_mul_f32_e32 v103, 0x3fb8aa3b, v67
	v_exp_f32_e32 v92, v92
	v_exp_f32_e32 v93, v93
	v_exp_f32_e32 v94, v94
	v_exp_f32_e32 v95, v95
	v_exp_f32_e32 v100, v100
	v_exp_f32_e32 v101, v101
	v_exp_f32_e32 v102, v102
	v_exp_f32_e32 v103, v103
	v_sub_f32_e32 v96, 1.0, v96
	v_sub_f32_e32 v97, 1.0, v97
	v_sub_f32_e32 v98, 1.0, v98
	v_sub_f32_e32 v99, 1.0, v99
	v_mul_f32_e32 v96, v96, v92
	v_mul_f32_e32 v97, v97, v93
	v_mul_f32_e32 v98, v98, v94
	v_mul_f32_e32 v99, v99, v95
	v_lshlrev_b32_e32 v92, 16, v26
	v_and_b32_e32 v93, 0xffff0000, v26
	v_lshlrev_b32_e32 v94, 16, v27
	v_and_b32_e32 v95, 0xffff0000, v27
	v_mul_f32_e32 v92, v92, v100
	v_mul_f32_e32 v93, v93, v101
	v_mul_f32_e32 v94, v94, v102
	v_mul_f32_e32 v95, v95, v103
	v_cvt_pk_bf16_f32 v108, v92, v93
	v_cvt_pk_bf16_f32 v109, v94, v95
	v_cvt_pk_bf16_f32 v110, v96, v97
	v_cvt_pk_bf16_f32 v111, v98, v99
	global_store_dwordx2 v112, v[108:109], s[2:3]
	global_store_dwordx2 v114, v[110:111], s[2:3]
	s_add_u32 s2, s2, 0x400
	s_addc_u32 s3, s3, 0
	v_mov_b32_e32 v104, v96
	v_mov_b32_e32 v105, v97
	v_mov_b32_e32 v106, v98
	v_mov_b32_e32 v107, v99
	v_lshlrev_b32_e32 v92, 16, v28
	v_and_b32_e32 v93, 0xffff0000, v28
	v_lshlrev_b32_e32 v94, 16, v29
	v_and_b32_e32 v95, 0xffff0000, v29
	v_mul_f32_e32 v92, 0xbfb8aa3b, v92
	v_mul_f32_e32 v93, 0xbfb8aa3b, v93
	v_mul_f32_e32 v94, 0xbfb8aa3b, v94
	v_mul_f32_e32 v95, 0xbfb8aa3b, v95
	v_exp_f32_e32 v92, v92
	v_exp_f32_e32 v93, v93
	v_exp_f32_e32 v94, v94
	v_exp_f32_e32 v95, v95
	v_add_f32_e32 v92, 1.0, v92
	v_add_f32_e32 v93, 1.0, v93
	v_add_f32_e32 v94, 1.0, v94
	v_add_f32_e32 v95, 1.0, v95
	v_rcp_f32_e32 v92, v92
	v_rcp_f32_e32 v93, v93
	v_rcp_f32_e32 v94, v94
	v_rcp_f32_e32 v95, v95
	v_fma_f32 v96, v72, v92, v68
	v_fma_f32 v97, v73, v93, v69
	v_fma_f32 v98, v74, v94, v70
	v_fma_f32 v99, v75, v95, v71
	v_cmp_gt_f32_e64 s[22:23], s30, v96
	v_cmp_gt_f32_e64 s[24:25], s30, v97
	v_cmp_gt_f32_e64 s[26:27], s30, v98
	v_cmp_gt_f32_e64 s[28:29], s30, v99
	v_cndmask_b32_e64 v92, 0, 32, s[22:23]
	v_cndmask_b32_e64 v93, 0, 32, s[24:25]
	v_cndmask_b32_e64 v94, 0, 32, s[26:27]
	v_cndmask_b32_e64 v95, 0, 32, s[28:29]
	v_ldexp_f32 v92, v96, v92
; DEV u16 f2bf(float f) { return (u16)(pack2(f, f) & 0xffffu); }
; DEV float bf2f(u16 h) { return __uint_as_float(((unsigned)h) << 16); }
; DEV float sigmoid_f(float x) { return __builtin_amdgcn_rcpf(1.f + __expf(-x)); }
; DEV void phase_p15(const Params& p, int g) {
;     ...
;       for (int cc = 0; cc < 2; ++cc) {
;         const int c = tid + 256 * cc;
;         unsigned kb[8];
; #pragma unroll
;         for (int e = 0; e < 8; ++e) {
;           const int jj = j8 * 8 + e;
;           const int j = dir ? 63 - jj : jj;
;           const size_t tok = (size_t)cidx * 64 + j;
;           const float f = lb[cc] + (1.f - lb[cc]) * sigmoid_f(bf2f(xr[st][cc][e]));
;           G[cc] += __logf(f);
;           const float eg = __expf(G[cc]), ig = __expf(-G[cc]);
;           Qp[tok * 512 + c] = f2bf(bf2f(qr[st][cc][e]) * eg);
;           const u16 kk = f2bf((1.f - f) * ig);
;           Kp[tok * 512 + c] = kk;
;           kb[e] = kk;
;         }
;         const int s0 = dir ? 56 - 8 * j8 : 8 * j8;
;         uint4 w;
;         w.x = dir ? (kb[7] | (kb[6] << 16)) : (kb[0] | (kb[1] << 16));
;         w.y = dir ? (kb[5] | (kb[4] << 16)) : (kb[2] | (kb[3] << 16));
;         w.z = dir ? (kb[3] | (kb[2] << 16)) : (kb[4] | (kb[5] << 16));
;         w.w = dir ? (kb[1] | (kb[0] << 16)) : (kb[6] | (kb[7] << 16));
;         *(uint4*)(KT + (((size_t)cidx * 2 + dir) * 512 + c) * 64 + s0) = w;
	v_ldexp_f32 v93, v97, v93
	v_ldexp_f32 v94, v98, v94
	v_ldexp_f32 v95, v99, v95
	v_log_f32_e32 v92, v92
	v_log_f32_e32 v93, v93
	v_log_f32_e32 v94, v94
	v_log_f32_e32 v95, v95
	v_mul_f32_e32 v100, 0x3f317217, v92
	v_mul_f32_e32 v101, 0x3f317217, v93
	v_mul_f32_e32 v102, 0x3f317217, v94
	v_mul_f32_e32 v103, 0x3f317217, v95
	v_fma_f32 v100, v92, s31, -v100
	v_fma_f32 v101, v93, s31, -v101
	v_fma_f32 v102, v94, s31, -v102
	v_fma_f32 v103, v95, s31, -v103
	v_fmac_f32_e32 v100, 0x3377d1cf, v92
	v_fmac_f32_e32 v101, 0x3377d1cf, v93
	v_fmac_f32_e32 v102, 0x3377d1cf, v94
	v_fmac_f32_e32 v103, 0x3377d1cf, v95
	v_fmac_f32_e32 v100, 0x3f317217, v92
	v_fmac_f32_e32 v101, 0x3f317217, v93
	v_fmac_f32_e32 v102, 0x3f317217, v94
	v_fmac_f32_e32 v103, 0x3f317217, v95
	v_cmp_lt_f32_e64 vcc, |v92|, s34
	v_cndmask_b32_e32 v92, v92, v100, vcc
	v_cmp_lt_f32_e64 vcc, |v93|, s34
	v_cndmask_b32_e32 v93, v93, v101, vcc
	v_cmp_lt_f32_e64 vcc, |v94|, s34
	v_cndmask_b32_e32 v94, v94, v102, vcc
	v_cmp_lt_f32_e64 vcc, |v95|, s34
	v_cndmask_b32_e32 v95, v95, v103, vcc
	v_cndmask_b32_e64 v100, 0, v213, s[22:23]
	v_cndmask_b32_e64 v101, 0, v213, s[24:25]
	v_cndmask_b32_e64 v102, 0, v213, s[26:27]
	v_cndmask_b32_e64 v103, 0, v213, s[28:29]
	v_sub_f32_e32 v92, v92, v100
	v_sub_f32_e32 v93, v93, v101
	v_sub_f32_e32 v94, v94, v102
	v_sub_f32_e32 v95, v95, v103
	v_add_f32_e32 v64, v64, v92
	v_add_f32_e32 v65, v65, v93
	v_add_f32_e32 v66, v66, v94
	v_add_f32_e32 v67, v67, v95
	v_mul_f32_e32 v92, 0xbfb8aa3b, v64
	v_mul_f32_e32 v93, 0xbfb8aa3b, v65
	v_mul_f32_e32 v94, 0xbfb8aa3b, v66
	v_mul_f32_e32 v95, 0xbfb8aa3b, v67
	v_mul_f32_e32 v100, 0x3fb8aa3b, v64
	v_mul_f32_e32 v101, 0x3fb8aa3b, v65
	v_mul_f32_e32 v102, 0x3fb8aa3b, v66
	v_mul_f32_e32 v103, 0x3fb8aa3b, v67
	v_exp_f32_e32 v92, v92
	v_exp_f32_e32 v93, v93
	v_exp_f32_e32 v94, v94
	v_exp_f32_e32 v95, v95
	v_exp_f32_e32 v100, v100
	v_exp_f32_e32 v101, v101
	v_exp_f32_e32 v102, v102
	v_exp_f32_e32 v103, v103
	v_sub_f32_e32 v96, 1.0, v96
	v_sub_f32_e32 v97, 1.0, v97
	v_sub_f32_e32 v98, 1.0, v98
	v_sub_f32_e32 v99, 1.0, v99
	v_mul_f32_e32 v96, v96, v92
	v_mul_f32_e32 v97, v97, v93
	v_mul_f32_e32 v98, v98, v94
	v_mul_f32_e32 v99, v99, v95
	v_lshlrev_b32_e32 v92, 16, v30
	v_and_b32_e32 v93, 0xffff0000, v30
	v_lshlrev_b32_e32 v94, 16, v31
	v_and_b32_e32 v95, 0xffff0000, v31
	v_mul_f32_e32 v92, v92, v100
	v_mul_f32_e32 v93, v93, v101
	v_mul_f32_e32 v94, v94, v102
	v_mul_f32_e32 v95, v95, v103
	v_cvt_pk_bf16_f32 v108, v92, v93
	v_cvt_pk_bf16_f32 v109, v94, v95
	v_cvt_pk_bf16_f32 v110, v96, v97
	v_cvt_pk_bf16_f32 v111, v98, v99
	global_store_dwordx2 v112, v[108:109], s[2:3]
	global_store_dwordx2 v114, v[110:111], s[2:3]
	s_add_u32 s2, s2, 0x400
	s_addc_u32 s3, s3, 0
	v_cvt_pk_bf16_f32 v119, v104, v96
	v_cvt_pk_bf16_f32 v127, v105, v97
	v_cvt_pk_bf16_f32 v135, v106, v98
	v_cvt_pk_bf16_f32 v143, v107, v99
	global_load_dwordx2 v[0:1], v113, s[0:1]
	global_load_dwordx2 v[2:3], v112, s[0:1]
	s_add_u32 s0, s0, 0x1400
	s_addc_u32 s1, s1, 0
	global_load_dwordx2 v[4:5], v113, s[0:1]
	global_load_dwordx2 v[6:7], v112, s[0:1]
	s_add_u32 s0, s0, 0x1400
	s_addc_u32 s1, s1, 0
	global_load_dwordx2 v[8:9], v113, s[0:1]
	global_load_dwordx2 v[10:11], v112, s[0:1]
	s_add_u32 s0, s0, 0x1400
	s_addc_u32 s1, s1, 0
	global_load_dwordx2 v[12:13], v113, s[0:1]
	global_load_dwordx2 v[14:15], v112, s[0:1]
	s_add_u32 s0, s0, 0x1400
	s_addc_u32 s1, s1, 0
	global_load_dwordx2 v[16:17], v113, s[0:1]
	global_load_dwordx2 v[18:19], v112, s[0:1]
	s_add_u32 s0, s0, 0x1400
	s_addc_u32 s1, s1, 0
	global_load_dwordx2 v[20:21], v113, s[0:1]
	global_load_dwordx2 v[22:23], v112, s[0:1]
	s_add_u32 s0, s0, 0x1400
	s_addc_u32 s1, s1, 0
	global_load_dwordx2 v[24:25], v113, s[0:1]
	global_load_dwordx2 v[26:27], v112, s[0:1]
	s_add_u32 s0, s0, 0x1400
	s_addc_u32 s1, s1, 0
	global_load_dwordx2 v[28:29], v113, s[0:1]
	global_load_dwordx2 v[30:31], v112, s[0:1]
	s_add_u32 s0, s0, 0x1400
	s_addc_u32 s1, s1, 0
	s_waitcnt vmcnt(32)
	v_lshlrev_b32_e32 v92, 16, v32
	v_and_b32_e32 v93, 0xffff0000, v32
	v_lshlrev_b32_e32 v94, 16, v33
	v_and_b32_e32 v95, 0xffff0000, v33
	v_mul_f32_e32 v92, 0xbfb8aa3b, v92
	v_mul_f32_e32 v93, 0xbfb8aa3b, v93
	v_mul_f32_e32 v94, 0xbfb8aa3b, v94
	v_mul_f32_e32 v95, 0xbfb8aa3b, v95
	v_exp_f32_e32 v92, v92
	v_exp_f32_e32 v93, v93
	v_exp_f32_e32 v94, v94
	v_exp_f32_e32 v95, v95
	v_add_f32_e32 v92, 1.0, v92
	v_add_f32_e32 v93, 1.0, v93
	v_add_f32_e32 v94, 1.0, v94
	v_add_f32_e32 v95, 1.0, v95
	v_rcp_f32_e32 v92, v92
	v_rcp_f32_e32 v93, v93
	v_rcp_f32_e32 v94, v94
	v_rcp_f32_e32 v95, v95
	v_fma_f32 v96, v72, v92, v68
	v_fma_f32 v97, v73, v93, v69
	v_fma_f32 v98, v74, v94, v70
	v_fma_f32 v99, v75, v95, v71
	v_cmp_gt_f32_e64 s[22:23], s30, v96
	v_cmp_gt_f32_e64 s[24:25], s30, v97
	v_cmp_gt_f32_e64 s[26:27], s30, v98
	v_cmp_gt_f32_e64 s[28:29], s30, v99
	v_cndmask_b32_e64 v92, 0, 32, s[22:23]
	v_cndmask_b32_e64 v93, 0, 32, s[24:25]
	v_cndmask_b32_e64 v94, 0, 32, s[26:27]
	v_cndmask_b32_e64 v95, 0, 32, s[28:29]
	v_ldexp_f32 v92, v96, v92
	v_ldexp_f32 v93, v97, v93
	v_ldexp_f32 v94, v98, v94
	v_ldexp_f32 v95, v99, v95
	v_log_f32_e32 v92, v92
	v_log_f32_e32 v93, v93
	v_log_f32_e32 v94, v94
	v_log_f32_e32 v95, v95
	v_mul_f32_e32 v100, 0x3f317217, v92
	v_mul_f32_e32 v101, 0x3f317217, v93
	v_mul_f32_e32 v102, 0x3f317217, v94
	v_mul_f32_e32 v103, 0x3f317217, v95
	v_fma_f32 v100, v92, s31, -v100
	v_fma_f32 v101, v93, s31, -v101
	v_fma_f32 v102, v94, s31, -v102
	v_fma_f32 v103, v95, s31, -v103
	v_fmac_f32_e32 v100, 0x3377d1cf, v92
	v_fmac_f32_e32 v101, 0x3377d1cf, v93
	v_fmac_f32_e32 v102, 0x3377d1cf, v94
	v_fmac_f32_e32 v103, 0x3377d1cf, v95
	v_fmac_f32_e32 v100, 0x3f317217, v92
; DEV u16 f2bf(float f) { return (u16)(pack2(f, f) & 0xffffu); }
; DEV float bf2f(u16 h) { return __uint_as_float(((unsigned)h) << 16); }
; DEV float sigmoid_f(float x) { return __builtin_amdgcn_rcpf(1.f + __expf(-x)); }
; DEV void phase_p15(const Params& p, int g) {
;     ...
;       for (int cc = 0; cc < 2; ++cc) {
;         const int c = tid + 256 * cc;
;         unsigned kb[8];
; #pragma unroll
;         for (int e = 0; e < 8; ++e) {
;           const int jj = j8 * 8 + e;
;           const int j = dir ? 63 - jj : jj;
;           const size_t tok = (size_t)cidx * 64 + j;
;           const float f = lb[cc] + (1.f - lb[cc]) * sigmoid_f(bf2f(xr[st][cc][e]));
;           G[cc] += __logf(f);
;           const float eg = __expf(G[cc]), ig = __expf(-G[cc]);
;           Qp[tok * 512 + c] = f2bf(bf2f(qr[st][cc][e]) * eg);
;           const u16 kk = f2bf((1.f - f) * ig);
;           Kp[tok * 512 + c] = kk;
;           kb[e] = kk;
;         }
;         const int s0 = dir ? 56 - 8 * j8 : 8 * j8;
;         uint4 w;
;         w.x = dir ? (kb[7] | (kb[6] << 16)) : (kb[0] | (kb[1] << 16));
;         w.y = dir ? (kb[5] | (kb[4] << 16)) : (kb[2] | (kb[3] << 16));
;         w.z = dir ? (kb[3] | (kb[2] << 16)) : (kb[4] | (kb[5] << 16));
;         w.w = dir ? (kb[1] | (kb[0] << 16)) : (kb[6] | (kb[7] << 16));
;         *(uint4*)(KT + (((size_t)cidx * 2 + dir) * 512 + c) * 64 + s0) = w;
	v_fmac_f32_e32 v101, 0x3f317217, v93
	v_fmac_f32_e32 v102, 0x3f317217, v94
	v_fmac_f32_e32 v103, 0x3f317217, v95
	v_cmp_lt_f32_e64 vcc, |v92|, s34
	v_cndmask_b32_e32 v92, v92, v100, vcc
	v_cmp_lt_f32_e64 vcc, |v93|, s34
	v_cndmask_b32_e32 v93, v93, v101, vcc
	v_cmp_lt_f32_e64 vcc, |v94|, s34
	v_cndmask_b32_e32 v94, v94, v102, vcc
	v_cmp_lt_f32_e64 vcc, |v95|, s34
	v_cndmask_b32_e32 v95, v95, v103, vcc
	v_cndmask_b32_e64 v100, 0, v213, s[22:23]
	v_cndmask_b32_e64 v101, 0, v213, s[24:25]
	v_cndmask_b32_e64 v102, 0, v213, s[26:27]
	v_cndmask_b32_e64 v103, 0, v213, s[28:29]
	v_sub_f32_e32 v92, v92, v100
	v_sub_f32_e32 v93, v93, v101
	v_sub_f32_e32 v94, v94, v102
	v_sub_f32_e32 v95, v95, v103
	v_add_f32_e32 v64, v64, v92
	v_add_f32_e32 v65, v65, v93
	v_add_f32_e32 v66, v66, v94
	v_add_f32_e32 v67, v67, v95
	v_mul_f32_e32 v92, 0xbfb8aa3b, v64
	v_mul_f32_e32 v93, 0xbfb8aa3b, v65
	v_mul_f32_e32 v94, 0xbfb8aa3b, v66
	v_mul_f32_e32 v95, 0xbfb8aa3b, v67
	v_mul_f32_e32 v100, 0x3fb8aa3b, v64
	v_mul_f32_e32 v101, 0x3fb8aa3b, v65
	v_mul_f32_e32 v102, 0x3fb8aa3b, v66
	v_mul_f32_e32 v103, 0x3fb8aa3b, v67
	v_exp_f32_e32 v92, v92
	v_exp_f32_e32 v93, v93
	v_exp_f32_e32 v94, v94
	v_exp_f32_e32 v95, v95
	v_exp_f32_e32 v100, v100
	v_exp_f32_e32 v101, v101
	v_exp_f32_e32 v102, v102
	v_exp_f32_e32 v103, v103
	v_sub_f32_e32 v96, 1.0, v96
	v_sub_f32_e32 v97, 1.0, v97
	v_sub_f32_e32 v98, 1.0, v98
	v_sub_f32_e32 v99, 1.0, v99
	v_mul_f32_e32 v96, v96, v92
	v_mul_f32_e32 v97, v97, v93
	v_mul_f32_e32 v98, v98, v94
	v_mul_f32_e32 v99, v99, v95
	v_lshlrev_b32_e32 v92, 16, v34
	v_and_b32_e32 v93, 0xffff0000, v34
	v_lshlrev_b32_e32 v94, 16, v35
	v_and_b32_e32 v95, 0xffff0000, v35
	v_mul_f32_e32 v92, v92, v100
	v_mul_f32_e32 v93, v93, v101
	v_mul_f32_e32 v94, v94, v102
	v_mul_f32_e32 v95, v95, v103
	v_cvt_pk_bf16_f32 v108, v92, v93
	v_cvt_pk_bf16_f32 v109, v94, v95
	v_cvt_pk_bf16_f32 v110, v96, v97
	v_cvt_pk_bf16_f32 v111, v98, v99
	global_store_dwordx2 v112, v[108:109], s[2:3]
	global_store_dwordx2 v114, v[110:111], s[2:3]
	s_add_u32 s2, s2, 0x400
	s_addc_u32 s3, s3, 0
	v_mov_b32_e32 v104, v96
	v_mov_b32_e32 v105, v97
	v_mov_b32_e32 v106, v98
	v_mov_b32_e32 v107, v99
	v_lshlrev_b32_e32 v92, 16, v36
	v_and_b32_e32 v93, 0xffff0000, v36
	v_lshlrev_b32_e32 v94, 16, v37
	v_and_b32_e32 v95, 0xffff0000, v37
	v_mul_f32_e32 v92, 0xbfb8aa3b, v92
	v_mul_f32_e32 v93, 0xbfb8aa3b, v93
	v_mul_f32_e32 v94, 0xbfb8aa3b, v94
	v_mul_f32_e32 v95, 0xbfb8aa3b, v95
	v_exp_f32_e32 v92, v92
	v_exp_f32_e32 v93, v93
	v_exp_f32_e32 v94, v94
	v_exp_f32_e32 v95, v95
	v_add_f32_e32 v92, 1.0, v92
	v_add_f32_e32 v93, 1.0, v93
	v_add_f32_e32 v94, 1.0, v94
	v_add_f32_e32 v95, 1.0, v95
	v_rcp_f32_e32 v92, v92
	v_rcp_f32_e32 v93, v93
	v_rcp_f32_e32 v94, v94
	v_rcp_f32_e32 v95, v95
	v_fma_f32 v96, v72, v92, v68
	v_fma_f32 v97, v73, v93, v69
	v_fma_f32 v98, v74, v94, v70
	v_fma_f32 v99, v75, v95, v71
	v_cmp_gt_f32_e64 s[22:23], s30, v96
	v_cmp_gt_f32_e64 s[24:25], s30, v97
	v_cmp_gt_f32_e64 s[26:27], s30, v98
	v_cmp_gt_f32_e64 s[28:29], s30, v99
	v_cndmask_b32_e64 v92, 0, 32, s[22:23]
	v_cndmask_b32_e64 v93, 0, 32, s[24:25]
	v_cndmask_b32_e64 v94, 0, 32, s[26:27]
	v_cndmask_b32_e64 v95, 0, 32, s[28:29]
	v_ldexp_f32 v92, v96, v92
	v_ldexp_f32 v93, v97, v93
	v_ldexp_f32 v94, v98, v94
	v_ldexp_f32 v95, v99, v95
	v_log_f32_e32 v92, v92
	v_log_f32_e32 v93, v93
	v_log_f32_e32 v94, v94
	v_log_f32_e32 v95, v95
	v_mul_f32_e32 v100, 0x3f317217, v92
	v_mul_f32_e32 v101, 0x3f317217, v93
	v_mul_f32_e32 v102, 0x3f317217, v94
	v_mul_f32_e32 v103, 0x3f317217, v95
	v_fma_f32 v100, v92, s31, -v100
	v_fma_f32 v101, v93, s31, -v101
	v_fma_f32 v102, v94, s31, -v102
	v_fma_f32 v103, v95, s31, -v103
	v_fmac_f32_e32 v100, 0x3377d1cf, v92
	v_fmac_f32_e32 v101, 0x3377d1cf, v93
	v_fmac_f32_e32 v102, 0x3377d1cf, v94
	v_fmac_f32_e32 v103, 0x3377d1cf, v95
	v_fmac_f32_e32 v100, 0x3f317217, v92
	v_fmac_f32_e32 v101, 0x3f317217, v93
	v_fmac_f32_e32 v102, 0x3f317217, v94
	v_fmac_f32_e32 v103, 0x3f317217, v95
	v_cmp_lt_f32_e64 vcc, |v92|, s34
	v_cndmask_b32_e32 v92, v92, v100, vcc
	v_cmp_lt_f32_e64 vcc, |v93|, s34
	v_cndmask_b32_e32 v93, v93, v101, vcc
	v_cmp_lt_f32_e64 vcc, |v94|, s34
	v_cndmask_b32_e32 v94, v94, v102, vcc
	v_cmp_lt_f32_e64 vcc, |v95|, s34
	v_cndmask_b32_e32 v95, v95, v103, vcc
	v_cndmask_b32_e64 v100, 0, v213, s[22:23]
	v_cndmask_b32_e64 v101, 0, v213, s[24:25]
	v_cndmask_b32_e64 v102, 0, v213, s[26:27]
	v_cndmask_b32_e64 v103, 0, v213, s[28:29]
	v_sub_f32_e32 v92, v92, v100
	v_sub_f32_e32 v93, v93, v101
	v_sub_f32_e32 v94, v94, v102
	v_sub_f32_e32 v95, v95, v103
	v_add_f32_e32 v64, v64, v92
	v_add_f32_e32 v65, v65, v93
	v_add_f32_e32 v66, v66, v94
	v_add_f32_e32 v67, v67, v95
	v_mul_f32_e32 v92, 0xbfb8aa3b, v64
	v_mul_f32_e32 v93, 0xbfb8aa3b, v65
	v_mul_f32_e32 v94, 0xbfb8aa3b, v66
	v_mul_f32_e32 v95, 0xbfb8aa3b, v67
	v_mul_f32_e32 v100, 0x3fb8aa3b, v64
	v_mul_f32_e32 v101, 0x3fb8aa3b, v65
	v_mul_f32_e32 v102, 0x3fb8aa3b, v66
	v_mul_f32_e32 v103, 0x3fb8aa3b, v67
	v_exp_f32_e32 v92, v92
	v_exp_f32_e32 v93, v93
	v_exp_f32_e32 v94, v94
	v_exp_f32_e32 v95, v95
	v_exp_f32_e32 v100, v100
	v_exp_f32_e32 v101, v101
	v_exp_f32_e32 v102, v102
	v_exp_f32_e32 v103, v103
	v_sub_f32_e32 v96, 1.0, v96
	v_sub_f32_e32 v97, 1.0, v97
	v_sub_f32_e32 v98, 1.0, v98
	v_sub_f32_e32 v99, 1.0, v99
	v_mul_f32_e32 v96, v96, v92
	v_mul_f32_e32 v97, v97, v93
	v_mul_f32_e32 v98, v98, v94
	v_mul_f32_e32 v99, v99, v95
	v_lshlrev_b32_e32 v92, 16, v38
	v_and_b32_e32 v93, 0xffff0000, v38
	v_lshlrev_b32_e32 v94, 16, v39
	v_and_b32_e32 v95, 0xffff0000, v39
	v_mul_f32_e32 v92, v92, v100
	v_mul_f32_e32 v93, v93, v101
	v_mul_f32_e32 v94, v94, v102
; DEV u16 f2bf(float f) { return (u16)(pack2(f, f) & 0xffffu); }
; DEV float bf2f(u16 h) { return __uint_as_float(((unsigned)h) << 16); }
; DEV float sigmoid_f(float x) { return __builtin_amdgcn_rcpf(1.f + __expf(-x)); }
; DEV void phase_p15(const Params& p, int g) {
;     ...
;       for (int cc = 0; cc < 2; ++cc) {
;         const int c = tid + 256 * cc;
;         unsigned kb[8];
; #pragma unroll
;         for (int e = 0; e < 8; ++e) {
;           const int jj = j8 * 8 + e;
;           const int j = dir ? 63 - jj : jj;
;           const size_t tok = (size_t)cidx * 64 + j;
;           const float f = lb[cc] + (1.f - lb[cc]) * sigmoid_f(bf2f(xr[st][cc][e]));
;           G[cc] += __logf(f);
;           const float eg = __expf(G[cc]), ig = __expf(-G[cc]);
;           Qp[tok * 512 + c] = f2bf(bf2f(qr[st][cc][e]) * eg);
;           const u16 kk = f2bf((1.f - f) * ig);
;           Kp[tok * 512 + c] = kk;
;           kb[e] = kk;
;         }
;         const int s0 = dir ? 56 - 8 * j8 : 8 * j8;
;         uint4 w;
;         w.x = dir ? (kb[7] | (kb[6] << 16)) : (kb[0] | (kb[1] << 16));
;         w.y = dir ? (kb[5] | (kb[4] << 16)) : (kb[2] | (kb[3] << 16));
;         w.z = dir ? (kb[3] | (kb[2] << 16)) : (kb[4] | (kb[5] << 16));
;         w.w = dir ? (kb[1] | (kb[0] << 16)) : (kb[6] | (kb[7] << 16));
;         *(uint4*)(KT + (((size_t)cidx * 2 + dir) * 512 + c) * 64 + s0) = w;
	v_mul_f32_e32 v95, v95, v103
	v_cvt_pk_bf16_f32 v108, v92, v93
	v_cvt_pk_bf16_f32 v109, v94, v95
	v_cvt_pk_bf16_f32 v110, v96, v97
	v_cvt_pk_bf16_f32 v111, v98, v99
	global_store_dwordx2 v112, v[108:109], s[2:3]
	global_store_dwordx2 v114, v[110:111], s[2:3]
	s_add_u32 s2, s2, 0x400
	s_addc_u32 s3, s3, 0
	v_cvt_pk_bf16_f32 v120, v104, v96
	v_cvt_pk_bf16_f32 v128, v105, v97
	v_cvt_pk_bf16_f32 v136, v106, v98
	v_cvt_pk_bf16_f32 v144, v107, v99
	v_lshlrev_b32_e32 v92, 16, v40
	v_and_b32_e32 v93, 0xffff0000, v40
	v_lshlrev_b32_e32 v94, 16, v41
	v_and_b32_e32 v95, 0xffff0000, v41
	v_mul_f32_e32 v92, 0xbfb8aa3b, v92
	v_mul_f32_e32 v93, 0xbfb8aa3b, v93
	v_mul_f32_e32 v94, 0xbfb8aa3b, v94
	v_mul_f32_e32 v95, 0xbfb8aa3b, v95
	v_exp_f32_e32 v92, v92
	v_exp_f32_e32 v93, v93
	v_exp_f32_e32 v94, v94
	v_exp_f32_e32 v95, v95
	v_add_f32_e32 v92, 1.0, v92
	v_add_f32_e32 v93, 1.0, v93
	v_add_f32_e32 v94, 1.0, v94
	v_add_f32_e32 v95, 1.0, v95
	v_rcp_f32_e32 v92, v92
	v_rcp_f32_e32 v93, v93
	v_rcp_f32_e32 v94, v94
	v_rcp_f32_e32 v95, v95
	v_fma_f32 v96, v72, v92, v68
	v_fma_f32 v97, v73, v93, v69
	v_fma_f32 v98, v74, v94, v70
	v_fma_f32 v99, v75, v95, v71
	v_cmp_gt_f32_e64 s[22:23], s30, v96
	v_cmp_gt_f32_e64 s[24:25], s30, v97
	v_cmp_gt_f32_e64 s[26:27], s30, v98
	v_cmp_gt_f32_e64 s[28:29], s30, v99
	v_cndmask_b32_e64 v92, 0, 32, s[22:23]
	v_cndmask_b32_e64 v93, 0, 32, s[24:25]
	v_cndmask_b32_e64 v94, 0, 32, s[26:27]
	v_cndmask_b32_e64 v95, 0, 32, s[28:29]
	v_ldexp_f32 v92, v96, v92
	v_ldexp_f32 v93, v97, v93
	v_ldexp_f32 v94, v98, v94
	v_ldexp_f32 v95, v99, v95
	v_log_f32_e32 v92, v92
	v_log_f32_e32 v93, v93
	v_log_f32_e32 v94, v94
	v_log_f32_e32 v95, v95
	v_mul_f32_e32 v100, 0x3f317217, v92
	v_mul_f32_e32 v101, 0x3f317217, v93
	v_mul_f32_e32 v102, 0x3f317217, v94
	v_mul_f32_e32 v103, 0x3f317217, v95
	v_fma_f32 v100, v92, s31, -v100
	v_fma_f32 v101, v93, s31, -v101
	v_fma_f32 v102, v94, s31, -v102
	v_fma_f32 v103, v95, s31, -v103
	v_fmac_f32_e32 v100, 0x3377d1cf, v92
	v_fmac_f32_e32 v101, 0x3377d1cf, v93
	v_fmac_f32_e32 v102, 0x3377d1cf, v94
	v_fmac_f32_e32 v103, 0x3377d1cf, v95
	v_fmac_f32_e32 v100, 0x3f317217, v92
	v_fmac_f32_e32 v101, 0x3f317217, v93
	v_fmac_f32_e32 v102, 0x3f317217, v94
	v_fmac_f32_e32 v103, 0x3f317217, v95
	v_cmp_lt_f32_e64 vcc, |v92|, s34
	v_cndmask_b32_e32 v92, v92, v100, vcc
	v_cmp_lt_f32_e64 vcc, |v93|, s34
	v_cndmask_b32_e32 v93, v93, v101, vcc
	v_cmp_lt_f32_e64 vcc, |v94|, s34
	v_cndmask_b32_e32 v94, v94, v102, vcc
	v_cmp_lt_f32_e64 vcc, |v95|, s34
	v_cndmask_b32_e32 v95, v95, v103, vcc
	v_cndmask_b32_e64 v100, 0, v213, s[22:23]
	v_cndmask_b32_e64 v101, 0, v213, s[24:25]
	v_cndmask_b32_e64 v102, 0, v213, s[26:27]
	v_cndmask_b32_e64 v103, 0, v213, s[28:29]
	v_sub_f32_e32 v92, v92, v100
	v_sub_f32_e32 v93, v93, v101
	v_sub_f32_e32 v94, v94, v102
	v_sub_f32_e32 v95, v95, v103
	v_add_f32_e32 v64, v64, v92
	v_add_f32_e32 v65, v65, v93
	v_add_f32_e32 v66, v66, v94
	v_add_f32_e32 v67, v67, v95
	v_mul_f32_e32 v92, 0xbfb8aa3b, v64
	v_mul_f32_e32 v93, 0xbfb8aa3b, v65
	v_mul_f32_e32 v94, 0xbfb8aa3b, v66
	v_mul_f32_e32 v95, 0xbfb8aa3b, v67
	v_mul_f32_e32 v100, 0x3fb8aa3b, v64
	v_mul_f32_e32 v101, 0x3fb8aa3b, v65
	v_mul_f32_e32 v102, 0x3fb8aa3b, v66
	v_mul_f32_e32 v103, 0x3fb8aa3b, v67
	v_exp_f32_e32 v92, v92
	v_exp_f32_e32 v93, v93
	v_exp_f32_e32 v94, v94
	v_exp_f32_e32 v95, v95
	v_exp_f32_e32 v100, v100
	v_exp_f32_e32 v101, v101
	v_exp_f32_e32 v102, v102
	v_exp_f32_e32 v103, v103
	v_sub_f32_e32 v96, 1.0, v96
	v_sub_f32_e32 v97, 1.0, v97
	v_sub_f32_e32 v98, 1.0, v98
	v_sub_f32_e32 v99, 1.0, v99
	v_mul_f32_e32 v96, v96, v92
	v_mul_f32_e32 v97, v97, v93
	v_mul_f32_e32 v98, v98, v94
	v_mul_f32_e32 v99, v99, v95
	v_lshlrev_b32_e32 v92, 16, v42
	v_and_b32_e32 v93, 0xffff0000, v42
	v_lshlrev_b32_e32 v94, 16, v43
	v_and_b32_e32 v95, 0xffff0000, v43
	v_mul_f32_e32 v92, v92, v100
	v_mul_f32_e32 v93, v93, v101
	v_mul_f32_e32 v94, v94, v102
	v_mul_f32_e32 v95, v95, v103
	v_cvt_pk_bf16_f32 v108, v92, v93
	v_cvt_pk_bf16_f32 v109, v94, v95
	v_cvt_pk_bf16_f32 v110, v96, v97
	v_cvt_pk_bf16_f32 v111, v98, v99
	global_store_dwordx2 v112, v[108:109], s[2:3]
	global_store_dwordx2 v114, v[110:111], s[2:3]
	s_add_u32 s2, s2, 0x400
	s_addc_u32 s3, s3, 0
	v_mov_b32_e32 v104, v96
	v_mov_b32_e32 v105, v97
	v_mov_b32_e32 v106, v98
	v_mov_b32_e32 v107, v99
	v_lshlrev_b32_e32 v92, 16, v44
	v_and_b32_e32 v93, 0xffff0000, v44
	v_lshlrev_b32_e32 v94, 16, v45
	v_and_b32_e32 v95, 0xffff0000, v45
	v_mul_f32_e32 v92, 0xbfb8aa3b, v92
	v_mul_f32_e32 v93, 0xbfb8aa3b, v93
	v_mul_f32_e32 v94, 0xbfb8aa3b, v94
	v_mul_f32_e32 v95, 0xbfb8aa3b, v95
	v_exp_f32_e32 v92, v92
	v_exp_f32_e32 v93, v93
	v_exp_f32_e32 v94, v94
	v_exp_f32_e32 v95, v95
	v_add_f32_e32 v92, 1.0, v92
	v_add_f32_e32 v93, 1.0, v93
	v_add_f32_e32 v94, 1.0, v94
	v_add_f32_e32 v95, 1.0, v95
	v_rcp_f32_e32 v92, v92
	v_rcp_f32_e32 v93, v93
	v_rcp_f32_e32 v94, v94
	v_rcp_f32_e32 v95, v95
	v_fma_f32 v96, v72, v92, v68
	v_fma_f32 v97, v73, v93, v69
	v_fma_f32 v98, v74, v94, v70
	v_fma_f32 v99, v75, v95, v71
	v_cmp_gt_f32_e64 s[22:23], s30, v96
	v_cmp_gt_f32_e64 s[24:25], s30, v97
	v_cmp_gt_f32_e64 s[26:27], s30, v98
	v_cmp_gt_f32_e64 s[28:29], s30, v99
	v_cndmask_b32_e64 v92, 0, 32, s[22:23]
	v_cndmask_b32_e64 v93, 0, 32, s[24:25]
	v_cndmask_b32_e64 v94, 0, 32, s[26:27]
	v_cndmask_b32_e64 v95, 0, 32, s[28:29]
	v_ldexp_f32 v92, v96, v92
	v_ldexp_f32 v93, v97, v93
	v_ldexp_f32 v94, v98, v94
	v_ldexp_f32 v95, v99, v95
	v_log_f32_e32 v92, v92
	v_log_f32_e32 v93, v93
	v_log_f32_e32 v94, v94
	v_log_f32_e32 v95, v95
	v_mul_f32_e32 v100, 0x3f317217, v92
	v_mul_f32_e32 v101, 0x3f317217, v93
	v_mul_f32_e32 v102, 0x3f317217, v94
; DEV u16 f2bf(float f) { return (u16)(pack2(f, f) & 0xffffu); }
; DEV float bf2f(u16 h) { return __uint_as_float(((unsigned)h) << 16); }
; DEV float sigmoid_f(float x) { return __builtin_amdgcn_rcpf(1.f + __expf(-x)); }
; DEV void phase_p15(const Params& p, int g) {
;     ...
;       for (int cc = 0; cc < 2; ++cc) {
;         const int c = tid + 256 * cc;
;         unsigned kb[8];
; #pragma unroll
;         for (int e = 0; e < 8; ++e) {
;           const int jj = j8 * 8 + e;
;           const int j = dir ? 63 - jj : jj;
;           const size_t tok = (size_t)cidx * 64 + j;
;           const float f = lb[cc] + (1.f - lb[cc]) * sigmoid_f(bf2f(xr[st][cc][e]));
;           G[cc] += __logf(f);
;           const float eg = __expf(G[cc]), ig = __expf(-G[cc]);
;           Qp[tok * 512 + c] = f2bf(bf2f(qr[st][cc][e]) * eg);
;           const u16 kk = f2bf((1.f - f) * ig);
;           Kp[tok * 512 + c] = kk;
;           kb[e] = kk;
;         }
;         const int s0 = dir ? 56 - 8 * j8 : 8 * j8;
;         uint4 w;
;         w.x = dir ? (kb[7] | (kb[6] << 16)) : (kb[0] | (kb[1] << 16));
;         w.y = dir ? (kb[5] | (kb[4] << 16)) : (kb[2] | (kb[3] << 16));
;         w.z = dir ? (kb[3] | (kb[2] << 16)) : (kb[4] | (kb[5] << 16));
;         w.w = dir ? (kb[1] | (kb[0] << 16)) : (kb[6] | (kb[7] << 16));
;         *(uint4*)(KT + (((size_t)cidx * 2 + dir) * 512 + c) * 64 + s0) = w;
	v_mul_f32_e32 v103, 0x3f317217, v95
	v_fma_f32 v100, v92, s31, -v100
	v_fma_f32 v101, v93, s31, -v101
	v_fma_f32 v102, v94, s31, -v102
	v_fma_f32 v103, v95, s31, -v103
	v_fmac_f32_e32 v100, 0x3377d1cf, v92
	v_fmac_f32_e32 v101, 0x3377d1cf, v93
	v_fmac_f32_e32 v102, 0x3377d1cf, v94
	v_fmac_f32_e32 v103, 0x3377d1cf, v95
	v_fmac_f32_e32 v100, 0x3f317217, v92
	v_fmac_f32_e32 v101, 0x3f317217, v93
	v_fmac_f32_e32 v102, 0x3f317217, v94
	v_fmac_f32_e32 v103, 0x3f317217, v95
	v_cmp_lt_f32_e64 vcc, |v92|, s34
	v_cndmask_b32_e32 v92, v92, v100, vcc
	v_cmp_lt_f32_e64 vcc, |v93|, s34
	v_cndmask_b32_e32 v93, v93, v101, vcc
	v_cmp_lt_f32_e64 vcc, |v94|, s34
	v_cndmask_b32_e32 v94, v94, v102, vcc
	v_cmp_lt_f32_e64 vcc, |v95|, s34
	v_cndmask_b32_e32 v95, v95, v103, vcc
	v_cndmask_b32_e64 v100, 0, v213, s[22:23]
	v_cndmask_b32_e64 v101, 0, v213, s[24:25]
	v_cndmask_b32_e64 v102, 0, v213, s[26:27]
	v_cndmask_b32_e64 v103, 0, v213, s[28:29]
	v_sub_f32_e32 v92, v92, v100
	v_sub_f32_e32 v93, v93, v101
	v_sub_f32_e32 v94, v94, v102
	v_sub_f32_e32 v95, v95, v103
	v_add_f32_e32 v64, v64, v92
	v_add_f32_e32 v65, v65, v93
	v_add_f32_e32 v66, v66, v94
	v_add_f32_e32 v67, v67, v95
	v_mul_f32_e32 v92, 0xbfb8aa3b, v64
	v_mul_f32_e32 v93, 0xbfb8aa3b, v65
	v_mul_f32_e32 v94, 0xbfb8aa3b, v66
	v_mul_f32_e32 v95, 0xbfb8aa3b, v67
	v_mul_f32_e32 v100, 0x3fb8aa3b, v64
	v_mul_f32_e32 v101, 0x3fb8aa3b, v65
	v_mul_f32_e32 v102, 0x3fb8aa3b, v66
	v_mul_f32_e32 v103, 0x3fb8aa3b, v67
	v_exp_f32_e32 v92, v92
	v_exp_f32_e32 v93, v93
	v_exp_f32_e32 v94, v94
	v_exp_f32_e32 v95, v95
	v_exp_f32_e32 v100, v100
	v_exp_f32_e32 v101, v101
	v_exp_f32_e32 v102, v102
	v_exp_f32_e32 v103, v103
	v_sub_f32_e32 v96, 1.0, v96
	v_sub_f32_e32 v97, 1.0, v97
	v_sub_f32_e32 v98, 1.0, v98
	v_sub_f32_e32 v99, 1.0, v99
	v_mul_f32_e32 v96, v96, v92
	v_mul_f32_e32 v97, v97, v93
	v_mul_f32_e32 v98, v98, v94
	v_mul_f32_e32 v99, v99, v95
	v_lshlrev_b32_e32 v92, 16, v46
	v_and_b32_e32 v93, 0xffff0000, v46
	v_lshlrev_b32_e32 v94, 16, v47
	v_and_b32_e32 v95, 0xffff0000, v47
	v_mul_f32_e32 v92, v92, v100
	v_mul_f32_e32 v93, v93, v101
	v_mul_f32_e32 v94, v94, v102
	v_mul_f32_e32 v95, v95, v103
	v_cvt_pk_bf16_f32 v108, v92, v93
	v_cvt_pk_bf16_f32 v109, v94, v95
	v_cvt_pk_bf16_f32 v110, v96, v97
	v_cvt_pk_bf16_f32 v111, v98, v99
	global_store_dwordx2 v112, v[108:109], s[2:3]
	global_store_dwordx2 v114, v[110:111], s[2:3]
	s_add_u32 s2, s2, 0x400
	s_addc_u32 s3, s3, 0
	v_cvt_pk_bf16_f32 v121, v104, v96
	v_cvt_pk_bf16_f32 v129, v105, v97
	v_cvt_pk_bf16_f32 v137, v106, v98
	v_cvt_pk_bf16_f32 v145, v107, v99
	v_lshlrev_b32_e32 v92, 16, v48
	v_and_b32_e32 v93, 0xffff0000, v48
	v_lshlrev_b32_e32 v94, 16, v49
	v_and_b32_e32 v95, 0xffff0000, v49
	v_mul_f32_e32 v92, 0xbfb8aa3b, v92
	v_mul_f32_e32 v93, 0xbfb8aa3b, v93
	v_mul_f32_e32 v94, 0xbfb8aa3b, v94
	v_mul_f32_e32 v95, 0xbfb8aa3b, v95
	v_exp_f32_e32 v92, v92
	v_exp_f32_e32 v93, v93
	v_exp_f32_e32 v94, v94
	v_exp_f32_e32 v95, v95
	v_add_f32_e32 v92, 1.0, v92
	v_add_f32_e32 v93, 1.0, v93
	v_add_f32_e32 v94, 1.0, v94
	v_add_f32_e32 v95, 1.0, v95
	v_rcp_f32_e32 v92, v92
	v_rcp_f32_e32 v93, v93
	v_rcp_f32_e32 v94, v94
	v_rcp_f32_e32 v95, v95
	v_fma_f32 v96, v72, v92, v68
	v_fma_f32 v97, v73, v93, v69
	v_fma_f32 v98, v74, v94, v70
	v_fma_f32 v99, v75, v95, v71
	v_cmp_gt_f32_e64 s[22:23], s30, v96
	v_cmp_gt_f32_e64 s[24:25], s30, v97
	v_cmp_gt_f32_e64 s[26:27], s30, v98
	v_cmp_gt_f32_e64 s[28:29], s30, v99
	v_cndmask_b32_e64 v92, 0, 32, s[22:23]
	v_cndmask_b32_e64 v93, 0, 32, s[24:25]
	v_cndmask_b32_e64 v94, 0, 32, s[26:27]
	v_cndmask_b32_e64 v95, 0, 32, s[28:29]
	v_ldexp_f32 v92, v96, v92
	v_ldexp_f32 v93, v97, v93
	v_ldexp_f32 v94, v98, v94
	v_ldexp_f32 v95, v99, v95
	v_log_f32_e32 v92, v92
	v_log_f32_e32 v93, v93
	v_log_f32_e32 v94, v94
	v_log_f32_e32 v95, v95
	v_mul_f32_e32 v100, 0x3f317217, v92
	v_mul_f32_e32 v101, 0x3f317217, v93
	v_mul_f32_e32 v102, 0x3f317217, v94
	v_mul_f32_e32 v103, 0x3f317217, v95
	v_fma_f32 v100, v92, s31, -v100
	v_fma_f32 v101, v93, s31, -v101
	v_fma_f32 v102, v94, s31, -v102
	v_fma_f32 v103, v95, s31, -v103
	v_fmac_f32_e32 v100, 0x3377d1cf, v92
	v_fmac_f32_e32 v101, 0x3377d1cf, v93
	v_fmac_f32_e32 v102, 0x3377d1cf, v94
	v_fmac_f32_e32 v103, 0x3377d1cf, v95
	v_fmac_f32_e32 v100, 0x3f317217, v92
	v_fmac_f32_e32 v101, 0x3f317217, v93
	v_fmac_f32_e32 v102, 0x3f317217, v94
	v_fmac_f32_e32 v103, 0x3f317217, v95
	v_cmp_lt_f32_e64 vcc, |v92|, s34
	v_cndmask_b32_e32 v92, v92, v100, vcc
	v_cmp_lt_f32_e64 vcc, |v93|, s34
	v_cndmask_b32_e32 v93, v93, v101, vcc
	v_cmp_lt_f32_e64 vcc, |v94|, s34
	v_cndmask_b32_e32 v94, v94, v102, vcc
	v_cmp_lt_f32_e64 vcc, |v95|, s34
	v_cndmask_b32_e32 v95, v95, v103, vcc
	v_cndmask_b32_e64 v100, 0, v213, s[22:23]
	v_cndmask_b32_e64 v101, 0, v213, s[24:25]
	v_cndmask_b32_e64 v102, 0, v213, s[26:27]
	v_cndmask_b32_e64 v103, 0, v213, s[28:29]
	v_sub_f32_e32 v92, v92, v100
	v_sub_f32_e32 v93, v93, v101
	v_sub_f32_e32 v94, v94, v102
	v_sub_f32_e32 v95, v95, v103
	v_add_f32_e32 v64, v64, v92
	v_add_f32_e32 v65, v65, v93
	v_add_f32_e32 v66, v66, v94
	v_add_f32_e32 v67, v67, v95
	v_mul_f32_e32 v92, 0xbfb8aa3b, v64
	v_mul_f32_e32 v93, 0xbfb8aa3b, v65
	v_mul_f32_e32 v94, 0xbfb8aa3b, v66
	v_mul_f32_e32 v95, 0xbfb8aa3b, v67
	v_mul_f32_e32 v100, 0x3fb8aa3b, v64
	v_mul_f32_e32 v101, 0x3fb8aa3b, v65
	v_mul_f32_e32 v102, 0x3fb8aa3b, v66
	v_mul_f32_e32 v103, 0x3fb8aa3b, v67
	v_exp_f32_e32 v92, v92
	v_exp_f32_e32 v93, v93
	v_exp_f32_e32 v94, v94
	v_exp_f32_e32 v95, v95
	v_exp_f32_e32 v100, v100
	v_exp_f32_e32 v101, v101
	v_exp_f32_e32 v102, v102
	v_exp_f32_e32 v103, v103
	v_sub_f32_e32 v96, 1.0, v96
	v_sub_f32_e32 v97, 1.0, v97
	v_sub_f32_e32 v98, 1.0, v98
; DEV u16 f2bf(float f) { return (u16)(pack2(f, f) & 0xffffu); }
; DEV float bf2f(u16 h) { return __uint_as_float(((unsigned)h) << 16); }
; DEV float sigmoid_f(float x) { return __builtin_amdgcn_rcpf(1.f + __expf(-x)); }
; DEV void phase_p15(const Params& p, int g) {
;     ...
;       for (int cc = 0; cc < 2; ++cc) {
;         const int c = tid + 256 * cc;
;         unsigned kb[8];
; #pragma unroll
;         for (int e = 0; e < 8; ++e) {
;           const int jj = j8 * 8 + e;
;           const int j = dir ? 63 - jj : jj;
;           const size_t tok = (size_t)cidx * 64 + j;
;           const float f = lb[cc] + (1.f - lb[cc]) * sigmoid_f(bf2f(xr[st][cc][e]));
;           G[cc] += __logf(f);
;           const float eg = __expf(G[cc]), ig = __expf(-G[cc]);
;           Qp[tok * 512 + c] = f2bf(bf2f(qr[st][cc][e]) * eg);
;           const u16 kk = f2bf((1.f - f) * ig);
;           Kp[tok * 512 + c] = kk;
;           kb[e] = kk;
;         }
;         const int s0 = dir ? 56 - 8 * j8 : 8 * j8;
;         uint4 w;
;         w.x = dir ? (kb[7] | (kb[6] << 16)) : (kb[0] | (kb[1] << 16));
;         w.y = dir ? (kb[5] | (kb[4] << 16)) : (kb[2] | (kb[3] << 16));
;         w.z = dir ? (kb[3] | (kb[2] << 16)) : (kb[4] | (kb[5] << 16));
;         w.w = dir ? (kb[1] | (kb[0] << 16)) : (kb[6] | (kb[7] << 16));
;         *(uint4*)(KT + (((size_t)cidx * 2 + dir) * 512 + c) * 64 + s0) = w;
	v_sub_f32_e32 v99, 1.0, v99
	v_mul_f32_e32 v96, v96, v92
	v_mul_f32_e32 v97, v97, v93
	v_mul_f32_e32 v98, v98, v94
	v_mul_f32_e32 v99, v99, v95
	v_lshlrev_b32_e32 v92, 16, v50
	v_and_b32_e32 v93, 0xffff0000, v50
	v_lshlrev_b32_e32 v94, 16, v51
	v_and_b32_e32 v95, 0xffff0000, v51
	v_mul_f32_e32 v92, v92, v100
	v_mul_f32_e32 v93, v93, v101
	v_mul_f32_e32 v94, v94, v102
	v_mul_f32_e32 v95, v95, v103
	v_cvt_pk_bf16_f32 v108, v92, v93
	v_cvt_pk_bf16_f32 v109, v94, v95
	v_cvt_pk_bf16_f32 v110, v96, v97
	v_cvt_pk_bf16_f32 v111, v98, v99
	global_store_dwordx2 v112, v[108:109], s[2:3]
	global_store_dwordx2 v114, v[110:111], s[2:3]
	s_add_u32 s2, s2, 0x400
	s_addc_u32 s3, s3, 0
	v_mov_b32_e32 v104, v96
	v_mov_b32_e32 v105, v97
	v_mov_b32_e32 v106, v98
	v_mov_b32_e32 v107, v99
	v_lshlrev_b32_e32 v92, 16, v52
	v_and_b32_e32 v93, 0xffff0000, v52
	v_lshlrev_b32_e32 v94, 16, v53
	v_and_b32_e32 v95, 0xffff0000, v53
	v_mul_f32_e32 v92, 0xbfb8aa3b, v92
	v_mul_f32_e32 v93, 0xbfb8aa3b, v93
	v_mul_f32_e32 v94, 0xbfb8aa3b, v94
	v_mul_f32_e32 v95, 0xbfb8aa3b, v95
	v_exp_f32_e32 v92, v92
	v_exp_f32_e32 v93, v93
	v_exp_f32_e32 v94, v94
	v_exp_f32_e32 v95, v95
	v_add_f32_e32 v92, 1.0, v92
	v_add_f32_e32 v93, 1.0, v93
	v_add_f32_e32 v94, 1.0, v94
	v_add_f32_e32 v95, 1.0, v95
	v_rcp_f32_e32 v92, v92
	v_rcp_f32_e32 v93, v93
	v_rcp_f32_e32 v94, v94
	v_rcp_f32_e32 v95, v95
	v_fma_f32 v96, v72, v92, v68
	v_fma_f32 v97, v73, v93, v69
	v_fma_f32 v98, v74, v94, v70
	v_fma_f32 v99, v75, v95, v71
	v_cmp_gt_f32_e64 s[22:23], s30, v96
	v_cmp_gt_f32_e64 s[24:25], s30, v97
	v_cmp_gt_f32_e64 s[26:27], s30, v98
	v_cmp_gt_f32_e64 s[28:29], s30, v99
	v_cndmask_b32_e64 v92, 0, 32, s[22:23]
	v_cndmask_b32_e64 v93, 0, 32, s[24:25]
	v_cndmask_b32_e64 v94, 0, 32, s[26:27]
	v_cndmask_b32_e64 v95, 0, 32, s[28:29]
	v_ldexp_f32 v92, v96, v92
	v_ldexp_f32 v93, v97, v93
	v_ldexp_f32 v94, v98, v94
	v_ldexp_f32 v95, v99, v95
	v_log_f32_e32 v92, v92
	v_log_f32_e32 v93, v93
	v_log_f32_e32 v94, v94
	v_log_f32_e32 v95, v95
	v_mul_f32_e32 v100, 0x3f317217, v92
	v_mul_f32_e32 v101, 0x3f317217, v93
	v_mul_f32_e32 v102, 0x3f317217, v94
	v_mul_f32_e32 v103, 0x3f317217, v95
	v_fma_f32 v100, v92, s31, -v100
	v_fma_f32 v101, v93, s31, -v101
	v_fma_f32 v102, v94, s31, -v102
	v_fma_f32 v103, v95, s31, -v103
	v_fmac_f32_e32 v100, 0x3377d1cf, v92
	v_fmac_f32_e32 v101, 0x3377d1cf, v93
	v_fmac_f32_e32 v102, 0x3377d1cf, v94
	v_fmac_f32_e32 v103, 0x3377d1cf, v95
	v_fmac_f32_e32 v100, 0x3f317217, v92
	v_fmac_f32_e32 v101, 0x3f317217, v93
	v_fmac_f32_e32 v102, 0x3f317217, v94
	v_fmac_f32_e32 v103, 0x3f317217, v95
	v_cmp_lt_f32_e64 vcc, |v92|, s34
	v_cndmask_b32_e32 v92, v92, v100, vcc
	v_cmp_lt_f32_e64 vcc, |v93|, s34
	v_cndmask_b32_e32 v93, v93, v101, vcc
	v_cmp_lt_f32_e64 vcc, |v94|, s34
	v_cndmask_b32_e32 v94, v94, v102, vcc
	v_cmp_lt_f32_e64 vcc, |v95|, s34
	v_cndmask_b32_e32 v95, v95, v103, vcc
	v_cndmask_b32_e64 v100, 0, v213, s[22:23]
	v_cndmask_b32_e64 v101, 0, v213, s[24:25]
	v_cndmask_b32_e64 v102, 0, v213, s[26:27]
	v_cndmask_b32_e64 v103, 0, v213, s[28:29]
	v_sub_f32_e32 v92, v92, v100
	v_sub_f32_e32 v93, v93, v101
	v_sub_f32_e32 v94, v94, v102
	v_sub_f32_e32 v95, v95, v103
	v_add_f32_e32 v64, v64, v92
	v_add_f32_e32 v65, v65, v93
	v_add_f32_e32 v66, v66, v94
	v_add_f32_e32 v67, v67, v95
	v_mul_f32_e32 v92, 0xbfb8aa3b, v64
	v_mul_f32_e32 v93, 0xbfb8aa3b, v65
	v_mul_f32_e32 v94, 0xbfb8aa3b, v66
	v_mul_f32_e32 v95, 0xbfb8aa3b, v67
	v_mul_f32_e32 v100, 0x3fb8aa3b, v64
	v_mul_f32_e32 v101, 0x3fb8aa3b, v65
	v_mul_f32_e32 v102, 0x3fb8aa3b, v66
	v_mul_f32_e32 v103, 0x3fb8aa3b, v67
	v_exp_f32_e32 v92, v92
	v_exp_f32_e32 v93, v93
	v_exp_f32_e32 v94, v94
	v_exp_f32_e32 v95, v95
	v_exp_f32_e32 v100, v100
	v_exp_f32_e32 v101, v101
	v_exp_f32_e32 v102, v102
	v_exp_f32_e32 v103, v103
	v_sub_f32_e32 v96, 1.0, v96
	v_sub_f32_e32 v97, 1.0, v97
	v_sub_f32_e32 v98, 1.0, v98
	v_sub_f32_e32 v99, 1.0, v99
	v_mul_f32_e32 v96, v96, v92
	v_mul_f32_e32 v97, v97, v93
	v_mul_f32_e32 v98, v98, v94
	v_mul_f32_e32 v99, v99, v95
	v_lshlrev_b32_e32 v92, 16, v54
	v_and_b32_e32 v93, 0xffff0000, v54
	v_lshlrev_b32_e32 v94, 16, v55
	v_and_b32_e32 v95, 0xffff0000, v55
	v_mul_f32_e32 v92, v92, v100
	v_mul_f32_e32 v93, v93, v101
	v_mul_f32_e32 v94, v94, v102
	v_mul_f32_e32 v95, v95, v103
	v_cvt_pk_bf16_f32 v108, v92, v93
	v_cvt_pk_bf16_f32 v109, v94, v95
	v_cvt_pk_bf16_f32 v110, v96, v97
	v_cvt_pk_bf16_f32 v111, v98, v99
	global_store_dwordx2 v112, v[108:109], s[2:3]
	global_store_dwordx2 v114, v[110:111], s[2:3]
	s_add_u32 s2, s2, 0x400
	s_addc_u32 s3, s3, 0
	v_cvt_pk_bf16_f32 v122, v104, v96
	v_cvt_pk_bf16_f32 v130, v105, v97
	v_cvt_pk_bf16_f32 v138, v106, v98
	v_cvt_pk_bf16_f32 v146, v107, v99
	v_lshlrev_b32_e32 v92, 16, v56
	v_and_b32_e32 v93, 0xffff0000, v56
	v_lshlrev_b32_e32 v94, 16, v57
	v_and_b32_e32 v95, 0xffff0000, v57
	v_mul_f32_e32 v92, 0xbfb8aa3b, v92
	v_mul_f32_e32 v93, 0xbfb8aa3b, v93
	v_mul_f32_e32 v94, 0xbfb8aa3b, v94
	v_mul_f32_e32 v95, 0xbfb8aa3b, v95
	v_exp_f32_e32 v92, v92
	v_exp_f32_e32 v93, v93
	v_exp_f32_e32 v94, v94
	v_exp_f32_e32 v95, v95
	v_add_f32_e32 v92, 1.0, v92
	v_add_f32_e32 v93, 1.0, v93
	v_add_f32_e32 v94, 1.0, v94
	v_add_f32_e32 v95, 1.0, v95
	v_rcp_f32_e32 v92, v92
	v_rcp_f32_e32 v93, v93
	v_rcp_f32_e32 v94, v94
	v_rcp_f32_e32 v95, v95
	v_fma_f32 v96, v72, v92, v68
	v_fma_f32 v97, v73, v93, v69
	v_fma_f32 v98, v74, v94, v70
	v_fma_f32 v99, v75, v95, v71
	v_cmp_gt_f32_e64 s[22:23], s30, v96
	v_cmp_gt_f32_e64 s[24:25], s30, v97
	v_cmp_gt_f32_e64 s[26:27], s30, v98
	v_cmp_gt_f32_e64 s[28:29], s30, v99
	v_cndmask_b32_e64 v92, 0, 32, s[22:23]
	v_cndmask_b32_e64 v93, 0, 32, s[24:25]
	v_cndmask_b32_e64 v94, 0, 32, s[26:27]
; DEV u16 f2bf(float f) { return (u16)(pack2(f, f) & 0xffffu); }
; DEV float bf2f(u16 h) { return __uint_as_float(((unsigned)h) << 16); }
; DEV float sigmoid_f(float x) { return __builtin_amdgcn_rcpf(1.f + __expf(-x)); }
; DEV void phase_p15(const Params& p, int g) {
;     ...
;       for (int cc = 0; cc < 2; ++cc) {
;         const int c = tid + 256 * cc;
;         unsigned kb[8];
; #pragma unroll
;         for (int e = 0; e < 8; ++e) {
;           const int jj = j8 * 8 + e;
;           const int j = dir ? 63 - jj : jj;
;           const size_t tok = (size_t)cidx * 64 + j;
;           const float f = lb[cc] + (1.f - lb[cc]) * sigmoid_f(bf2f(xr[st][cc][e]));
;           G[cc] += __logf(f);
;           const float eg = __expf(G[cc]), ig = __expf(-G[cc]);
;           Qp[tok * 512 + c] = f2bf(bf2f(qr[st][cc][e]) * eg);
;           const u16 kk = f2bf((1.f - f) * ig);
;           Kp[tok * 512 + c] = kk;
;           kb[e] = kk;
;         }
;         const int s0 = dir ? 56 - 8 * j8 : 8 * j8;
;         uint4 w;
;         w.x = dir ? (kb[7] | (kb[6] << 16)) : (kb[0] | (kb[1] << 16));
;         w.y = dir ? (kb[5] | (kb[4] << 16)) : (kb[2] | (kb[3] << 16));
;         w.z = dir ? (kb[3] | (kb[2] << 16)) : (kb[4] | (kb[5] << 16));
;         w.w = dir ? (kb[1] | (kb[0] << 16)) : (kb[6] | (kb[7] << 16));
;         *(uint4*)(KT + (((size_t)cidx * 2 + dir) * 512 + c) * 64 + s0) = w;
	v_cndmask_b32_e64 v95, 0, 32, s[28:29]
	v_ldexp_f32 v92, v96, v92
	v_ldexp_f32 v93, v97, v93
	v_ldexp_f32 v94, v98, v94
	v_ldexp_f32 v95, v99, v95
	v_log_f32_e32 v92, v92
	v_log_f32_e32 v93, v93
	v_log_f32_e32 v94, v94
	v_log_f32_e32 v95, v95
	v_mul_f32_e32 v100, 0x3f317217, v92
	v_mul_f32_e32 v101, 0x3f317217, v93
	v_mul_f32_e32 v102, 0x3f317217, v94
	v_mul_f32_e32 v103, 0x3f317217, v95
	v_fma_f32 v100, v92, s31, -v100
	v_fma_f32 v101, v93, s31, -v101
	v_fma_f32 v102, v94, s31, -v102
	v_fma_f32 v103, v95, s31, -v103
	v_fmac_f32_e32 v100, 0x3377d1cf, v92
	v_fmac_f32_e32 v101, 0x3377d1cf, v93
	v_fmac_f32_e32 v102, 0x3377d1cf, v94
	v_fmac_f32_e32 v103, 0x3377d1cf, v95
	v_fmac_f32_e32 v100, 0x3f317217, v92
	v_fmac_f32_e32 v101, 0x3f317217, v93
	v_fmac_f32_e32 v102, 0x3f317217, v94
	v_fmac_f32_e32 v103, 0x3f317217, v95
	v_cmp_lt_f32_e64 vcc, |v92|, s34
	v_cndmask_b32_e32 v92, v92, v100, vcc
	v_cmp_lt_f32_e64 vcc, |v93|, s34
	v_cndmask_b32_e32 v93, v93, v101, vcc
	v_cmp_lt_f32_e64 vcc, |v94|, s34
	v_cndmask_b32_e32 v94, v94, v102, vcc
	v_cmp_lt_f32_e64 vcc, |v95|, s34
	v_cndmask_b32_e32 v95, v95, v103, vcc
	v_cndmask_b32_e64 v100, 0, v213, s[22:23]
	v_cndmask_b32_e64 v101, 0, v213, s[24:25]
	v_cndmask_b32_e64 v102, 0, v213, s[26:27]
	v_cndmask_b32_e64 v103, 0, v213, s[28:29]
	v_sub_f32_e32 v92, v92, v100
	v_sub_f32_e32 v93, v93, v101
	v_sub_f32_e32 v94, v94, v102
	v_sub_f32_e32 v95, v95, v103
	v_add_f32_e32 v64, v64, v92
	v_add_f32_e32 v65, v65, v93
	v_add_f32_e32 v66, v66, v94
	v_add_f32_e32 v67, v67, v95
	v_mul_f32_e32 v92, 0xbfb8aa3b, v64
	v_mul_f32_e32 v93, 0xbfb8aa3b, v65
	v_mul_f32_e32 v94, 0xbfb8aa3b, v66
	v_mul_f32_e32 v95, 0xbfb8aa3b, v67
	v_mul_f32_e32 v100, 0x3fb8aa3b, v64
	v_mul_f32_e32 v101, 0x3fb8aa3b, v65
	v_mul_f32_e32 v102, 0x3fb8aa3b, v66
	v_mul_f32_e32 v103, 0x3fb8aa3b, v67
	v_exp_f32_e32 v92, v92
	v_exp_f32_e32 v93, v93
	v_exp_f32_e32 v94, v94
	v_exp_f32_e32 v95, v95
	v_exp_f32_e32 v100, v100
	v_exp_f32_e32 v101, v101
	v_exp_f32_e32 v102, v102
	v_exp_f32_e32 v103, v103
	v_sub_f32_e32 v96, 1.0, v96
	v_sub_f32_e32 v97, 1.0, v97
	v_sub_f32_e32 v98, 1.0, v98
	v_sub_f32_e32 v99, 1.0, v99
	v_mul_f32_e32 v96, v96, v92
	v_mul_f32_e32 v97, v97, v93
	v_mul_f32_e32 v98, v98, v94
	v_mul_f32_e32 v99, v99, v95
	v_lshlrev_b32_e32 v92, 16, v58
	v_and_b32_e32 v93, 0xffff0000, v58
	v_lshlrev_b32_e32 v94, 16, v59
	v_and_b32_e32 v95, 0xffff0000, v59
	v_mul_f32_e32 v92, v92, v100
	v_mul_f32_e32 v93, v93, v101
	v_mul_f32_e32 v94, v94, v102
	v_mul_f32_e32 v95, v95, v103
	v_cvt_pk_bf16_f32 v108, v92, v93
	v_cvt_pk_bf16_f32 v109, v94, v95
	v_cvt_pk_bf16_f32 v110, v96, v97
	v_cvt_pk_bf16_f32 v111, v98, v99
	global_store_dwordx2 v112, v[108:109], s[2:3]
	global_store_dwordx2 v114, v[110:111], s[2:3]
	s_add_u32 s2, s2, 0x400
	s_addc_u32 s3, s3, 0
	v_mov_b32_e32 v104, v96
	v_mov_b32_e32 v105, v97
	v_mov_b32_e32 v106, v98
	v_mov_b32_e32 v107, v99
	v_lshlrev_b32_e32 v92, 16, v60
	v_and_b32_e32 v93, 0xffff0000, v60
	v_lshlrev_b32_e32 v94, 16, v61
	v_and_b32_e32 v95, 0xffff0000, v61
	v_mul_f32_e32 v92, 0xbfb8aa3b, v92
	v_mul_f32_e32 v93, 0xbfb8aa3b, v93
	v_mul_f32_e32 v94, 0xbfb8aa3b, v94
	v_mul_f32_e32 v95, 0xbfb8aa3b, v95
	v_exp_f32_e32 v92, v92
	v_exp_f32_e32 v93, v93
	v_exp_f32_e32 v94, v94
	v_exp_f32_e32 v95, v95
	v_add_f32_e32 v92, 1.0, v92
	v_add_f32_e32 v93, 1.0, v93
	v_add_f32_e32 v94, 1.0, v94
	v_add_f32_e32 v95, 1.0, v95
	v_rcp_f32_e32 v92, v92
	v_rcp_f32_e32 v93, v93
	v_rcp_f32_e32 v94, v94
	v_rcp_f32_e32 v95, v95
	v_fma_f32 v96, v72, v92, v68
	v_fma_f32 v97, v73, v93, v69
	v_fma_f32 v98, v74, v94, v70
	v_fma_f32 v99, v75, v95, v71
	v_cmp_gt_f32_e64 s[22:23], s30, v96
	v_cmp_gt_f32_e64 s[24:25], s30, v97
	v_cmp_gt_f32_e64 s[26:27], s30, v98
	v_cmp_gt_f32_e64 s[28:29], s30, v99
	v_cndmask_b32_e64 v92, 0, 32, s[22:23]
	v_cndmask_b32_e64 v93, 0, 32, s[24:25]
	v_cndmask_b32_e64 v94, 0, 32, s[26:27]
	v_cndmask_b32_e64 v95, 0, 32, s[28:29]
	v_ldexp_f32 v92, v96, v92
	v_ldexp_f32 v93, v97, v93
	v_ldexp_f32 v94, v98, v94
	v_ldexp_f32 v95, v99, v95
	v_log_f32_e32 v92, v92
	v_log_f32_e32 v93, v93
	v_log_f32_e32 v94, v94
	v_log_f32_e32 v95, v95
	v_mul_f32_e32 v100, 0x3f317217, v92
	v_mul_f32_e32 v101, 0x3f317217, v93
	v_mul_f32_e32 v102, 0x3f317217, v94
	v_mul_f32_e32 v103, 0x3f317217, v95
	v_fma_f32 v100, v92, s31, -v100
	v_fma_f32 v101, v93, s31, -v101
	v_fma_f32 v102, v94, s31, -v102
	v_fma_f32 v103, v95, s31, -v103
	v_fmac_f32_e32 v100, 0x3377d1cf, v92
	v_fmac_f32_e32 v101, 0x3377d1cf, v93
	v_fmac_f32_e32 v102, 0x3377d1cf, v94
	v_fmac_f32_e32 v103, 0x3377d1cf, v95
	v_fmac_f32_e32 v100, 0x3f317217, v92
	v_fmac_f32_e32 v101, 0x3f317217, v93
	v_fmac_f32_e32 v102, 0x3f317217, v94
	v_fmac_f32_e32 v103, 0x3f317217, v95
	v_cmp_lt_f32_e64 vcc, |v92|, s34
	v_cndmask_b32_e32 v92, v92, v100, vcc
	v_cmp_lt_f32_e64 vcc, |v93|, s34
	v_cndmask_b32_e32 v93, v93, v101, vcc
	v_cmp_lt_f32_e64 vcc, |v94|, s34
	v_cndmask_b32_e32 v94, v94, v102, vcc
	v_cmp_lt_f32_e64 vcc, |v95|, s34
	v_cndmask_b32_e32 v95, v95, v103, vcc
	v_cndmask_b32_e64 v100, 0, v213, s[22:23]
	v_cndmask_b32_e64 v101, 0, v213, s[24:25]
	v_cndmask_b32_e64 v102, 0, v213, s[26:27]
	v_cndmask_b32_e64 v103, 0, v213, s[28:29]
	v_sub_f32_e32 v92, v92, v100
	v_sub_f32_e32 v93, v93, v101
	v_sub_f32_e32 v94, v94, v102
	v_sub_f32_e32 v95, v95, v103
	v_add_f32_e32 v64, v64, v92
	v_add_f32_e32 v65, v65, v93
	v_add_f32_e32 v66, v66, v94
	v_add_f32_e32 v67, v67, v95
	v_mul_f32_e32 v92, 0xbfb8aa3b, v64
	v_mul_f32_e32 v93, 0xbfb8aa3b, v65
	v_mul_f32_e32 v94, 0xbfb8aa3b, v66
	v_mul_f32_e32 v95, 0xbfb8aa3b, v67
	v_mul_f32_e32 v100, 0x3fb8aa3b, v64
	v_mul_f32_e32 v101, 0x3fb8aa3b, v65
	v_mul_f32_e32 v102, 0x3fb8aa3b, v66
; DEV u16 f2bf(float f) { return (u16)(pack2(f, f) & 0xffffu); }
; DEV float bf2f(u16 h) { return __uint_as_float(((unsigned)h) << 16); }
; DEV float sigmoid_f(float x) { return __builtin_amdgcn_rcpf(1.f + __expf(-x)); }
; DEV void phase_p15(const Params& p, int g) {
;     ...
;     P15_LOAD(0, 0);
;     P15_LOAD(1, 1);
; #pragma unroll
;     for (int j8 = 0; j8 < 8; ++j8) {
;       const int st = j8 % 3;
;       if (j8 < 6) { P15_LOAD((j8 + 2) % 3, j8 + 2); }
; #pragma unroll
;       for (int cc = 0; cc < 2; ++cc) {
;         const int c = tid + 256 * cc;
;         unsigned kb[8];
; #pragma unroll
;         for (int e = 0; e < 8; ++e) {
;           const int jj = j8 * 8 + e;
;           const int j = dir ? 63 - jj : jj;
;           const size_t tok = (size_t)cidx * 64 + j;
;           const float f = lb[cc] + (1.f - lb[cc]) * sigmoid_f(bf2f(xr[st][cc][e]));
;           G[cc] += __logf(f);
;           const float eg = __expf(G[cc]), ig = __expf(-G[cc]);
;           Qp[tok * 512 + c] = f2bf(bf2f(qr[st][cc][e]) * eg);
;           const u16 kk = f2bf((1.f - f) * ig);
;           Kp[tok * 512 + c] = kk;
;           kb[e] = kk;
;         }
;         const int s0 = dir ? 56 - 8 * j8 : 8 * j8;
;         uint4 w;
;         w.x = dir ? (kb[7] | (kb[6] << 16)) : (kb[0] | (kb[1] << 16));
;         w.y = dir ? (kb[5] | (kb[4] << 16)) : (kb[2] | (kb[3] << 16));
;         w.z = dir ? (kb[3] | (kb[2] << 16)) : (kb[4] | (kb[5] << 16));
;         w.w = dir ? (kb[1] | (kb[0] << 16)) : (kb[6] | (kb[7] << 16));
;         *(uint4*)(KT + (((size_t)cidx * 2 + dir) * 512 + c) * 64 + s0) = w;
;       }
;     }
	v_mul_f32_e32 v103, 0x3fb8aa3b, v67
	v_exp_f32_e32 v92, v92
	v_exp_f32_e32 v93, v93
	v_exp_f32_e32 v94, v94
	v_exp_f32_e32 v95, v95
	v_exp_f32_e32 v100, v100
	v_exp_f32_e32 v101, v101
	v_exp_f32_e32 v102, v102
	v_exp_f32_e32 v103, v103
	v_sub_f32_e32 v96, 1.0, v96
	v_sub_f32_e32 v97, 1.0, v97
	v_sub_f32_e32 v98, 1.0, v98
	v_sub_f32_e32 v99, 1.0, v99
	v_mul_f32_e32 v96, v96, v92
	v_mul_f32_e32 v97, v97, v93
	v_mul_f32_e32 v98, v98, v94
	v_mul_f32_e32 v99, v99, v95
	v_lshlrev_b32_e32 v92, 16, v62
	v_and_b32_e32 v93, 0xffff0000, v62
	v_lshlrev_b32_e32 v94, 16, v63
	v_and_b32_e32 v95, 0xffff0000, v63
	v_mul_f32_e32 v92, v92, v100
	v_mul_f32_e32 v93, v93, v101
	v_mul_f32_e32 v94, v94, v102
	v_mul_f32_e32 v95, v95, v103
	v_cvt_pk_bf16_f32 v108, v92, v93
	v_cvt_pk_bf16_f32 v109, v94, v95
	v_cvt_pk_bf16_f32 v110, v96, v97
	v_cvt_pk_bf16_f32 v111, v98, v99
	global_store_dwordx2 v112, v[108:109], s[2:3]
	global_store_dwordx2 v114, v[110:111], s[2:3]
	s_add_u32 s2, s2, 0x400
	s_addc_u32 s3, s3, 0
	v_cvt_pk_bf16_f32 v123, v104, v96
	v_cvt_pk_bf16_f32 v131, v105, v97
	v_cvt_pk_bf16_f32 v139, v106, v98
	v_cvt_pk_bf16_f32 v147, v107, v99
	global_store_dwordx4 v115, v[116:119], s[4:5]
	global_store_dwordx4 v115, v[120:123], s[4:5] offset:16
	global_store_dwordx4 v115, v[124:127], s[4:5] offset:128
	global_store_dwordx4 v115, v[128:131], s[4:5] offset:144
	global_store_dwordx4 v115, v[132:135], s[4:5] offset:256
	global_store_dwordx4 v115, v[136:139], s[4:5] offset:272
	global_store_dwordx4 v115, v[140:143], s[4:5] offset:384
	global_store_dwordx4 v115, v[144:147], s[4:5] offset:400
	s_add_u32 s4, s4, 32
	s_addc_u32 s5, s5, 0
	global_load_dwordx2 v[32:33], v113, s[0:1]
	global_load_dwordx2 v[34:35], v112, s[0:1]
	s_add_u32 s0, s0, 0x1400
	s_addc_u32 s1, s1, 0
	global_load_dwordx2 v[36:37], v113, s[0:1]
	global_load_dwordx2 v[38:39], v112, s[0:1]
	s_add_u32 s0, s0, 0x1400
	s_addc_u32 s1, s1, 0
	global_load_dwordx2 v[40:41], v113, s[0:1]
	global_load_dwordx2 v[42:43], v112, s[0:1]
	s_add_u32 s0, s0, 0x1400
	s_addc_u32 s1, s1, 0
	global_load_dwordx2 v[44:45], v113, s[0:1]
	global_load_dwordx2 v[46:47], v112, s[0:1]
	s_add_u32 s0, s0, 0x1400
	s_addc_u32 s1, s1, 0
	global_load_dwordx2 v[48:49], v113, s[0:1]
	global_load_dwordx2 v[50:51], v112, s[0:1]
	s_add_u32 s0, s0, 0x1400
	s_addc_u32 s1, s1, 0
	global_load_dwordx2 v[52:53], v113, s[0:1]
	global_load_dwordx2 v[54:55], v112, s[0:1]
	s_add_u32 s0, s0, 0x1400
	s_addc_u32 s1, s1, 0
	global_load_dwordx2 v[56:57], v113, s[0:1]
	global_load_dwordx2 v[58:59], v112, s[0:1]
	s_add_u32 s0, s0, 0x1400
	s_addc_u32 s1, s1, 0
	global_load_dwordx2 v[60:61], v113, s[0:1]
	global_load_dwordx2 v[62:63], v112, s[0:1]
	s_add_u32 s0, s0, 0x1400
	s_addc_u32 s1, s1, 0
	s_add_u32 s35, s35, 1
	s_cmp_lt_u32 s35, 4
	s_cbranch_scc1 .Lp15_d0_loop
	s_branch .Lp15_done
.Lp15_d1:
	global_load_dwordx2 v[0:1], v113, s[0:1]
	global_load_dwordx2 v[2:3], v112, s[0:1]
	s_sub_u32 s0, s0, 0x1400
	s_subb_u32 s1, s1, 0
	global_load_dwordx2 v[4:5], v113, s[0:1]
	global_load_dwordx2 v[6:7], v112, s[0:1]
	s_sub_u32 s0, s0, 0x1400
	s_subb_u32 s1, s1, 0
	global_load_dwordx2 v[8:9], v113, s[0:1]
	global_load_dwordx2 v[10:11], v112, s[0:1]
	s_sub_u32 s0, s0, 0x1400
	s_subb_u32 s1, s1, 0
	global_load_dwordx2 v[12:13], v113, s[0:1]
	global_load_dwordx2 v[14:15], v112, s[0:1]
	s_sub_u32 s0, s0, 0x1400
	s_subb_u32 s1, s1, 0
	global_load_dwordx2 v[16:17], v113, s[0:1]
	global_load_dwordx2 v[18:19], v112, s[0:1]
	s_sub_u32 s0, s0, 0x1400
	s_subb_u32 s1, s1, 0
	global_load_dwordx2 v[20:21], v113, s[0:1]
	global_load_dwordx2 v[22:23], v112, s[0:1]
	s_sub_u32 s0, s0, 0x1400
	s_subb_u32 s1, s1, 0
	global_load_dwordx2 v[24:25], v113, s[0:1]
	global_load_dwordx2 v[26:27], v112, s[0:1]
	s_sub_u32 s0, s0, 0x1400
	s_subb_u32 s1, s1, 0
	global_load_dwordx2 v[28:29], v113, s[0:1]
	global_load_dwordx2 v[30:31], v112, s[0:1]
	s_sub_u32 s0, s0, 0x1400
	s_subb_u32 s1, s1, 0
	global_load_dwordx2 v[32:33], v113, s[0:1]
	global_load_dwordx2 v[34:35], v112, s[0:1]
	s_sub_u32 s0, s0, 0x1400
	s_subb_u32 s1, s1, 0
	global_load_dwordx2 v[36:37], v113, s[0:1]
	global_load_dwordx2 v[38:39], v112, s[0:1]
	s_sub_u32 s0, s0, 0x1400
	s_subb_u32 s1, s1, 0
	global_load_dwordx2 v[40:41], v113, s[0:1]
	global_load_dwordx2 v[42:43], v112, s[0:1]
	s_sub_u32 s0, s0, 0x1400
	s_subb_u32 s1, s1, 0
	global_load_dwordx2 v[44:45], v113, s[0:1]
	global_load_dwordx2 v[46:47], v112, s[0:1]
	s_sub_u32 s0, s0, 0x1400
	s_subb_u32 s1, s1, 0
	global_load_dwordx2 v[48:49], v113, s[0:1]
	global_load_dwordx2 v[50:51], v112, s[0:1]
	s_sub_u32 s0, s0, 0x1400
	s_subb_u32 s1, s1, 0
	global_load_dwordx2 v[52:53], v113, s[0:1]
	global_load_dwordx2 v[54:55], v112, s[0:1]
	s_sub_u32 s0, s0, 0x1400
	s_subb_u32 s1, s1, 0
	global_load_dwordx2 v[56:57], v113, s[0:1]
	global_load_dwordx2 v[58:59], v112, s[0:1]
	s_sub_u32 s0, s0, 0x1400
	s_subb_u32 s1, s1, 0
	global_load_dwordx2 v[60:61], v113, s[0:1]
	global_load_dwordx2 v[62:63], v112, s[0:1]
	s_sub_u32 s0, s0, 0x1400
	s_subb_u32 s1, s1, 0
	s_mov_b32 s35, 0
	s_waitcnt vmcnt(16)
; DEV u16 f2bf(float f) { return (u16)(pack2(f, f) & 0xffffu); }
; DEV float bf2f(u16 h) { return __uint_as_float(((unsigned)h) << 16); }
; DEV float sigmoid_f(float x) { return __builtin_amdgcn_rcpf(1.f + __expf(-x)); }
; DEV void phase_p15(const Params& p, int g) {
;     ...
;       for (int cc = 0; cc < 2; ++cc) {
;         const int c = tid + 256 * cc;
;         unsigned kb[8];
; #pragma unroll
;         for (int e = 0; e < 8; ++e) {
;           const int jj = j8 * 8 + e;
;           const int j = dir ? 63 - jj : jj;
;           const size_t tok = (size_t)cidx * 64 + j;
;           const float f = lb[cc] + (1.f - lb[cc]) * sigmoid_f(bf2f(xr[st][cc][e]));
;           G[cc] += __logf(f);
;           const float eg = __expf(G[cc]), ig = __expf(-G[cc]);
;           Qp[tok * 512 + c] = f2bf(bf2f(qr[st][cc][e]) * eg);
;           const u16 kk = f2bf((1.f - f) * ig);
;           Kp[tok * 512 + c] = kk;
;           kb[e] = kk;
;         }
;         const int s0 = dir ? 56 - 8 * j8 : 8 * j8;
;         uint4 w;
;         w.x = dir ? (kb[7] | (kb[6] << 16)) : (kb[0] | (kb[1] << 16));
;         w.y = dir ? (kb[5] | (kb[4] << 16)) : (kb[2] | (kb[3] << 16));
;         w.z = dir ? (kb[3] | (kb[2] << 16)) : (kb[4] | (kb[5] << 16));
;         w.w = dir ? (kb[1] | (kb[0] << 16)) : (kb[6] | (kb[7] << 16));
;         *(uint4*)(KT + (((size_t)cidx * 2 + dir) * 512 + c) * 64 + s0) = w;
.Lp15_d1_loop:
	s_waitcnt vmcnt(40)
	v_lshlrev_b32_e32 v92, 16, v0
	v_and_b32_e32 v93, 0xffff0000, v0
	v_lshlrev_b32_e32 v94, 16, v1
	v_and_b32_e32 v95, 0xffff0000, v1
	v_mul_f32_e32 v92, 0xbfb8aa3b, v92
	v_mul_f32_e32 v93, 0xbfb8aa3b, v93
	v_mul_f32_e32 v94, 0xbfb8aa3b, v94
	v_mul_f32_e32 v95, 0xbfb8aa3b, v95
	v_exp_f32_e32 v92, v92
	v_exp_f32_e32 v93, v93
	v_exp_f32_e32 v94, v94
	v_exp_f32_e32 v95, v95
	v_add_f32_e32 v92, 1.0, v92
	v_add_f32_e32 v93, 1.0, v93
	v_add_f32_e32 v94, 1.0, v94
	v_add_f32_e32 v95, 1.0, v95
	v_rcp_f32_e32 v92, v92
	v_rcp_f32_e32 v93, v93
	v_rcp_f32_e32 v94, v94
	v_rcp_f32_e32 v95, v95
	v_fma_f32 v96, v72, v92, v68
	v_fma_f32 v97, v73, v93, v69
	v_fma_f32 v98, v74, v94, v70
	v_fma_f32 v99, v75, v95, v71
	v_cmp_gt_f32_e64 s[22:23], s30, v96
	v_cmp_gt_f32_e64 s[24:25], s30, v97
	v_cmp_gt_f32_e64 s[26:27], s30, v98
	v_cmp_gt_f32_e64 s[28:29], s30, v99
	v_cndmask_b32_e64 v92, 0, 32, s[22:23]
	v_cndmask_b32_e64 v93, 0, 32, s[24:25]
	v_cndmask_b32_e64 v94, 0, 32, s[26:27]
	v_cndmask_b32_e64 v95, 0, 32, s[28:29]
	v_ldexp_f32 v92, v96, v92
	v_ldexp_f32 v93, v97, v93
	v_ldexp_f32 v94, v98, v94
	v_ldexp_f32 v95, v99, v95
	v_log_f32_e32 v92, v92
	v_log_f32_e32 v93, v93
	v_log_f32_e32 v94, v94
	v_log_f32_e32 v95, v95
	v_mul_f32_e32 v100, 0x3f317217, v92
	v_mul_f32_e32 v101, 0x3f317217, v93
	v_mul_f32_e32 v102, 0x3f317217, v94
	v_mul_f32_e32 v103, 0x3f317217, v95
	v_fma_f32 v100, v92, s31, -v100
	v_fma_f32 v101, v93, s31, -v101
	v_fma_f32 v102, v94, s31, -v102
	v_fma_f32 v103, v95, s31, -v103
	v_fmac_f32_e32 v100, 0x3377d1cf, v92
	v_fmac_f32_e32 v101, 0x3377d1cf, v93
	v_fmac_f32_e32 v102, 0x3377d1cf, v94
	v_fmac_f32_e32 v103, 0x3377d1cf, v95
	v_fmac_f32_e32 v100, 0x3f317217, v92
	v_fmac_f32_e32 v101, 0x3f317217, v93
	v_fmac_f32_e32 v102, 0x3f317217, v94
	v_fmac_f32_e32 v103, 0x3f317217, v95
	v_cmp_lt_f32_e64 vcc, |v92|, s34
	v_cndmask_b32_e32 v92, v92, v100, vcc
	v_cmp_lt_f32_e64 vcc, |v93|, s34
	v_cndmask_b32_e32 v93, v93, v101, vcc
	v_cmp_lt_f32_e64 vcc, |v94|, s34
	v_cndmask_b32_e32 v94, v94, v102, vcc
	v_cmp_lt_f32_e64 vcc, |v95|, s34
	v_cndmask_b32_e32 v95, v95, v103, vcc
	v_cndmask_b32_e64 v100, 0, v213, s[22:23]
	v_cndmask_b32_e64 v101, 0, v213, s[24:25]
	v_cndmask_b32_e64 v102, 0, v213, s[26:27]
	v_cndmask_b32_e64 v103, 0, v213, s[28:29]
	v_sub_f32_e32 v92, v92, v100
	v_sub_f32_e32 v93, v93, v101
	v_sub_f32_e32 v94, v94, v102
	v_sub_f32_e32 v95, v95, v103
	v_add_f32_e32 v64, v64, v92
	v_add_f32_e32 v65, v65, v93
	v_add_f32_e32 v66, v66, v94
	v_add_f32_e32 v67, v67, v95
	v_mul_f32_e32 v92, 0xbfb8aa3b, v64
	v_mul_f32_e32 v93, 0xbfb8aa3b, v65
	v_mul_f32_e32 v94, 0xbfb8aa3b, v66
	v_mul_f32_e32 v95, 0xbfb8aa3b, v67
	v_mul_f32_e32 v100, 0x3fb8aa3b, v64
	v_mul_f32_e32 v101, 0x3fb8aa3b, v65
	v_mul_f32_e32 v102, 0x3fb8aa3b, v66
	v_mul_f32_e32 v103, 0x3fb8aa3b, v67
	v_exp_f32_e32 v92, v92
	v_exp_f32_e32 v93, v93
	v_exp_f32_e32 v94, v94
	v_exp_f32_e32 v95, v95
	v_exp_f32_e32 v100, v100
	v_exp_f32_e32 v101, v101
	v_exp_f32_e32 v102, v102
	v_exp_f32_e32 v103, v103
	v_sub_f32_e32 v96, 1.0, v96
	v_sub_f32_e32 v97, 1.0, v97
	v_sub_f32_e32 v98, 1.0, v98
	v_sub_f32_e32 v99, 1.0, v99
	v_mul_f32_e32 v96, v96, v92
	v_mul_f32_e32 v97, v97, v93
	v_mul_f32_e32 v98, v98, v94
	v_mul_f32_e32 v99, v99, v95
	v_lshlrev_b32_e32 v92, 16, v2
	v_and_b32_e32 v93, 0xffff0000, v2
	v_lshlrev_b32_e32 v94, 16, v3
	v_and_b32_e32 v95, 0xffff0000, v3
	v_mul_f32_e32 v92, v92, v100
	v_mul_f32_e32 v93, v93, v101
	v_mul_f32_e32 v94, v94, v102
	v_mul_f32_e32 v95, v95, v103
	v_cvt_pk_bf16_f32 v108, v92, v93
	v_cvt_pk_bf16_f32 v109, v94, v95
	v_cvt_pk_bf16_f32 v110, v96, v97
	v_cvt_pk_bf16_f32 v111, v98, v99
	global_store_dwordx2 v112, v[108:109], s[2:3]
	global_store_dwordx2 v114, v[110:111], s[2:3]
	s_sub_u32 s2, s2, 0x400
	s_subb_u32 s3, s3, 0
	v_mov_b32_e32 v104, v96
	v_mov_b32_e32 v105, v97
	v_mov_b32_e32 v106, v98
	v_mov_b32_e32 v107, v99
	v_lshlrev_b32_e32 v92, 16, v4
	v_and_b32_e32 v93, 0xffff0000, v4
	v_lshlrev_b32_e32 v94, 16, v5
	v_and_b32_e32 v95, 0xffff0000, v5
	v_mul_f32_e32 v92, 0xbfb8aa3b, v92
	v_mul_f32_e32 v93, 0xbfb8aa3b, v93
	v_mul_f32_e32 v94, 0xbfb8aa3b, v94
	v_mul_f32_e32 v95, 0xbfb8aa3b, v95
	v_exp_f32_e32 v92, v92
	v_exp_f32_e32 v93, v93
	v_exp_f32_e32 v94, v94
	v_exp_f32_e32 v95, v95
	v_add_f32_e32 v92, 1.0, v92
	v_add_f32_e32 v93, 1.0, v93
	v_add_f32_e32 v94, 1.0, v94
	v_add_f32_e32 v95, 1.0, v95
	v_rcp_f32_e32 v92, v92
	v_rcp_f32_e32 v93, v93
	v_rcp_f32_e32 v94, v94
	v_rcp_f32_e32 v95, v95
	v_fma_f32 v96, v72, v92, v68
	v_fma_f32 v97, v73, v93, v69
	v_fma_f32 v98, v74, v94, v70
	v_fma_f32 v99, v75, v95, v71
	v_cmp_gt_f32_e64 s[22:23], s30, v96
	v_cmp_gt_f32_e64 s[24:25], s30, v97
	v_cmp_gt_f32_e64 s[26:27], s30, v98
	v_cmp_gt_f32_e64 s[28:29], s30, v99
	v_cndmask_b32_e64 v92, 0, 32, s[22:23]
	v_cndmask_b32_e64 v93, 0, 32, s[24:25]
	v_cndmask_b32_e64 v94, 0, 32, s[26:27]
	v_cndmask_b32_e64 v95, 0, 32, s[28:29]
	v_ldexp_f32 v92, v96, v92
	v_ldexp_f32 v93, v97, v93
	v_ldexp_f32 v94, v98, v94
	v_ldexp_f32 v95, v99, v95
	v_log_f32_e32 v92, v92
	v_log_f32_e32 v93, v93
	v_log_f32_e32 v94, v94
	v_log_f32_e32 v95, v95
	v_mul_f32_e32 v100, 0x3f317217, v92
	v_mul_f32_e32 v101, 0x3f317217, v93
	v_mul_f32_e32 v102, 0x3f317217, v94
	v_mul_f32_e32 v103, 0x3f317217, v95
	v_fma_f32 v100, v92, s31, -v100
	v_fma_f32 v101, v93, s31, -v101
	v_fma_f32 v102, v94, s31, -v102
	v_fma_f32 v103, v95, s31, -v103
	v_fmac_f32_e32 v100, 0x3377d1cf, v92
	v_fmac_f32_e32 v101, 0x3377d1cf, v93
	v_fmac_f32_e32 v102, 0x3377d1cf, v94
	v_fmac_f32_e32 v103, 0x3377d1cf, v95
	v_fmac_f32_e32 v100, 0x3f317217, v92
	v_fmac_f32_e32 v101, 0x3f317217, v93
	v_fmac_f32_e32 v102, 0x3f317217, v94
; DEV u16 f2bf(float f) { return (u16)(pack2(f, f) & 0xffffu); }
; DEV float bf2f(u16 h) { return __uint_as_float(((unsigned)h) << 16); }
; DEV float sigmoid_f(float x) { return __builtin_amdgcn_rcpf(1.f + __expf(-x)); }
; DEV void phase_p15(const Params& p, int g) {
;     ...
;       for (int cc = 0; cc < 2; ++cc) {
;         const int c = tid + 256 * cc;
;         unsigned kb[8];
; #pragma unroll
;         for (int e = 0; e < 8; ++e) {
;           const int jj = j8 * 8 + e;
;           const int j = dir ? 63 - jj : jj;
;           const size_t tok = (size_t)cidx * 64 + j;
;           const float f = lb[cc] + (1.f - lb[cc]) * sigmoid_f(bf2f(xr[st][cc][e]));
;           G[cc] += __logf(f);
;           const float eg = __expf(G[cc]), ig = __expf(-G[cc]);
;           Qp[tok * 512 + c] = f2bf(bf2f(qr[st][cc][e]) * eg);
;           const u16 kk = f2bf((1.f - f) * ig);
;           Kp[tok * 512 + c] = kk;
;           kb[e] = kk;
;         }
;         const int s0 = dir ? 56 - 8 * j8 : 8 * j8;
;         uint4 w;
;         w.x = dir ? (kb[7] | (kb[6] << 16)) : (kb[0] | (kb[1] << 16));
;         w.y = dir ? (kb[5] | (kb[4] << 16)) : (kb[2] | (kb[3] << 16));
;         w.z = dir ? (kb[3] | (kb[2] << 16)) : (kb[4] | (kb[5] << 16));
;         w.w = dir ? (kb[1] | (kb[0] << 16)) : (kb[6] | (kb[7] << 16));
;         *(uint4*)(KT + (((size_t)cidx * 2 + dir) * 512 + c) * 64 + s0) = w;
	v_fmac_f32_e32 v103, 0x3f317217, v95
	v_cmp_lt_f32_e64 vcc, |v92|, s34
	v_cndmask_b32_e32 v92, v92, v100, vcc
	v_cmp_lt_f32_e64 vcc, |v93|, s34
	v_cndmask_b32_e32 v93, v93, v101, vcc
	v_cmp_lt_f32_e64 vcc, |v94|, s34
	v_cndmask_b32_e32 v94, v94, v102, vcc
	v_cmp_lt_f32_e64 vcc, |v95|, s34
	v_cndmask_b32_e32 v95, v95, v103, vcc
	v_cndmask_b32_e64 v100, 0, v213, s[22:23]
	v_cndmask_b32_e64 v101, 0, v213, s[24:25]
	v_cndmask_b32_e64 v102, 0, v213, s[26:27]
	v_cndmask_b32_e64 v103, 0, v213, s[28:29]
	v_sub_f32_e32 v92, v92, v100
	v_sub_f32_e32 v93, v93, v101
	v_sub_f32_e32 v94, v94, v102
	v_sub_f32_e32 v95, v95, v103
	v_add_f32_e32 v64, v64, v92
	v_add_f32_e32 v65, v65, v93
	v_add_f32_e32 v66, v66, v94
	v_add_f32_e32 v67, v67, v95
	v_mul_f32_e32 v92, 0xbfb8aa3b, v64
	v_mul_f32_e32 v93, 0xbfb8aa3b, v65
	v_mul_f32_e32 v94, 0xbfb8aa3b, v66
	v_mul_f32_e32 v95, 0xbfb8aa3b, v67
	v_mul_f32_e32 v100, 0x3fb8aa3b, v64
	v_mul_f32_e32 v101, 0x3fb8aa3b, v65
	v_mul_f32_e32 v102, 0x3fb8aa3b, v66
	v_mul_f32_e32 v103, 0x3fb8aa3b, v67
	v_exp_f32_e32 v92, v92
	v_exp_f32_e32 v93, v93
	v_exp_f32_e32 v94, v94
	v_exp_f32_e32 v95, v95
	v_exp_f32_e32 v100, v100
	v_exp_f32_e32 v101, v101
	v_exp_f32_e32 v102, v102
	v_exp_f32_e32 v103, v103
	v_sub_f32_e32 v96, 1.0, v96
	v_sub_f32_e32 v97, 1.0, v97
	v_sub_f32_e32 v98, 1.0, v98
	v_sub_f32_e32 v99, 1.0, v99
	v_mul_f32_e32 v96, v96, v92
	v_mul_f32_e32 v97, v97, v93
	v_mul_f32_e32 v98, v98, v94
	v_mul_f32_e32 v99, v99, v95
	v_lshlrev_b32_e32 v92, 16, v6
	v_and_b32_e32 v93, 0xffff0000, v6
	v_lshlrev_b32_e32 v94, 16, v7
	v_and_b32_e32 v95, 0xffff0000, v7
	v_mul_f32_e32 v92, v92, v100
	v_mul_f32_e32 v93, v93, v101
	v_mul_f32_e32 v94, v94, v102
	v_mul_f32_e32 v95, v95, v103
	v_cvt_pk_bf16_f32 v108, v92, v93
	v_cvt_pk_bf16_f32 v109, v94, v95
	v_cvt_pk_bf16_f32 v110, v96, v97
	v_cvt_pk_bf16_f32 v111, v98, v99
	global_store_dwordx2 v112, v[108:109], s[2:3]
	global_store_dwordx2 v114, v[110:111], s[2:3]
	s_sub_u32 s2, s2, 0x400
	s_subb_u32 s3, s3, 0
	v_cvt_pk_bf16_f32 v123, v96, v104
	v_cvt_pk_bf16_f32 v131, v97, v105
	v_cvt_pk_bf16_f32 v139, v98, v106
	v_cvt_pk_bf16_f32 v147, v99, v107
	v_lshlrev_b32_e32 v92, 16, v8
	v_and_b32_e32 v93, 0xffff0000, v8
	v_lshlrev_b32_e32 v94, 16, v9
	v_and_b32_e32 v95, 0xffff0000, v9
	v_mul_f32_e32 v92, 0xbfb8aa3b, v92
	v_mul_f32_e32 v93, 0xbfb8aa3b, v93
	v_mul_f32_e32 v94, 0xbfb8aa3b, v94
	v_mul_f32_e32 v95, 0xbfb8aa3b, v95
	v_exp_f32_e32 v92, v92
	v_exp_f32_e32 v93, v93
	v_exp_f32_e32 v94, v94
	v_exp_f32_e32 v95, v95
	v_add_f32_e32 v92, 1.0, v92
	v_add_f32_e32 v93, 1.0, v93
	v_add_f32_e32 v94, 1.0, v94
	v_add_f32_e32 v95, 1.0, v95
	v_rcp_f32_e32 v92, v92
	v_rcp_f32_e32 v93, v93
	v_rcp_f32_e32 v94, v94
	v_rcp_f32_e32 v95, v95
	v_fma_f32 v96, v72, v92, v68
	v_fma_f32 v97, v73, v93, v69
	v_fma_f32 v98, v74, v94, v70
	v_fma_f32 v99, v75, v95, v71
	v_cmp_gt_f32_e64 s[22:23], s30, v96
	v_cmp_gt_f32_e64 s[24:25], s30, v97
	v_cmp_gt_f32_e64 s[26:27], s30, v98
	v_cmp_gt_f32_e64 s[28:29], s30, v99
	v_cndmask_b32_e64 v92, 0, 32, s[22:23]
	v_cndmask_b32_e64 v93, 0, 32, s[24:25]
	v_cndmask_b32_e64 v94, 0, 32, s[26:27]
	v_cndmask_b32_e64 v95, 0, 32, s[28:29]
	v_ldexp_f32 v92, v96, v92
	v_ldexp_f32 v93, v97, v93
	v_ldexp_f32 v94, v98, v94
	v_ldexp_f32 v95, v99, v95
	v_log_f32_e32 v92, v92
	v_log_f32_e32 v93, v93
	v_log_f32_e32 v94, v94
	v_log_f32_e32 v95, v95
	v_mul_f32_e32 v100, 0x3f317217, v92
	v_mul_f32_e32 v101, 0x3f317217, v93
	v_mul_f32_e32 v102, 0x3f317217, v94
	v_mul_f32_e32 v103, 0x3f317217, v95
	v_fma_f32 v100, v92, s31, -v100
	v_fma_f32 v101, v93, s31, -v101
	v_fma_f32 v102, v94, s31, -v102
	v_fma_f32 v103, v95, s31, -v103
	v_fmac_f32_e32 v100, 0x3377d1cf, v92
	v_fmac_f32_e32 v101, 0x3377d1cf, v93
	v_fmac_f32_e32 v102, 0x3377d1cf, v94
	v_fmac_f32_e32 v103, 0x3377d1cf, v95
	v_fmac_f32_e32 v100, 0x3f317217, v92
	v_fmac_f32_e32 v101, 0x3f317217, v93
	v_fmac_f32_e32 v102, 0x3f317217, v94
	v_fmac_f32_e32 v103, 0x3f317217, v95
	v_cmp_lt_f32_e64 vcc, |v92|, s34
	v_cndmask_b32_e32 v92, v92, v100, vcc
	v_cmp_lt_f32_e64 vcc, |v93|, s34
	v_cndmask_b32_e32 v93, v93, v101, vcc
	v_cmp_lt_f32_e64 vcc, |v94|, s34
	v_cndmask_b32_e32 v94, v94, v102, vcc
	v_cmp_lt_f32_e64 vcc, |v95|, s34
	v_cndmask_b32_e32 v95, v95, v103, vcc
	v_cndmask_b32_e64 v100, 0, v213, s[22:23]
	v_cndmask_b32_e64 v101, 0, v213, s[24:25]
	v_cndmask_b32_e64 v102, 0, v213, s[26:27]
	v_cndmask_b32_e64 v103, 0, v213, s[28:29]
	v_sub_f32_e32 v92, v92, v100
	v_sub_f32_e32 v93, v93, v101
	v_sub_f32_e32 v94, v94, v102
	v_sub_f32_e32 v95, v95, v103
	v_add_f32_e32 v64, v64, v92
	v_add_f32_e32 v65, v65, v93
	v_add_f32_e32 v66, v66, v94
	v_add_f32_e32 v67, v67, v95
	v_mul_f32_e32 v92, 0xbfb8aa3b, v64
	v_mul_f32_e32 v93, 0xbfb8aa3b, v65
	v_mul_f32_e32 v94, 0xbfb8aa3b, v66
	v_mul_f32_e32 v95, 0xbfb8aa3b, v67
	v_mul_f32_e32 v100, 0x3fb8aa3b, v64
	v_mul_f32_e32 v101, 0x3fb8aa3b, v65
	v_mul_f32_e32 v102, 0x3fb8aa3b, v66
	v_mul_f32_e32 v103, 0x3fb8aa3b, v67
	v_exp_f32_e32 v92, v92
	v_exp_f32_e32 v93, v93
	v_exp_f32_e32 v94, v94
	v_exp_f32_e32 v95, v95
	v_exp_f32_e32 v100, v100
	v_exp_f32_e32 v101, v101
	v_exp_f32_e32 v102, v102
	v_exp_f32_e32 v103, v103
	v_sub_f32_e32 v96, 1.0, v96
	v_sub_f32_e32 v97, 1.0, v97
	v_sub_f32_e32 v98, 1.0, v98
	v_sub_f32_e32 v99, 1.0, v99
	v_mul_f32_e32 v96, v96, v92
	v_mul_f32_e32 v97, v97, v93
	v_mul_f32_e32 v98, v98, v94
	v_mul_f32_e32 v99, v99, v95
	v_lshlrev_b32_e32 v92, 16, v10
	v_and_b32_e32 v93, 0xffff0000, v10
	v_lshlrev_b32_e32 v94, 16, v11
	v_and_b32_e32 v95, 0xffff0000, v11
	v_mul_f32_e32 v92, v92, v100
	v_mul_f32_e32 v93, v93, v101
	v_mul_f32_e32 v94, v94, v102
	v_mul_f32_e32 v95, v95, v103
	v_cvt_pk_bf16_f32 v108, v92, v93
; DEV u16 f2bf(float f) { return (u16)(pack2(f, f) & 0xffffu); }
; DEV float bf2f(u16 h) { return __uint_as_float(((unsigned)h) << 16); }
; DEV float sigmoid_f(float x) { return __builtin_amdgcn_rcpf(1.f + __expf(-x)); }
; DEV void phase_p15(const Params& p, int g) {
;     ...
;       for (int cc = 0; cc < 2; ++cc) {
;         const int c = tid + 256 * cc;
;         unsigned kb[8];
; #pragma unroll
;         for (int e = 0; e < 8; ++e) {
;           const int jj = j8 * 8 + e;
;           const int j = dir ? 63 - jj : jj;
;           const size_t tok = (size_t)cidx * 64 + j;
;           const float f = lb[cc] + (1.f - lb[cc]) * sigmoid_f(bf2f(xr[st][cc][e]));
;           G[cc] += __logf(f);
;           const float eg = __expf(G[cc]), ig = __expf(-G[cc]);
;           Qp[tok * 512 + c] = f2bf(bf2f(qr[st][cc][e]) * eg);
;           const u16 kk = f2bf((1.f - f) * ig);
;           Kp[tok * 512 + c] = kk;
;           kb[e] = kk;
;         }
;         const int s0 = dir ? 56 - 8 * j8 : 8 * j8;
;         uint4 w;
;         w.x = dir ? (kb[7] | (kb[6] << 16)) : (kb[0] | (kb[1] << 16));
;         w.y = dir ? (kb[5] | (kb[4] << 16)) : (kb[2] | (kb[3] << 16));
;         w.z = dir ? (kb[3] | (kb[2] << 16)) : (kb[4] | (kb[5] << 16));
;         w.w = dir ? (kb[1] | (kb[0] << 16)) : (kb[6] | (kb[7] << 16));
;         *(uint4*)(KT + (((size_t)cidx * 2 + dir) * 512 + c) * 64 + s0) = w;
	v_cvt_pk_bf16_f32 v109, v94, v95
	v_cvt_pk_bf16_f32 v110, v96, v97
	v_cvt_pk_bf16_f32 v111, v98, v99
	global_store_dwordx2 v112, v[108:109], s[2:3]
	global_store_dwordx2 v114, v[110:111], s[2:3]
	s_sub_u32 s2, s2, 0x400
	s_subb_u32 s3, s3, 0
	v_mov_b32_e32 v104, v96
	v_mov_b32_e32 v105, v97
	v_mov_b32_e32 v106, v98
	v_mov_b32_e32 v107, v99
	v_lshlrev_b32_e32 v92, 16, v12
	v_and_b32_e32 v93, 0xffff0000, v12
	v_lshlrev_b32_e32 v94, 16, v13
	v_and_b32_e32 v95, 0xffff0000, v13
	v_mul_f32_e32 v92, 0xbfb8aa3b, v92
	v_mul_f32_e32 v93, 0xbfb8aa3b, v93
	v_mul_f32_e32 v94, 0xbfb8aa3b, v94
	v_mul_f32_e32 v95, 0xbfb8aa3b, v95
	v_exp_f32_e32 v92, v92
	v_exp_f32_e32 v93, v93
	v_exp_f32_e32 v94, v94
	v_exp_f32_e32 v95, v95
	v_add_f32_e32 v92, 1.0, v92
	v_add_f32_e32 v93, 1.0, v93
	v_add_f32_e32 v94, 1.0, v94
	v_add_f32_e32 v95, 1.0, v95
	v_rcp_f32_e32 v92, v92
	v_rcp_f32_e32 v93, v93
	v_rcp_f32_e32 v94, v94
	v_rcp_f32_e32 v95, v95
	v_fma_f32 v96, v72, v92, v68
	v_fma_f32 v97, v73, v93, v69
	v_fma_f32 v98, v74, v94, v70
	v_fma_f32 v99, v75, v95, v71
	v_cmp_gt_f32_e64 s[22:23], s30, v96
	v_cmp_gt_f32_e64 s[24:25], s30, v97
	v_cmp_gt_f32_e64 s[26:27], s30, v98
	v_cmp_gt_f32_e64 s[28:29], s30, v99
	v_cndmask_b32_e64 v92, 0, 32, s[22:23]
	v_cndmask_b32_e64 v93, 0, 32, s[24:25]
	v_cndmask_b32_e64 v94, 0, 32, s[26:27]
	v_cndmask_b32_e64 v95, 0, 32, s[28:29]
	v_ldexp_f32 v92, v96, v92
	v_ldexp_f32 v93, v97, v93
	v_ldexp_f32 v94, v98, v94
	v_ldexp_f32 v95, v99, v95
	v_log_f32_e32 v92, v92
	v_log_f32_e32 v93, v93
	v_log_f32_e32 v94, v94
	v_log_f32_e32 v95, v95
	v_mul_f32_e32 v100, 0x3f317217, v92
	v_mul_f32_e32 v101, 0x3f317217, v93
	v_mul_f32_e32 v102, 0x3f317217, v94
	v_mul_f32_e32 v103, 0x3f317217, v95
	v_fma_f32 v100, v92, s31, -v100
	v_fma_f32 v101, v93, s31, -v101
	v_fma_f32 v102, v94, s31, -v102
	v_fma_f32 v103, v95, s31, -v103
	v_fmac_f32_e32 v100, 0x3377d1cf, v92
	v_fmac_f32_e32 v101, 0x3377d1cf, v93
	v_fmac_f32_e32 v102, 0x3377d1cf, v94
	v_fmac_f32_e32 v103, 0x3377d1cf, v95
	v_fmac_f32_e32 v100, 0x3f317217, v92
	v_fmac_f32_e32 v101, 0x3f317217, v93
	v_fmac_f32_e32 v102, 0x3f317217, v94
	v_fmac_f32_e32 v103, 0x3f317217, v95
	v_cmp_lt_f32_e64 vcc, |v92|, s34
	v_cndmask_b32_e32 v92, v92, v100, vcc
	v_cmp_lt_f32_e64 vcc, |v93|, s34
	v_cndmask_b32_e32 v93, v93, v101, vcc
	v_cmp_lt_f32_e64 vcc, |v94|, s34
	v_cndmask_b32_e32 v94, v94, v102, vcc
	v_cmp_lt_f32_e64 vcc, |v95|, s34
	v_cndmask_b32_e32 v95, v95, v103, vcc
	v_cndmask_b32_e64 v100, 0, v213, s[22:23]
	v_cndmask_b32_e64 v101, 0, v213, s[24:25]
	v_cndmask_b32_e64 v102, 0, v213, s[26:27]
	v_cndmask_b32_e64 v103, 0, v213, s[28:29]
	v_sub_f32_e32 v92, v92, v100
	v_sub_f32_e32 v93, v93, v101
	v_sub_f32_e32 v94, v94, v102
	v_sub_f32_e32 v95, v95, v103
	v_add_f32_e32 v64, v64, v92
	v_add_f32_e32 v65, v65, v93
	v_add_f32_e32 v66, v66, v94
	v_add_f32_e32 v67, v67, v95
	v_mul_f32_e32 v92, 0xbfb8aa3b, v64
	v_mul_f32_e32 v93, 0xbfb8aa3b, v65
	v_mul_f32_e32 v94, 0xbfb8aa3b, v66
	v_mul_f32_e32 v95, 0xbfb8aa3b, v67
	v_mul_f32_e32 v100, 0x3fb8aa3b, v64
	v_mul_f32_e32 v101, 0x3fb8aa3b, v65
	v_mul_f32_e32 v102, 0x3fb8aa3b, v66
	v_mul_f32_e32 v103, 0x3fb8aa3b, v67
	v_exp_f32_e32 v92, v92
	v_exp_f32_e32 v93, v93
	v_exp_f32_e32 v94, v94
	v_exp_f32_e32 v95, v95
	v_exp_f32_e32 v100, v100
	v_exp_f32_e32 v101, v101
	v_exp_f32_e32 v102, v102
	v_exp_f32_e32 v103, v103
	v_sub_f32_e32 v96, 1.0, v96
	v_sub_f32_e32 v97, 1.0, v97
	v_sub_f32_e32 v98, 1.0, v98
	v_sub_f32_e32 v99, 1.0, v99
	v_mul_f32_e32 v96, v96, v92
	v_mul_f32_e32 v97, v97, v93
	v_mul_f32_e32 v98, v98, v94
	v_mul_f32_e32 v99, v99, v95
	v_lshlrev_b32_e32 v92, 16, v14
	v_and_b32_e32 v93, 0xffff0000, v14
	v_lshlrev_b32_e32 v94, 16, v15
	v_and_b32_e32 v95, 0xffff0000, v15
	v_mul_f32_e32 v92, v92, v100
	v_mul_f32_e32 v93, v93, v101
	v_mul_f32_e32 v94, v94, v102
	v_mul_f32_e32 v95, v95, v103
	v_cvt_pk_bf16_f32 v108, v92, v93
	v_cvt_pk_bf16_f32 v109, v94, v95
	v_cvt_pk_bf16_f32 v110, v96, v97
	v_cvt_pk_bf16_f32 v111, v98, v99
	global_store_dwordx2 v112, v[108:109], s[2:3]
	global_store_dwordx2 v114, v[110:111], s[2:3]
	s_sub_u32 s2, s2, 0x400
	s_subb_u32 s3, s3, 0
	v_cvt_pk_bf16_f32 v122, v96, v104
	v_cvt_pk_bf16_f32 v130, v97, v105
	v_cvt_pk_bf16_f32 v138, v98, v106
	v_cvt_pk_bf16_f32 v146, v99, v107
	v_lshlrev_b32_e32 v92, 16, v16
	v_and_b32_e32 v93, 0xffff0000, v16
	v_lshlrev_b32_e32 v94, 16, v17
	v_and_b32_e32 v95, 0xffff0000, v17
	v_mul_f32_e32 v92, 0xbfb8aa3b, v92
	v_mul_f32_e32 v93, 0xbfb8aa3b, v93
	v_mul_f32_e32 v94, 0xbfb8aa3b, v94
	v_mul_f32_e32 v95, 0xbfb8aa3b, v95
	v_exp_f32_e32 v92, v92
	v_exp_f32_e32 v93, v93
	v_exp_f32_e32 v94, v94
	v_exp_f32_e32 v95, v95
	v_add_f32_e32 v92, 1.0, v92
	v_add_f32_e32 v93, 1.0, v93
	v_add_f32_e32 v94, 1.0, v94
	v_add_f32_e32 v95, 1.0, v95
	v_rcp_f32_e32 v92, v92
	v_rcp_f32_e32 v93, v93
	v_rcp_f32_e32 v94, v94
	v_rcp_f32_e32 v95, v95
	v_fma_f32 v96, v72, v92, v68
	v_fma_f32 v97, v73, v93, v69
	v_fma_f32 v98, v74, v94, v70
	v_fma_f32 v99, v75, v95, v71
	v_cmp_gt_f32_e64 s[22:23], s30, v96
	v_cmp_gt_f32_e64 s[24:25], s30, v97
	v_cmp_gt_f32_e64 s[26:27], s30, v98
	v_cmp_gt_f32_e64 s[28:29], s30, v99
	v_cndmask_b32_e64 v92, 0, 32, s[22:23]
	v_cndmask_b32_e64 v93, 0, 32, s[24:25]
	v_cndmask_b32_e64 v94, 0, 32, s[26:27]
	v_cndmask_b32_e64 v95, 0, 32, s[28:29]
	v_ldexp_f32 v92, v96, v92
	v_ldexp_f32 v93, v97, v93
	v_ldexp_f32 v94, v98, v94
	v_ldexp_f32 v95, v99, v95
	v_log_f32_e32 v92, v92
	v_log_f32_e32 v93, v93
	v_log_f32_e32 v94, v94
	v_log_f32_e32 v95, v95
	v_mul_f32_e32 v100, 0x3f317217, v92
	v_mul_f32_e32 v101, 0x3f317217, v93
	v_mul_f32_e32 v102, 0x3f317217, v94
	v_mul_f32_e32 v103, 0x3f317217, v95
	v_fma_f32 v100, v92, s31, -v100
; DEV u16 f2bf(float f) { return (u16)(pack2(f, f) & 0xffffu); }
; DEV float bf2f(u16 h) { return __uint_as_float(((unsigned)h) << 16); }
; DEV float sigmoid_f(float x) { return __builtin_amdgcn_rcpf(1.f + __expf(-x)); }
; DEV void phase_p15(const Params& p, int g) {
;     ...
;         for (int e = 0; e < 8; ++e) {
;           const int jj = j8 * 8 + e;
;           const int j = dir ? 63 - jj : jj;
;           const size_t tok = (size_t)cidx * 64 + j;
;           const float f = lb[cc] + (1.f - lb[cc]) * sigmoid_f(bf2f(xr[st][cc][e]));
;           G[cc] += __logf(f);
;           const float eg = __expf(G[cc]), ig = __expf(-G[cc]);
;           Qp[tok * 512 + c] = f2bf(bf2f(qr[st][cc][e]) * eg);
;           const u16 kk = f2bf((1.f - f) * ig);
;           Kp[tok * 512 + c] = kk;
;           kb[e] = kk;
;         }
;     ...
;         w.x = dir ? (kb[7] | (kb[6] << 16)) : (kb[0] | (kb[1] << 16));
;         w.y = dir ? (kb[5] | (kb[4] << 16)) : (kb[2] | (kb[3] << 16));
;         w.z = dir ? (kb[3] | (kb[2] << 16)) : (kb[4] | (kb[5] << 16));
;         w.w = dir ? (kb[1] | (kb[0] << 16)) : (kb[6] | (kb[7] << 16));
	v_fma_f32 v101, v93, s31, -v101
	v_fma_f32 v102, v94, s31, -v102
	v_fma_f32 v103, v95, s31, -v103
	v_fmac_f32_e32 v100, 0x3377d1cf, v92
	v_fmac_f32_e32 v101, 0x3377d1cf, v93
	v_fmac_f32_e32 v102, 0x3377d1cf, v94
	v_fmac_f32_e32 v103, 0x3377d1cf, v95
	v_fmac_f32_e32 v100, 0x3f317217, v92
	v_fmac_f32_e32 v101, 0x3f317217, v93
	v_fmac_f32_e32 v102, 0x3f317217, v94
	v_fmac_f32_e32 v103, 0x3f317217, v95
	v_cmp_lt_f32_e64 vcc, |v92|, s34
	v_cndmask_b32_e32 v92, v92, v100, vcc
	v_cmp_lt_f32_e64 vcc, |v93|, s34
	v_cndmask_b32_e32 v93, v93, v101, vcc
	v_cmp_lt_f32_e64 vcc, |v94|, s34
	v_cndmask_b32_e32 v94, v94, v102, vcc
	v_cmp_lt_f32_e64 vcc, |v95|, s34
	v_cndmask_b32_e32 v95, v95, v103, vcc
	v_cndmask_b32_e64 v100, 0, v213, s[22:23]
	v_cndmask_b32_e64 v101, 0, v213, s[24:25]
	v_cndmask_b32_e64 v102, 0, v213, s[26:27]
	v_cndmask_b32_e64 v103, 0, v213, s[28:29]
	v_sub_f32_e32 v92, v92, v100
	v_sub_f32_e32 v93, v93, v101
	v_sub_f32_e32 v94, v94, v102
	v_sub_f32_e32 v95, v95, v103
	v_add_f32_e32 v64, v64, v92
	v_add_f32_e32 v65, v65, v93
	v_add_f32_e32 v66, v66, v94
	v_add_f32_e32 v67, v67, v95
	v_mul_f32_e32 v92, 0xbfb8aa3b, v64
	v_mul_f32_e32 v93, 0xbfb8aa3b, v65
	v_mul_f32_e32 v94, 0xbfb8aa3b, v66
	v_mul_f32_e32 v95, 0xbfb8aa3b, v67
	v_mul_f32_e32 v100, 0x3fb8aa3b, v64
	v_mul_f32_e32 v101, 0x3fb8aa3b, v65
	v_mul_f32_e32 v102, 0x3fb8aa3b, v66
	v_mul_f32_e32 v103, 0x3fb8aa3b, v67
	v_exp_f32_e32 v92, v92
	v_exp_f32_e32 v93, v93
	v_exp_f32_e32 v94, v94
	v_exp_f32_e32 v95, v95
	v_exp_f32_e32 v100, v100
	v_exp_f32_e32 v101, v101
	v_exp_f32_e32 v102, v102
	v_exp_f32_e32 v103, v103
	v_sub_f32_e32 v96, 1.0, v96
	v_sub_f32_e32 v97, 1.0, v97
	v_sub_f32_e32 v98, 1.0, v98
	v_sub_f32_e32 v99, 1.0, v99
	v_mul_f32_e32 v96, v96, v92
	v_mul_f32_e32 v97, v97, v93
	v_mul_f32_e32 v98, v98, v94
	v_mul_f32_e32 v99, v99, v95
	v_lshlrev_b32_e32 v92, 16, v18
	v_and_b32_e32 v93, 0xffff0000, v18
	v_lshlrev_b32_e32 v94, 16, v19
	v_and_b32_e32 v95, 0xffff0000, v19
	v_mul_f32_e32 v92, v92, v100
	v_mul_f32_e32 v93, v93, v101
	v_mul_f32_e32 v94, v94, v102
	v_mul_f32_e32 v95, v95, v103
	v_cvt_pk_bf16_f32 v108, v92, v93
	v_cvt_pk_bf16_f32 v109, v94, v95
	v_cvt_pk_bf16_f32 v110, v96, v97
	v_cvt_pk_bf16_f32 v111, v98, v99
	global_store_dwordx2 v112, v[108:109], s[2:3]
	global_store_dwordx2 v114, v[110:111], s[2:3]
	s_sub_u32 s2, s2, 0x400
	s_subb_u32 s3, s3, 0
	v_mov_b32_e32 v104, v96
	v_mov_b32_e32 v105, v97
	v_mov_b32_e32 v106, v98
	v_mov_b32_e32 v107, v99
	v_lshlrev_b32_e32 v92, 16, v20
	v_and_b32_e32 v93, 0xffff0000, v20
	v_lshlrev_b32_e32 v94, 16, v21
	v_and_b32_e32 v95, 0xffff0000, v21
	v_mul_f32_e32 v92, 0xbfb8aa3b, v92
	v_mul_f32_e32 v93, 0xbfb8aa3b, v93
	v_mul_f32_e32 v94, 0xbfb8aa3b, v94
	v_mul_f32_e32 v95, 0xbfb8aa3b, v95
	v_exp_f32_e32 v92, v92
	v_exp_f32_e32 v93, v93
	v_exp_f32_e32 v94, v94
	v_exp_f32_e32 v95, v95
	v_add_f32_e32 v92, 1.0, v92
	v_add_f32_e32 v93, 1.0, v93
	v_add_f32_e32 v94, 1.0, v94
	v_add_f32_e32 v95, 1.0, v95
	v_rcp_f32_e32 v92, v92
	v_rcp_f32_e32 v93, v93
	v_rcp_f32_e32 v94, v94
	v_rcp_f32_e32 v95, v95
	v_fma_f32 v96, v72, v92, v68
	v_fma_f32 v97, v73, v93, v69
	v_fma_f32 v98, v74, v94, v70
	v_fma_f32 v99, v75, v95, v71
	v_cmp_gt_f32_e64 s[22:23], s30, v96
	v_cmp_gt_f32_e64 s[24:25], s30, v97
	v_cmp_gt_f32_e64 s[26:27], s30, v98
	v_cmp_gt_f32_e64 s[28:29], s30, v99
	v_cndmask_b32_e64 v92, 0, 32, s[22:23]
	v_cndmask_b32_e64 v93, 0, 32, s[24:25]
	v_cndmask_b32_e64 v94, 0, 32, s[26:27]
	v_cndmask_b32_e64 v95, 0, 32, s[28:29]
	v_ldexp_f32 v92, v96, v92
	v_ldexp_f32 v93, v97, v93
	v_ldexp_f32 v94, v98, v94
	v_ldexp_f32 v95, v99, v95
	v_log_f32_e32 v92, v92
	v_log_f32_e32 v93, v93
	v_log_f32_e32 v94, v94
	v_log_f32_e32 v95, v95
	v_mul_f32_e32 v100, 0x3f317217, v92
	v_mul_f32_e32 v101, 0x3f317217, v93
	v_mul_f32_e32 v102, 0x3f317217, v94
	v_mul_f32_e32 v103, 0x3f317217, v95
	v_fma_f32 v100, v92, s31, -v100
	v_fma_f32 v101, v93, s31, -v101
	v_fma_f32 v102, v94, s31, -v102
	v_fma_f32 v103, v95, s31, -v103
	v_fmac_f32_e32 v100, 0x3377d1cf, v92
	v_fmac_f32_e32 v101, 0x3377d1cf, v93
	v_fmac_f32_e32 v102, 0x3377d1cf, v94
	v_fmac_f32_e32 v103, 0x3377d1cf, v95
	v_fmac_f32_e32 v100, 0x3f317217, v92
	v_fmac_f32_e32 v101, 0x3f317217, v93
	v_fmac_f32_e32 v102, 0x3f317217, v94
	v_fmac_f32_e32 v103, 0x3f317217, v95
	v_cmp_lt_f32_e64 vcc, |v92|, s34
	v_cndmask_b32_e32 v92, v92, v100, vcc
	v_cmp_lt_f32_e64 vcc, |v93|, s34
	v_cndmask_b32_e32 v93, v93, v101, vcc
	v_cmp_lt_f32_e64 vcc, |v94|, s34
	v_cndmask_b32_e32 v94, v94, v102, vcc
	v_cmp_lt_f32_e64 vcc, |v95|, s34
	v_cndmask_b32_e32 v95, v95, v103, vcc
	v_cndmask_b32_e64 v100, 0, v213, s[22:23]
	v_cndmask_b32_e64 v101, 0, v213, s[24:25]
	v_cndmask_b32_e64 v102, 0, v213, s[26:27]
	v_cndmask_b32_e64 v103, 0, v213, s[28:29]
	v_sub_f32_e32 v92, v92, v100
	v_sub_f32_e32 v93, v93, v101
	v_sub_f32_e32 v94, v94, v102
	v_sub_f32_e32 v95, v95, v103
	v_add_f32_e32 v64, v64, v92
	v_add_f32_e32 v65, v65, v93
	v_add_f32_e32 v66, v66, v94
	v_add_f32_e32 v67, v67, v95
	v_mul_f32_e32 v92, 0xbfb8aa3b, v64
	v_mul_f32_e32 v93, 0xbfb8aa3b, v65
	v_mul_f32_e32 v94, 0xbfb8aa3b, v66
	v_mul_f32_e32 v95, 0xbfb8aa3b, v67
	v_mul_f32_e32 v100, 0x3fb8aa3b, v64
	v_mul_f32_e32 v101, 0x3fb8aa3b, v65
	v_mul_f32_e32 v102, 0x3fb8aa3b, v66
	v_mul_f32_e32 v103, 0x3fb8aa3b, v67
	v_exp_f32_e32 v92, v92
	v_exp_f32_e32 v93, v93
	v_exp_f32_e32 v94, v94
	v_exp_f32_e32 v95, v95
	v_exp_f32_e32 v100, v100
	v_exp_f32_e32 v101, v101
	v_exp_f32_e32 v102, v102
	v_exp_f32_e32 v103, v103
	v_sub_f32_e32 v96, 1.0, v96
	v_sub_f32_e32 v97, 1.0, v97
	v_sub_f32_e32 v98, 1.0, v98
	v_sub_f32_e32 v99, 1.0, v99
	v_mul_f32_e32 v96, v96, v92
	v_mul_f32_e32 v97, v97, v93
; DEV u16 f2bf(float f) { return (u16)(pack2(f, f) & 0xffffu); }
; DEV float bf2f(u16 h) { return __uint_as_float(((unsigned)h) << 16); }
; DEV float sigmoid_f(float x) { return __builtin_amdgcn_rcpf(1.f + __expf(-x)); }
; DEV void phase_p15(const Params& p, int g) {
;     ...
;         for (int e = 0; e < 8; ++e) {
;           const int jj = j8 * 8 + e;
;           const int j = dir ? 63 - jj : jj;
;           const size_t tok = (size_t)cidx * 64 + j;
;           const float f = lb[cc] + (1.f - lb[cc]) * sigmoid_f(bf2f(xr[st][cc][e]));
;           G[cc] += __logf(f);
;           const float eg = __expf(G[cc]), ig = __expf(-G[cc]);
;           Qp[tok * 512 + c] = f2bf(bf2f(qr[st][cc][e]) * eg);
;           const u16 kk = f2bf((1.f - f) * ig);
;           Kp[tok * 512 + c] = kk;
;           kb[e] = kk;
;         }
;     ...
;         w.x = dir ? (kb[7] | (kb[6] << 16)) : (kb[0] | (kb[1] << 16));
;         w.y = dir ? (kb[5] | (kb[4] << 16)) : (kb[2] | (kb[3] << 16));
;         w.z = dir ? (kb[3] | (kb[2] << 16)) : (kb[4] | (kb[5] << 16));
;         w.w = dir ? (kb[1] | (kb[0] << 16)) : (kb[6] | (kb[7] << 16));
	v_mul_f32_e32 v98, v98, v94
	v_mul_f32_e32 v99, v99, v95
	v_lshlrev_b32_e32 v92, 16, v22
	v_and_b32_e32 v93, 0xffff0000, v22
	v_lshlrev_b32_e32 v94, 16, v23
	v_and_b32_e32 v95, 0xffff0000, v23
	v_mul_f32_e32 v92, v92, v100
	v_mul_f32_e32 v93, v93, v101
	v_mul_f32_e32 v94, v94, v102
	v_mul_f32_e32 v95, v95, v103
	v_cvt_pk_bf16_f32 v108, v92, v93
	v_cvt_pk_bf16_f32 v109, v94, v95
	v_cvt_pk_bf16_f32 v110, v96, v97
	v_cvt_pk_bf16_f32 v111, v98, v99
	global_store_dwordx2 v112, v[108:109], s[2:3]
	global_store_dwordx2 v114, v[110:111], s[2:3]
	s_sub_u32 s2, s2, 0x400
	s_subb_u32 s3, s3, 0
	v_cvt_pk_bf16_f32 v121, v96, v104
	v_cvt_pk_bf16_f32 v129, v97, v105
	v_cvt_pk_bf16_f32 v137, v98, v106
	v_cvt_pk_bf16_f32 v145, v99, v107
	v_lshlrev_b32_e32 v92, 16, v24
	v_and_b32_e32 v93, 0xffff0000, v24
	v_lshlrev_b32_e32 v94, 16, v25
	v_and_b32_e32 v95, 0xffff0000, v25
	v_mul_f32_e32 v92, 0xbfb8aa3b, v92
	v_mul_f32_e32 v93, 0xbfb8aa3b, v93
	v_mul_f32_e32 v94, 0xbfb8aa3b, v94
	v_mul_f32_e32 v95, 0xbfb8aa3b, v95
	v_exp_f32_e32 v92, v92
	v_exp_f32_e32 v93, v93
	v_exp_f32_e32 v94, v94
	v_exp_f32_e32 v95, v95
	v_add_f32_e32 v92, 1.0, v92
	v_add_f32_e32 v93, 1.0, v93
	v_add_f32_e32 v94, 1.0, v94
	v_add_f32_e32 v95, 1.0, v95
	v_rcp_f32_e32 v92, v92
	v_rcp_f32_e32 v93, v93
	v_rcp_f32_e32 v94, v94
	v_rcp_f32_e32 v95, v95
	v_fma_f32 v96, v72, v92, v68
	v_fma_f32 v97, v73, v93, v69
	v_fma_f32 v98, v74, v94, v70
	v_fma_f32 v99, v75, v95, v71
	v_cmp_gt_f32_e64 s[22:23], s30, v96
	v_cmp_gt_f32_e64 s[24:25], s30, v97
	v_cmp_gt_f32_e64 s[26:27], s30, v98
	v_cmp_gt_f32_e64 s[28:29], s30, v99
	v_cndmask_b32_e64 v92, 0, 32, s[22:23]
	v_cndmask_b32_e64 v93, 0, 32, s[24:25]
	v_cndmask_b32_e64 v94, 0, 32, s[26:27]
	v_cndmask_b32_e64 v95, 0, 32, s[28:29]
	v_ldexp_f32 v92, v96, v92
	v_ldexp_f32 v93, v97, v93
	v_ldexp_f32 v94, v98, v94
	v_ldexp_f32 v95, v99, v95
	v_log_f32_e32 v92, v92
	v_log_f32_e32 v93, v93
	v_log_f32_e32 v94, v94
	v_log_f32_e32 v95, v95
	v_mul_f32_e32 v100, 0x3f317217, v92
	v_mul_f32_e32 v101, 0x3f317217, v93
	v_mul_f32_e32 v102, 0x3f317217, v94
	v_mul_f32_e32 v103, 0x3f317217, v95
	v_fma_f32 v100, v92, s31, -v100
	v_fma_f32 v101, v93, s31, -v101
	v_fma_f32 v102, v94, s31, -v102
	v_fma_f32 v103, v95, s31, -v103
	v_fmac_f32_e32 v100, 0x3377d1cf, v92
	v_fmac_f32_e32 v101, 0x3377d1cf, v93
	v_fmac_f32_e32 v102, 0x3377d1cf, v94
	v_fmac_f32_e32 v103, 0x3377d1cf, v95
	v_fmac_f32_e32 v100, 0x3f317217, v92
	v_fmac_f32_e32 v101, 0x3f317217, v93
	v_fmac_f32_e32 v102, 0x3f317217, v94
	v_fmac_f32_e32 v103, 0x3f317217, v95
	v_cmp_lt_f32_e64 vcc, |v92|, s34
	v_cndmask_b32_e32 v92, v92, v100, vcc
	v_cmp_lt_f32_e64 vcc, |v93|, s34
	v_cndmask_b32_e32 v93, v93, v101, vcc
	v_cmp_lt_f32_e64 vcc, |v94|, s34
	v_cndmask_b32_e32 v94, v94, v102, vcc
	v_cmp_lt_f32_e64 vcc, |v95|, s34
	v_cndmask_b32_e32 v95, v95, v103, vcc
	v_cndmask_b32_e64 v100, 0, v213, s[22:23]
	v_cndmask_b32_e64 v101, 0, v213, s[24:25]
	v_cndmask_b32_e64 v102, 0, v213, s[26:27]
	v_cndmask_b32_e64 v103, 0, v213, s[28:29]
	v_sub_f32_e32 v92, v92, v100
	v_sub_f32_e32 v93, v93, v101
	v_sub_f32_e32 v94, v94, v102
	v_sub_f32_e32 v95, v95, v103
	v_add_f32_e32 v64, v64, v92
	v_add_f32_e32 v65, v65, v93
	v_add_f32_e32 v66, v66, v94
	v_add_f32_e32 v67, v67, v95
	v_mul_f32_e32 v92, 0xbfb8aa3b, v64
	v_mul_f32_e32 v93, 0xbfb8aa3b, v65
	v_mul_f32_e32 v94, 0xbfb8aa3b, v66
	v_mul_f32_e32 v95, 0xbfb8aa3b, v67
	v_mul_f32_e32 v100, 0x3fb8aa3b, v64
	v_mul_f32_e32 v101, 0x3fb8aa3b, v65
	v_mul_f32_e32 v102, 0x3fb8aa3b, v66
	v_mul_f32_e32 v103, 0x3fb8aa3b, v67
	v_exp_f32_e32 v92, v92
	v_exp_f32_e32 v93, v93
	v_exp_f32_e32 v94, v94
	v_exp_f32_e32 v95, v95
	v_exp_f32_e32 v100, v100
	v_exp_f32_e32 v101, v101
	v_exp_f32_e32 v102, v102
	v_exp_f32_e32 v103, v103
	v_sub_f32_e32 v96, 1.0, v96
	v_sub_f32_e32 v97, 1.0, v97
	v_sub_f32_e32 v98, 1.0, v98
	v_sub_f32_e32 v99, 1.0, v99
	v_mul_f32_e32 v96, v96, v92
	v_mul_f32_e32 v97, v97, v93
	v_mul_f32_e32 v98, v98, v94
	v_mul_f32_e32 v99, v99, v95
	v_lshlrev_b32_e32 v92, 16, v26
	v_and_b32_e32 v93, 0xffff0000, v26
	v_lshlrev_b32_e32 v94, 16, v27
	v_and_b32_e32 v95, 0xffff0000, v27
	v_mul_f32_e32 v92, v92, v100
	v_mul_f32_e32 v93, v93, v101
	v_mul_f32_e32 v94, v94, v102
	v_mul_f32_e32 v95, v95, v103
	v_cvt_pk_bf16_f32 v108, v92, v93
	v_cvt_pk_bf16_f32 v109, v94, v95
	v_cvt_pk_bf16_f32 v110, v96, v97
	v_cvt_pk_bf16_f32 v111, v98, v99
	global_store_dwordx2 v112, v[108:109], s[2:3]
	global_store_dwordx2 v114, v[110:111], s[2:3]
	s_sub_u32 s2, s2, 0x400
	s_subb_u32 s3, s3, 0
	v_mov_b32_e32 v104, v96
	v_mov_b32_e32 v105, v97
	v_mov_b32_e32 v106, v98
	v_mov_b32_e32 v107, v99
	v_lshlrev_b32_e32 v92, 16, v28
	v_and_b32_e32 v93, 0xffff0000, v28
	v_lshlrev_b32_e32 v94, 16, v29
	v_and_b32_e32 v95, 0xffff0000, v29
	v_mul_f32_e32 v92, 0xbfb8aa3b, v92
	v_mul_f32_e32 v93, 0xbfb8aa3b, v93
	v_mul_f32_e32 v94, 0xbfb8aa3b, v94
	v_mul_f32_e32 v95, 0xbfb8aa3b, v95
	v_exp_f32_e32 v92, v92
	v_exp_f32_e32 v93, v93
	v_exp_f32_e32 v94, v94
	v_exp_f32_e32 v95, v95
	v_add_f32_e32 v92, 1.0, v92
	v_add_f32_e32 v93, 1.0, v93
	v_add_f32_e32 v94, 1.0, v94
	v_add_f32_e32 v95, 1.0, v95
	v_rcp_f32_e32 v92, v92
	v_rcp_f32_e32 v93, v93
	v_rcp_f32_e32 v94, v94
	v_rcp_f32_e32 v95, v95
	v_fma_f32 v96, v72, v92, v68
	v_fma_f32 v97, v73, v93, v69
	v_fma_f32 v98, v74, v94, v70
	v_fma_f32 v99, v75, v95, v71
	v_cmp_gt_f32_e64 s[22:23], s30, v96
	v_cmp_gt_f32_e64 s[24:25], s30, v97
	v_cmp_gt_f32_e64 s[26:27], s30, v98
	v_cmp_gt_f32_e64 s[28:29], s30, v99
	v_cndmask_b32_e64 v92, 0, 32, s[22:23]
	v_cndmask_b32_e64 v93, 0, 32, s[24:25]
	v_cndmask_b32_e64 v94, 0, 32, s[26:27]
	v_cndmask_b32_e64 v95, 0, 32, s[28:29]
	v_ldexp_f32 v92, v96, v92
; DEV u16 f2bf(float f) { return (u16)(pack2(f, f) & 0xffffu); }
; DEV float bf2f(u16 h) { return __uint_as_float(((unsigned)h) << 16); }
; DEV float sigmoid_f(float x) { return __builtin_amdgcn_rcpf(1.f + __expf(-x)); }
; DEV void phase_p15(const Params& p, int g) {
;     ...
;       if (j8 < 6) { P15_LOAD((j8 + 2) % 3, j8 + 2); }
; #pragma unroll
;       for (int cc = 0; cc < 2; ++cc) {
;         const int c = tid + 256 * cc;
;         unsigned kb[8];
; #pragma unroll
;         for (int e = 0; e < 8; ++e) {
;           const int jj = j8 * 8 + e;
;           const int j = dir ? 63 - jj : jj;
;           const size_t tok = (size_t)cidx * 64 + j;
;           const float f = lb[cc] + (1.f - lb[cc]) * sigmoid_f(bf2f(xr[st][cc][e]));
;           G[cc] += __logf(f);
;           const float eg = __expf(G[cc]), ig = __expf(-G[cc]);
;           Qp[tok * 512 + c] = f2bf(bf2f(qr[st][cc][e]) * eg);
;           const u16 kk = f2bf((1.f - f) * ig);
;           Kp[tok * 512 + c] = kk;
;           kb[e] = kk;
;         }
;     ...
;         w.x = dir ? (kb[7] | (kb[6] << 16)) : (kb[0] | (kb[1] << 16));
;         w.y = dir ? (kb[5] | (kb[4] << 16)) : (kb[2] | (kb[3] << 16));
;         w.z = dir ? (kb[3] | (kb[2] << 16)) : (kb[4] | (kb[5] << 16));
;         w.w = dir ? (kb[1] | (kb[0] << 16)) : (kb[6] | (kb[7] << 16));
	v_ldexp_f32 v93, v97, v93
	v_ldexp_f32 v94, v98, v94
	v_ldexp_f32 v95, v99, v95
	v_log_f32_e32 v92, v92
	v_log_f32_e32 v93, v93
	v_log_f32_e32 v94, v94
	v_log_f32_e32 v95, v95
	v_mul_f32_e32 v100, 0x3f317217, v92
	v_mul_f32_e32 v101, 0x3f317217, v93
	v_mul_f32_e32 v102, 0x3f317217, v94
	v_mul_f32_e32 v103, 0x3f317217, v95
	v_fma_f32 v100, v92, s31, -v100
	v_fma_f32 v101, v93, s31, -v101
	v_fma_f32 v102, v94, s31, -v102
	v_fma_f32 v103, v95, s31, -v103
	v_fmac_f32_e32 v100, 0x3377d1cf, v92
	v_fmac_f32_e32 v101, 0x3377d1cf, v93
	v_fmac_f32_e32 v102, 0x3377d1cf, v94
	v_fmac_f32_e32 v103, 0x3377d1cf, v95
	v_fmac_f32_e32 v100, 0x3f317217, v92
	v_fmac_f32_e32 v101, 0x3f317217, v93
	v_fmac_f32_e32 v102, 0x3f317217, v94
	v_fmac_f32_e32 v103, 0x3f317217, v95
	v_cmp_lt_f32_e64 vcc, |v92|, s34
	v_cndmask_b32_e32 v92, v92, v100, vcc
	v_cmp_lt_f32_e64 vcc, |v93|, s34
	v_cndmask_b32_e32 v93, v93, v101, vcc
	v_cmp_lt_f32_e64 vcc, |v94|, s34
	v_cndmask_b32_e32 v94, v94, v102, vcc
	v_cmp_lt_f32_e64 vcc, |v95|, s34
	v_cndmask_b32_e32 v95, v95, v103, vcc
	v_cndmask_b32_e64 v100, 0, v213, s[22:23]
	v_cndmask_b32_e64 v101, 0, v213, s[24:25]
	v_cndmask_b32_e64 v102, 0, v213, s[26:27]
	v_cndmask_b32_e64 v103, 0, v213, s[28:29]
	v_sub_f32_e32 v92, v92, v100
	v_sub_f32_e32 v93, v93, v101
	v_sub_f32_e32 v94, v94, v102
	v_sub_f32_e32 v95, v95, v103
	v_add_f32_e32 v64, v64, v92
	v_add_f32_e32 v65, v65, v93
	v_add_f32_e32 v66, v66, v94
	v_add_f32_e32 v67, v67, v95
	v_mul_f32_e32 v92, 0xbfb8aa3b, v64
	v_mul_f32_e32 v93, 0xbfb8aa3b, v65
	v_mul_f32_e32 v94, 0xbfb8aa3b, v66
	v_mul_f32_e32 v95, 0xbfb8aa3b, v67
	v_mul_f32_e32 v100, 0x3fb8aa3b, v64
	v_mul_f32_e32 v101, 0x3fb8aa3b, v65
	v_mul_f32_e32 v102, 0x3fb8aa3b, v66
	v_mul_f32_e32 v103, 0x3fb8aa3b, v67
	v_exp_f32_e32 v92, v92
	v_exp_f32_e32 v93, v93
	v_exp_f32_e32 v94, v94
	v_exp_f32_e32 v95, v95
	v_exp_f32_e32 v100, v100
	v_exp_f32_e32 v101, v101
	v_exp_f32_e32 v102, v102
	v_exp_f32_e32 v103, v103
	v_sub_f32_e32 v96, 1.0, v96
	v_sub_f32_e32 v97, 1.0, v97
	v_sub_f32_e32 v98, 1.0, v98
	v_sub_f32_e32 v99, 1.0, v99
	v_mul_f32_e32 v96, v96, v92
	v_mul_f32_e32 v97, v97, v93
	v_mul_f32_e32 v98, v98, v94
	v_mul_f32_e32 v99, v99, v95
	v_lshlrev_b32_e32 v92, 16, v30
	v_and_b32_e32 v93, 0xffff0000, v30
	v_lshlrev_b32_e32 v94, 16, v31
	v_and_b32_e32 v95, 0xffff0000, v31
	v_mul_f32_e32 v92, v92, v100
	v_mul_f32_e32 v93, v93, v101
	v_mul_f32_e32 v94, v94, v102
	v_mul_f32_e32 v95, v95, v103
	v_cvt_pk_bf16_f32 v108, v92, v93
	v_cvt_pk_bf16_f32 v109, v94, v95
	v_cvt_pk_bf16_f32 v110, v96, v97
	v_cvt_pk_bf16_f32 v111, v98, v99
	global_store_dwordx2 v112, v[108:109], s[2:3]
	global_store_dwordx2 v114, v[110:111], s[2:3]
	s_sub_u32 s2, s2, 0x400
	s_subb_u32 s3, s3, 0
	v_cvt_pk_bf16_f32 v120, v96, v104
	v_cvt_pk_bf16_f32 v128, v97, v105
	v_cvt_pk_bf16_f32 v136, v98, v106
	v_cvt_pk_bf16_f32 v144, v99, v107
	global_load_dwordx2 v[0:1], v113, s[0:1]
	global_load_dwordx2 v[2:3], v112, s[0:1]
	s_sub_u32 s0, s0, 0x1400
	s_subb_u32 s1, s1, 0
	global_load_dwordx2 v[4:5], v113, s[0:1]
	global_load_dwordx2 v[6:7], v112, s[0:1]
	s_sub_u32 s0, s0, 0x1400
	s_subb_u32 s1, s1, 0
	global_load_dwordx2 v[8:9], v113, s[0:1]
	global_load_dwordx2 v[10:11], v112, s[0:1]
	s_sub_u32 s0, s0, 0x1400
	s_subb_u32 s1, s1, 0
	global_load_dwordx2 v[12:13], v113, s[0:1]
	global_load_dwordx2 v[14:15], v112, s[0:1]
	s_sub_u32 s0, s0, 0x1400
	s_subb_u32 s1, s1, 0
	global_load_dwordx2 v[16:17], v113, s[0:1]
	global_load_dwordx2 v[18:19], v112, s[0:1]
	s_sub_u32 s0, s0, 0x1400
	s_subb_u32 s1, s1, 0
	global_load_dwordx2 v[20:21], v113, s[0:1]
	global_load_dwordx2 v[22:23], v112, s[0:1]
	s_sub_u32 s0, s0, 0x1400
	s_subb_u32 s1, s1, 0
	global_load_dwordx2 v[24:25], v113, s[0:1]
	global_load_dwordx2 v[26:27], v112, s[0:1]
	s_sub_u32 s0, s0, 0x1400
	s_subb_u32 s1, s1, 0
	global_load_dwordx2 v[28:29], v113, s[0:1]
	global_load_dwordx2 v[30:31], v112, s[0:1]
	s_sub_u32 s0, s0, 0x1400
	s_subb_u32 s1, s1, 0
	s_waitcnt vmcnt(32)
	v_lshlrev_b32_e32 v92, 16, v32
	v_and_b32_e32 v93, 0xffff0000, v32
	v_lshlrev_b32_e32 v94, 16, v33
	v_and_b32_e32 v95, 0xffff0000, v33
	v_mul_f32_e32 v92, 0xbfb8aa3b, v92
	v_mul_f32_e32 v93, 0xbfb8aa3b, v93
	v_mul_f32_e32 v94, 0xbfb8aa3b, v94
	v_mul_f32_e32 v95, 0xbfb8aa3b, v95
	v_exp_f32_e32 v92, v92
	v_exp_f32_e32 v93, v93
	v_exp_f32_e32 v94, v94
	v_exp_f32_e32 v95, v95
	v_add_f32_e32 v92, 1.0, v92
	v_add_f32_e32 v93, 1.0, v93
	v_add_f32_e32 v94, 1.0, v94
	v_add_f32_e32 v95, 1.0, v95
	v_rcp_f32_e32 v92, v92
	v_rcp_f32_e32 v93, v93
	v_rcp_f32_e32 v94, v94
	v_rcp_f32_e32 v95, v95
	v_fma_f32 v96, v72, v92, v68
	v_fma_f32 v97, v73, v93, v69
	v_fma_f32 v98, v74, v94, v70
	v_fma_f32 v99, v75, v95, v71
	v_cmp_gt_f32_e64 s[22:23], s30, v96
	v_cmp_gt_f32_e64 s[24:25], s30, v97
	v_cmp_gt_f32_e64 s[26:27], s30, v98
	v_cmp_gt_f32_e64 s[28:29], s30, v99
	v_cndmask_b32_e64 v92, 0, 32, s[22:23]
	v_cndmask_b32_e64 v93, 0, 32, s[24:25]
	v_cndmask_b32_e64 v94, 0, 32, s[26:27]
	v_cndmask_b32_e64 v95, 0, 32, s[28:29]
	v_ldexp_f32 v92, v96, v92
	v_ldexp_f32 v93, v97, v93
	v_ldexp_f32 v94, v98, v94
	v_ldexp_f32 v95, v99, v95
	v_log_f32_e32 v92, v92
	v_log_f32_e32 v93, v93
	v_log_f32_e32 v94, v94
	v_log_f32_e32 v95, v95
	v_mul_f32_e32 v100, 0x3f317217, v92
	v_mul_f32_e32 v101, 0x3f317217, v93
	v_mul_f32_e32 v102, 0x3f317217, v94
	v_mul_f32_e32 v103, 0x3f317217, v95
	v_fma_f32 v100, v92, s31, -v100
	v_fma_f32 v101, v93, s31, -v101
	v_fma_f32 v102, v94, s31, -v102
	v_fma_f32 v103, v95, s31, -v103
	v_fmac_f32_e32 v100, 0x3377d1cf, v92
	v_fmac_f32_e32 v101, 0x3377d1cf, v93
	v_fmac_f32_e32 v102, 0x3377d1cf, v94
	v_fmac_f32_e32 v103, 0x3377d1cf, v95
	v_fmac_f32_e32 v100, 0x3f317217, v92
; DEV u16 f2bf(float f) { return (u16)(pack2(f, f) & 0xffffu); }
; DEV float bf2f(u16 h) { return __uint_as_float(((unsigned)h) << 16); }
; DEV float sigmoid_f(float x) { return __builtin_amdgcn_rcpf(1.f + __expf(-x)); }
; DEV void phase_p15(const Params& p, int g) {
;     ...
;         for (int e = 0; e < 8; ++e) {
;           const int jj = j8 * 8 + e;
;           const int j = dir ? 63 - jj : jj;
;           const size_t tok = (size_t)cidx * 64 + j;
;           const float f = lb[cc] + (1.f - lb[cc]) * sigmoid_f(bf2f(xr[st][cc][e]));
;           G[cc] += __logf(f);
;           const float eg = __expf(G[cc]), ig = __expf(-G[cc]);
;           Qp[tok * 512 + c] = f2bf(bf2f(qr[st][cc][e]) * eg);
;           const u16 kk = f2bf((1.f - f) * ig);
;           Kp[tok * 512 + c] = kk;
;           kb[e] = kk;
;         }
;     ...
;         w.x = dir ? (kb[7] | (kb[6] << 16)) : (kb[0] | (kb[1] << 16));
;         w.y = dir ? (kb[5] | (kb[4] << 16)) : (kb[2] | (kb[3] << 16));
;         w.z = dir ? (kb[3] | (kb[2] << 16)) : (kb[4] | (kb[5] << 16));
;         w.w = dir ? (kb[1] | (kb[0] << 16)) : (kb[6] | (kb[7] << 16));
	v_fmac_f32_e32 v101, 0x3f317217, v93
	v_fmac_f32_e32 v102, 0x3f317217, v94
	v_fmac_f32_e32 v103, 0x3f317217, v95
	v_cmp_lt_f32_e64 vcc, |v92|, s34
	v_cndmask_b32_e32 v92, v92, v100, vcc
	v_cmp_lt_f32_e64 vcc, |v93|, s34
	v_cndmask_b32_e32 v93, v93, v101, vcc
	v_cmp_lt_f32_e64 vcc, |v94|, s34
	v_cndmask_b32_e32 v94, v94, v102, vcc
	v_cmp_lt_f32_e64 vcc, |v95|, s34
	v_cndmask_b32_e32 v95, v95, v103, vcc
	v_cndmask_b32_e64 v100, 0, v213, s[22:23]
	v_cndmask_b32_e64 v101, 0, v213, s[24:25]
	v_cndmask_b32_e64 v102, 0, v213, s[26:27]
	v_cndmask_b32_e64 v103, 0, v213, s[28:29]
	v_sub_f32_e32 v92, v92, v100
	v_sub_f32_e32 v93, v93, v101
	v_sub_f32_e32 v94, v94, v102
	v_sub_f32_e32 v95, v95, v103
	v_add_f32_e32 v64, v64, v92
	v_add_f32_e32 v65, v65, v93
	v_add_f32_e32 v66, v66, v94
	v_add_f32_e32 v67, v67, v95
	v_mul_f32_e32 v92, 0xbfb8aa3b, v64
	v_mul_f32_e32 v93, 0xbfb8aa3b, v65
	v_mul_f32_e32 v94, 0xbfb8aa3b, v66
	v_mul_f32_e32 v95, 0xbfb8aa3b, v67
	v_mul_f32_e32 v100, 0x3fb8aa3b, v64
	v_mul_f32_e32 v101, 0x3fb8aa3b, v65
	v_mul_f32_e32 v102, 0x3fb8aa3b, v66
	v_mul_f32_e32 v103, 0x3fb8aa3b, v67
	v_exp_f32_e32 v92, v92
	v_exp_f32_e32 v93, v93
	v_exp_f32_e32 v94, v94
	v_exp_f32_e32 v95, v95
	v_exp_f32_e32 v100, v100
	v_exp_f32_e32 v101, v101
	v_exp_f32_e32 v102, v102
	v_exp_f32_e32 v103, v103
	v_sub_f32_e32 v96, 1.0, v96
	v_sub_f32_e32 v97, 1.0, v97
	v_sub_f32_e32 v98, 1.0, v98
	v_sub_f32_e32 v99, 1.0, v99
	v_mul_f32_e32 v96, v96, v92
	v_mul_f32_e32 v97, v97, v93
	v_mul_f32_e32 v98, v98, v94
	v_mul_f32_e32 v99, v99, v95
	v_lshlrev_b32_e32 v92, 16, v34
	v_and_b32_e32 v93, 0xffff0000, v34
	v_lshlrev_b32_e32 v94, 16, v35
	v_and_b32_e32 v95, 0xffff0000, v35
	v_mul_f32_e32 v92, v92, v100
	v_mul_f32_e32 v93, v93, v101
	v_mul_f32_e32 v94, v94, v102
	v_mul_f32_e32 v95, v95, v103
	v_cvt_pk_bf16_f32 v108, v92, v93
	v_cvt_pk_bf16_f32 v109, v94, v95
	v_cvt_pk_bf16_f32 v110, v96, v97
	v_cvt_pk_bf16_f32 v111, v98, v99
	global_store_dwordx2 v112, v[108:109], s[2:3]
	global_store_dwordx2 v114, v[110:111], s[2:3]
	s_sub_u32 s2, s2, 0x400
	s_subb_u32 s3, s3, 0
	v_mov_b32_e32 v104, v96
	v_mov_b32_e32 v105, v97
	v_mov_b32_e32 v106, v98
	v_mov_b32_e32 v107, v99
	v_lshlrev_b32_e32 v92, 16, v36
	v_and_b32_e32 v93, 0xffff0000, v36
	v_lshlrev_b32_e32 v94, 16, v37
	v_and_b32_e32 v95, 0xffff0000, v37
	v_mul_f32_e32 v92, 0xbfb8aa3b, v92
	v_mul_f32_e32 v93, 0xbfb8aa3b, v93
	v_mul_f32_e32 v94, 0xbfb8aa3b, v94
	v_mul_f32_e32 v95, 0xbfb8aa3b, v95
	v_exp_f32_e32 v92, v92
	v_exp_f32_e32 v93, v93
	v_exp_f32_e32 v94, v94
	v_exp_f32_e32 v95, v95
	v_add_f32_e32 v92, 1.0, v92
	v_add_f32_e32 v93, 1.0, v93
	v_add_f32_e32 v94, 1.0, v94
	v_add_f32_e32 v95, 1.0, v95
	v_rcp_f32_e32 v92, v92
	v_rcp_f32_e32 v93, v93
	v_rcp_f32_e32 v94, v94
	v_rcp_f32_e32 v95, v95
	v_fma_f32 v96, v72, v92, v68
	v_fma_f32 v97, v73, v93, v69
	v_fma_f32 v98, v74, v94, v70
	v_fma_f32 v99, v75, v95, v71
	v_cmp_gt_f32_e64 s[22:23], s30, v96
	v_cmp_gt_f32_e64 s[24:25], s30, v97
	v_cmp_gt_f32_e64 s[26:27], s30, v98
	v_cmp_gt_f32_e64 s[28:29], s30, v99
	v_cndmask_b32_e64 v92, 0, 32, s[22:23]
	v_cndmask_b32_e64 v93, 0, 32, s[24:25]
	v_cndmask_b32_e64 v94, 0, 32, s[26:27]
	v_cndmask_b32_e64 v95, 0, 32, s[28:29]
	v_ldexp_f32 v92, v96, v92
	v_ldexp_f32 v93, v97, v93
	v_ldexp_f32 v94, v98, v94
	v_ldexp_f32 v95, v99, v95
	v_log_f32_e32 v92, v92
	v_log_f32_e32 v93, v93
	v_log_f32_e32 v94, v94
	v_log_f32_e32 v95, v95
	v_mul_f32_e32 v100, 0x3f317217, v92
	v_mul_f32_e32 v101, 0x3f317217, v93
	v_mul_f32_e32 v102, 0x3f317217, v94
	v_mul_f32_e32 v103, 0x3f317217, v95
	v_fma_f32 v100, v92, s31, -v100
	v_fma_f32 v101, v93, s31, -v101
	v_fma_f32 v102, v94, s31, -v102
	v_fma_f32 v103, v95, s31, -v103
	v_fmac_f32_e32 v100, 0x3377d1cf, v92
	v_fmac_f32_e32 v101, 0x3377d1cf, v93
	v_fmac_f32_e32 v102, 0x3377d1cf, v94
	v_fmac_f32_e32 v103, 0x3377d1cf, v95
	v_fmac_f32_e32 v100, 0x3f317217, v92
	v_fmac_f32_e32 v101, 0x3f317217, v93
	v_fmac_f32_e32 v102, 0x3f317217, v94
	v_fmac_f32_e32 v103, 0x3f317217, v95
	v_cmp_lt_f32_e64 vcc, |v92|, s34
	v_cndmask_b32_e32 v92, v92, v100, vcc
	v_cmp_lt_f32_e64 vcc, |v93|, s34
	v_cndmask_b32_e32 v93, v93, v101, vcc
	v_cmp_lt_f32_e64 vcc, |v94|, s34
	v_cndmask_b32_e32 v94, v94, v102, vcc
	v_cmp_lt_f32_e64 vcc, |v95|, s34
	v_cndmask_b32_e32 v95, v95, v103, vcc
	v_cndmask_b32_e64 v100, 0, v213, s[22:23]
	v_cndmask_b32_e64 v101, 0, v213, s[24:25]
	v_cndmask_b32_e64 v102, 0, v213, s[26:27]
	v_cndmask_b32_e64 v103, 0, v213, s[28:29]
	v_sub_f32_e32 v92, v92, v100
	v_sub_f32_e32 v93, v93, v101
	v_sub_f32_e32 v94, v94, v102
	v_sub_f32_e32 v95, v95, v103
	v_add_f32_e32 v64, v64, v92
	v_add_f32_e32 v65, v65, v93
	v_add_f32_e32 v66, v66, v94
	v_add_f32_e32 v67, v67, v95
	v_mul_f32_e32 v92, 0xbfb8aa3b, v64
	v_mul_f32_e32 v93, 0xbfb8aa3b, v65
	v_mul_f32_e32 v94, 0xbfb8aa3b, v66
	v_mul_f32_e32 v95, 0xbfb8aa3b, v67
	v_mul_f32_e32 v100, 0x3fb8aa3b, v64
	v_mul_f32_e32 v101, 0x3fb8aa3b, v65
	v_mul_f32_e32 v102, 0x3fb8aa3b, v66
	v_mul_f32_e32 v103, 0x3fb8aa3b, v67
	v_exp_f32_e32 v92, v92
	v_exp_f32_e32 v93, v93
	v_exp_f32_e32 v94, v94
	v_exp_f32_e32 v95, v95
	v_exp_f32_e32 v100, v100
	v_exp_f32_e32 v101, v101
	v_exp_f32_e32 v102, v102
	v_exp_f32_e32 v103, v103
	v_sub_f32_e32 v96, 1.0, v96
	v_sub_f32_e32 v97, 1.0, v97
	v_sub_f32_e32 v98, 1.0, v98
	v_sub_f32_e32 v99, 1.0, v99
	v_mul_f32_e32 v96, v96, v92
	v_mul_f32_e32 v97, v97, v93
	v_mul_f32_e32 v98, v98, v94
	v_mul_f32_e32 v99, v99, v95
	v_lshlrev_b32_e32 v92, 16, v38
	v_and_b32_e32 v93, 0xffff0000, v38
	v_lshlrev_b32_e32 v94, 16, v39
	v_and_b32_e32 v95, 0xffff0000, v39
	v_mul_f32_e32 v92, v92, v100
	v_mul_f32_e32 v93, v93, v101
	v_mul_f32_e32 v94, v94, v102
; DEV u16 f2bf(float f) { return (u16)(pack2(f, f) & 0xffffu); }
; DEV float bf2f(u16 h) { return __uint_as_float(((unsigned)h) << 16); }
; DEV float sigmoid_f(float x) { return __builtin_amdgcn_rcpf(1.f + __expf(-x)); }
; DEV void phase_p15(const Params& p, int g) {
;     ...
;         for (int e = 0; e < 8; ++e) {
;           const int jj = j8 * 8 + e;
;           const int j = dir ? 63 - jj : jj;
;           const size_t tok = (size_t)cidx * 64 + j;
;           const float f = lb[cc] + (1.f - lb[cc]) * sigmoid_f(bf2f(xr[st][cc][e]));
;           G[cc] += __logf(f);
;           const float eg = __expf(G[cc]), ig = __expf(-G[cc]);
;           Qp[tok * 512 + c] = f2bf(bf2f(qr[st][cc][e]) * eg);
;           const u16 kk = f2bf((1.f - f) * ig);
;           Kp[tok * 512 + c] = kk;
;           kb[e] = kk;
;         }
;     ...
;         w.x = dir ? (kb[7] | (kb[6] << 16)) : (kb[0] | (kb[1] << 16));
;         w.y = dir ? (kb[5] | (kb[4] << 16)) : (kb[2] | (kb[3] << 16));
;         w.z = dir ? (kb[3] | (kb[2] << 16)) : (kb[4] | (kb[5] << 16));
;         w.w = dir ? (kb[1] | (kb[0] << 16)) : (kb[6] | (kb[7] << 16));
	v_mul_f32_e32 v95, v95, v103
	v_cvt_pk_bf16_f32 v108, v92, v93
	v_cvt_pk_bf16_f32 v109, v94, v95
	v_cvt_pk_bf16_f32 v110, v96, v97
	v_cvt_pk_bf16_f32 v111, v98, v99
	global_store_dwordx2 v112, v[108:109], s[2:3]
	global_store_dwordx2 v114, v[110:111], s[2:3]
	s_sub_u32 s2, s2, 0x400
	s_subb_u32 s3, s3, 0
	v_cvt_pk_bf16_f32 v119, v96, v104
	v_cvt_pk_bf16_f32 v127, v97, v105
	v_cvt_pk_bf16_f32 v135, v98, v106
	v_cvt_pk_bf16_f32 v143, v99, v107
	v_lshlrev_b32_e32 v92, 16, v40
	v_and_b32_e32 v93, 0xffff0000, v40
	v_lshlrev_b32_e32 v94, 16, v41
	v_and_b32_e32 v95, 0xffff0000, v41
	v_mul_f32_e32 v92, 0xbfb8aa3b, v92
	v_mul_f32_e32 v93, 0xbfb8aa3b, v93
	v_mul_f32_e32 v94, 0xbfb8aa3b, v94
	v_mul_f32_e32 v95, 0xbfb8aa3b, v95
	v_exp_f32_e32 v92, v92
	v_exp_f32_e32 v93, v93
	v_exp_f32_e32 v94, v94
	v_exp_f32_e32 v95, v95
	v_add_f32_e32 v92, 1.0, v92
	v_add_f32_e32 v93, 1.0, v93
	v_add_f32_e32 v94, 1.0, v94
	v_add_f32_e32 v95, 1.0, v95
	v_rcp_f32_e32 v92, v92
	v_rcp_f32_e32 v93, v93
	v_rcp_f32_e32 v94, v94
	v_rcp_f32_e32 v95, v95
	v_fma_f32 v96, v72, v92, v68
	v_fma_f32 v97, v73, v93, v69
	v_fma_f32 v98, v74, v94, v70
	v_fma_f32 v99, v75, v95, v71
	v_cmp_gt_f32_e64 s[22:23], s30, v96
	v_cmp_gt_f32_e64 s[24:25], s30, v97
	v_cmp_gt_f32_e64 s[26:27], s30, v98
	v_cmp_gt_f32_e64 s[28:29], s30, v99
	v_cndmask_b32_e64 v92, 0, 32, s[22:23]
	v_cndmask_b32_e64 v93, 0, 32, s[24:25]
	v_cndmask_b32_e64 v94, 0, 32, s[26:27]
	v_cndmask_b32_e64 v95, 0, 32, s[28:29]
	v_ldexp_f32 v92, v96, v92
	v_ldexp_f32 v93, v97, v93
	v_ldexp_f32 v94, v98, v94
	v_ldexp_f32 v95, v99, v95
	v_log_f32_e32 v92, v92
	v_log_f32_e32 v93, v93
	v_log_f32_e32 v94, v94
	v_log_f32_e32 v95, v95
	v_mul_f32_e32 v100, 0x3f317217, v92
	v_mul_f32_e32 v101, 0x3f317217, v93
	v_mul_f32_e32 v102, 0x3f317217, v94
	v_mul_f32_e32 v103, 0x3f317217, v95
	v_fma_f32 v100, v92, s31, -v100
	v_fma_f32 v101, v93, s31, -v101
	v_fma_f32 v102, v94, s31, -v102
	v_fma_f32 v103, v95, s31, -v103
	v_fmac_f32_e32 v100, 0x3377d1cf, v92
	v_fmac_f32_e32 v101, 0x3377d1cf, v93
	v_fmac_f32_e32 v102, 0x3377d1cf, v94
	v_fmac_f32_e32 v103, 0x3377d1cf, v95
	v_fmac_f32_e32 v100, 0x3f317217, v92
	v_fmac_f32_e32 v101, 0x3f317217, v93
	v_fmac_f32_e32 v102, 0x3f317217, v94
	v_fmac_f32_e32 v103, 0x3f317217, v95
	v_cmp_lt_f32_e64 vcc, |v92|, s34
	v_cndmask_b32_e32 v92, v92, v100, vcc
	v_cmp_lt_f32_e64 vcc, |v93|, s34
	v_cndmask_b32_e32 v93, v93, v101, vcc
	v_cmp_lt_f32_e64 vcc, |v94|, s34
	v_cndmask_b32_e32 v94, v94, v102, vcc
	v_cmp_lt_f32_e64 vcc, |v95|, s34
	v_cndmask_b32_e32 v95, v95, v103, vcc
	v_cndmask_b32_e64 v100, 0, v213, s[22:23]
	v_cndmask_b32_e64 v101, 0, v213, s[24:25]
	v_cndmask_b32_e64 v102, 0, v213, s[26:27]
	v_cndmask_b32_e64 v103, 0, v213, s[28:29]
	v_sub_f32_e32 v92, v92, v100
	v_sub_f32_e32 v93, v93, v101
	v_sub_f32_e32 v94, v94, v102
	v_sub_f32_e32 v95, v95, v103
	v_add_f32_e32 v64, v64, v92
	v_add_f32_e32 v65, v65, v93
	v_add_f32_e32 v66, v66, v94
	v_add_f32_e32 v67, v67, v95
	v_mul_f32_e32 v92, 0xbfb8aa3b, v64
	v_mul_f32_e32 v93, 0xbfb8aa3b, v65
	v_mul_f32_e32 v94, 0xbfb8aa3b, v66
	v_mul_f32_e32 v95, 0xbfb8aa3b, v67
	v_mul_f32_e32 v100, 0x3fb8aa3b, v64
	v_mul_f32_e32 v101, 0x3fb8aa3b, v65
	v_mul_f32_e32 v102, 0x3fb8aa3b, v66
	v_mul_f32_e32 v103, 0x3fb8aa3b, v67
	v_exp_f32_e32 v92, v92
	v_exp_f32_e32 v93, v93
	v_exp_f32_e32 v94, v94
	v_exp_f32_e32 v95, v95
	v_exp_f32_e32 v100, v100
	v_exp_f32_e32 v101, v101
	v_exp_f32_e32 v102, v102
	v_exp_f32_e32 v103, v103
	v_sub_f32_e32 v96, 1.0, v96
	v_sub_f32_e32 v97, 1.0, v97
	v_sub_f32_e32 v98, 1.0, v98
	v_sub_f32_e32 v99, 1.0, v99
	v_mul_f32_e32 v96, v96, v92
	v_mul_f32_e32 v97, v97, v93
	v_mul_f32_e32 v98, v98, v94
	v_mul_f32_e32 v99, v99, v95
	v_lshlrev_b32_e32 v92, 16, v42
	v_and_b32_e32 v93, 0xffff0000, v42
	v_lshlrev_b32_e32 v94, 16, v43
	v_and_b32_e32 v95, 0xffff0000, v43
	v_mul_f32_e32 v92, v92, v100
	v_mul_f32_e32 v93, v93, v101
	v_mul_f32_e32 v94, v94, v102
	v_mul_f32_e32 v95, v95, v103
	v_cvt_pk_bf16_f32 v108, v92, v93
	v_cvt_pk_bf16_f32 v109, v94, v95
	v_cvt_pk_bf16_f32 v110, v96, v97
	v_cvt_pk_bf16_f32 v111, v98, v99
	global_store_dwordx2 v112, v[108:109], s[2:3]
	global_store_dwordx2 v114, v[110:111], s[2:3]
	s_sub_u32 s2, s2, 0x400
	s_subb_u32 s3, s3, 0
	v_mov_b32_e32 v104, v96
	v_mov_b32_e32 v105, v97
	v_mov_b32_e32 v106, v98
	v_mov_b32_e32 v107, v99
	v_lshlrev_b32_e32 v92, 16, v44
	v_and_b32_e32 v93, 0xffff0000, v44
	v_lshlrev_b32_e32 v94, 16, v45
	v_and_b32_e32 v95, 0xffff0000, v45
	v_mul_f32_e32 v92, 0xbfb8aa3b, v92
	v_mul_f32_e32 v93, 0xbfb8aa3b, v93
	v_mul_f32_e32 v94, 0xbfb8aa3b, v94
	v_mul_f32_e32 v95, 0xbfb8aa3b, v95
	v_exp_f32_e32 v92, v92
	v_exp_f32_e32 v93, v93
	v_exp_f32_e32 v94, v94
	v_exp_f32_e32 v95, v95
	v_add_f32_e32 v92, 1.0, v92
	v_add_f32_e32 v93, 1.0, v93
	v_add_f32_e32 v94, 1.0, v94
	v_add_f32_e32 v95, 1.0, v95
	v_rcp_f32_e32 v92, v92
	v_rcp_f32_e32 v93, v93
	v_rcp_f32_e32 v94, v94
	v_rcp_f32_e32 v95, v95
	v_fma_f32 v96, v72, v92, v68
	v_fma_f32 v97, v73, v93, v69
	v_fma_f32 v98, v74, v94, v70
	v_fma_f32 v99, v75, v95, v71
	v_cmp_gt_f32_e64 s[22:23], s30, v96
	v_cmp_gt_f32_e64 s[24:25], s30, v97
	v_cmp_gt_f32_e64 s[26:27], s30, v98
	v_cmp_gt_f32_e64 s[28:29], s30, v99
	v_cndmask_b32_e64 v92, 0, 32, s[22:23]
	v_cndmask_b32_e64 v93, 0, 32, s[24:25]
	v_cndmask_b32_e64 v94, 0, 32, s[26:27]
	v_cndmask_b32_e64 v95, 0, 32, s[28:29]
	v_ldexp_f32 v92, v96, v92
	v_ldexp_f32 v93, v97, v93
	v_ldexp_f32 v94, v98, v94
	v_ldexp_f32 v95, v99, v95
	v_log_f32_e32 v92, v92
	v_log_f32_e32 v93, v93
	v_log_f32_e32 v94, v94
	v_log_f32_e32 v95, v95
	v_mul_f32_e32 v100, 0x3f317217, v92
	v_mul_f32_e32 v101, 0x3f317217, v93
	v_mul_f32_e32 v102, 0x3f317217, v94
; DEV u16 f2bf(float f) { return (u16)(pack2(f, f) & 0xffffu); }
; DEV float bf2f(u16 h) { return __uint_as_float(((unsigned)h) << 16); }
; DEV float sigmoid_f(float x) { return __builtin_amdgcn_rcpf(1.f + __expf(-x)); }
; DEV void phase_p15(const Params& p, int g) {
;     ...
;         for (int e = 0; e < 8; ++e) {
;           const int jj = j8 * 8 + e;
;           const int j = dir ? 63 - jj : jj;
;           const size_t tok = (size_t)cidx * 64 + j;
;           const float f = lb[cc] + (1.f - lb[cc]) * sigmoid_f(bf2f(xr[st][cc][e]));
;           G[cc] += __logf(f);
;           const float eg = __expf(G[cc]), ig = __expf(-G[cc]);
;           Qp[tok * 512 + c] = f2bf(bf2f(qr[st][cc][e]) * eg);
;           const u16 kk = f2bf((1.f - f) * ig);
;           Kp[tok * 512 + c] = kk;
;           kb[e] = kk;
;         }
;     ...
;         w.x = dir ? (kb[7] | (kb[6] << 16)) : (kb[0] | (kb[1] << 16));
;         w.y = dir ? (kb[5] | (kb[4] << 16)) : (kb[2] | (kb[3] << 16));
;         w.z = dir ? (kb[3] | (kb[2] << 16)) : (kb[4] | (kb[5] << 16));
;         w.w = dir ? (kb[1] | (kb[0] << 16)) : (kb[6] | (kb[7] << 16));
	v_mul_f32_e32 v103, 0x3f317217, v95
	v_fma_f32 v100, v92, s31, -v100
	v_fma_f32 v101, v93, s31, -v101
	v_fma_f32 v102, v94, s31, -v102
	v_fma_f32 v103, v95, s31, -v103
	v_fmac_f32_e32 v100, 0x3377d1cf, v92
	v_fmac_f32_e32 v101, 0x3377d1cf, v93
	v_fmac_f32_e32 v102, 0x3377d1cf, v94
	v_fmac_f32_e32 v103, 0x3377d1cf, v95
	v_fmac_f32_e32 v100, 0x3f317217, v92
	v_fmac_f32_e32 v101, 0x3f317217, v93
	v_fmac_f32_e32 v102, 0x3f317217, v94
	v_fmac_f32_e32 v103, 0x3f317217, v95
	v_cmp_lt_f32_e64 vcc, |v92|, s34
	v_cndmask_b32_e32 v92, v92, v100, vcc
	v_cmp_lt_f32_e64 vcc, |v93|, s34
	v_cndmask_b32_e32 v93, v93, v101, vcc
	v_cmp_lt_f32_e64 vcc, |v94|, s34
	v_cndmask_b32_e32 v94, v94, v102, vcc
	v_cmp_lt_f32_e64 vcc, |v95|, s34
	v_cndmask_b32_e32 v95, v95, v103, vcc
	v_cndmask_b32_e64 v100, 0, v213, s[22:23]
	v_cndmask_b32_e64 v101, 0, v213, s[24:25]
	v_cndmask_b32_e64 v102, 0, v213, s[26:27]
	v_cndmask_b32_e64 v103, 0, v213, s[28:29]
	v_sub_f32_e32 v92, v92, v100
	v_sub_f32_e32 v93, v93, v101
	v_sub_f32_e32 v94, v94, v102
	v_sub_f32_e32 v95, v95, v103
	v_add_f32_e32 v64, v64, v92
	v_add_f32_e32 v65, v65, v93
	v_add_f32_e32 v66, v66, v94
	v_add_f32_e32 v67, v67, v95
	v_mul_f32_e32 v92, 0xbfb8aa3b, v64
	v_mul_f32_e32 v93, 0xbfb8aa3b, v65
	v_mul_f32_e32 v94, 0xbfb8aa3b, v66
	v_mul_f32_e32 v95, 0xbfb8aa3b, v67
	v_mul_f32_e32 v100, 0x3fb8aa3b, v64
	v_mul_f32_e32 v101, 0x3fb8aa3b, v65
	v_mul_f32_e32 v102, 0x3fb8aa3b, v66
	v_mul_f32_e32 v103, 0x3fb8aa3b, v67
	v_exp_f32_e32 v92, v92
	v_exp_f32_e32 v93, v93
	v_exp_f32_e32 v94, v94
	v_exp_f32_e32 v95, v95
	v_exp_f32_e32 v100, v100
	v_exp_f32_e32 v101, v101
	v_exp_f32_e32 v102, v102
	v_exp_f32_e32 v103, v103
	v_sub_f32_e32 v96, 1.0, v96
	v_sub_f32_e32 v97, 1.0, v97
	v_sub_f32_e32 v98, 1.0, v98
	v_sub_f32_e32 v99, 1.0, v99
	v_mul_f32_e32 v96, v96, v92
	v_mul_f32_e32 v97, v97, v93
	v_mul_f32_e32 v98, v98, v94
	v_mul_f32_e32 v99, v99, v95
	v_lshlrev_b32_e32 v92, 16, v46
	v_and_b32_e32 v93, 0xffff0000, v46
	v_lshlrev_b32_e32 v94, 16, v47
	v_and_b32_e32 v95, 0xffff0000, v47
	v_mul_f32_e32 v92, v92, v100
	v_mul_f32_e32 v93, v93, v101
	v_mul_f32_e32 v94, v94, v102
	v_mul_f32_e32 v95, v95, v103
	v_cvt_pk_bf16_f32 v108, v92, v93
	v_cvt_pk_bf16_f32 v109, v94, v95
	v_cvt_pk_bf16_f32 v110, v96, v97
	v_cvt_pk_bf16_f32 v111, v98, v99
	global_store_dwordx2 v112, v[108:109], s[2:3]
	global_store_dwordx2 v114, v[110:111], s[2:3]
	s_sub_u32 s2, s2, 0x400
	s_subb_u32 s3, s3, 0
	v_cvt_pk_bf16_f32 v118, v96, v104
	v_cvt_pk_bf16_f32 v126, v97, v105
	v_cvt_pk_bf16_f32 v134, v98, v106
	v_cvt_pk_bf16_f32 v142, v99, v107
	v_lshlrev_b32_e32 v92, 16, v48
	v_and_b32_e32 v93, 0xffff0000, v48
	v_lshlrev_b32_e32 v94, 16, v49
	v_and_b32_e32 v95, 0xffff0000, v49
	v_mul_f32_e32 v92, 0xbfb8aa3b, v92
	v_mul_f32_e32 v93, 0xbfb8aa3b, v93
	v_mul_f32_e32 v94, 0xbfb8aa3b, v94
	v_mul_f32_e32 v95, 0xbfb8aa3b, v95
	v_exp_f32_e32 v92, v92
	v_exp_f32_e32 v93, v93
	v_exp_f32_e32 v94, v94
	v_exp_f32_e32 v95, v95
	v_add_f32_e32 v92, 1.0, v92
	v_add_f32_e32 v93, 1.0, v93
	v_add_f32_e32 v94, 1.0, v94
	v_add_f32_e32 v95, 1.0, v95
	v_rcp_f32_e32 v92, v92
	v_rcp_f32_e32 v93, v93
	v_rcp_f32_e32 v94, v94
	v_rcp_f32_e32 v95, v95
	v_fma_f32 v96, v72, v92, v68
	v_fma_f32 v97, v73, v93, v69
	v_fma_f32 v98, v74, v94, v70
	v_fma_f32 v99, v75, v95, v71
	v_cmp_gt_f32_e64 s[22:23], s30, v96
	v_cmp_gt_f32_e64 s[24:25], s30, v97
	v_cmp_gt_f32_e64 s[26:27], s30, v98
	v_cmp_gt_f32_e64 s[28:29], s30, v99
	v_cndmask_b32_e64 v92, 0, 32, s[22:23]
	v_cndmask_b32_e64 v93, 0, 32, s[24:25]
	v_cndmask_b32_e64 v94, 0, 32, s[26:27]
	v_cndmask_b32_e64 v95, 0, 32, s[28:29]
	v_ldexp_f32 v92, v96, v92
	v_ldexp_f32 v93, v97, v93
	v_ldexp_f32 v94, v98, v94
	v_ldexp_f32 v95, v99, v95
	v_log_f32_e32 v92, v92
	v_log_f32_e32 v93, v93
	v_log_f32_e32 v94, v94
	v_log_f32_e32 v95, v95
	v_mul_f32_e32 v100, 0x3f317217, v92
	v_mul_f32_e32 v101, 0x3f317217, v93
	v_mul_f32_e32 v102, 0x3f317217, v94
	v_mul_f32_e32 v103, 0x3f317217, v95
	v_fma_f32 v100, v92, s31, -v100
	v_fma_f32 v101, v93, s31, -v101
	v_fma_f32 v102, v94, s31, -v102
	v_fma_f32 v103, v95, s31, -v103
	v_fmac_f32_e32 v100, 0x3377d1cf, v92
	v_fmac_f32_e32 v101, 0x3377d1cf, v93
	v_fmac_f32_e32 v102, 0x3377d1cf, v94
	v_fmac_f32_e32 v103, 0x3377d1cf, v95
	v_fmac_f32_e32 v100, 0x3f317217, v92
	v_fmac_f32_e32 v101, 0x3f317217, v93
	v_fmac_f32_e32 v102, 0x3f317217, v94
	v_fmac_f32_e32 v103, 0x3f317217, v95
	v_cmp_lt_f32_e64 vcc, |v92|, s34
	v_cndmask_b32_e32 v92, v92, v100, vcc
	v_cmp_lt_f32_e64 vcc, |v93|, s34
	v_cndmask_b32_e32 v93, v93, v101, vcc
	v_cmp_lt_f32_e64 vcc, |v94|, s34
	v_cndmask_b32_e32 v94, v94, v102, vcc
	v_cmp_lt_f32_e64 vcc, |v95|, s34
	v_cndmask_b32_e32 v95, v95, v103, vcc
	v_cndmask_b32_e64 v100, 0, v213, s[22:23]
	v_cndmask_b32_e64 v101, 0, v213, s[24:25]
	v_cndmask_b32_e64 v102, 0, v213, s[26:27]
	v_cndmask_b32_e64 v103, 0, v213, s[28:29]
	v_sub_f32_e32 v92, v92, v100
	v_sub_f32_e32 v93, v93, v101
	v_sub_f32_e32 v94, v94, v102
	v_sub_f32_e32 v95, v95, v103
	v_add_f32_e32 v64, v64, v92
	v_add_f32_e32 v65, v65, v93
	v_add_f32_e32 v66, v66, v94
	v_add_f32_e32 v67, v67, v95
	v_mul_f32_e32 v92, 0xbfb8aa3b, v64
	v_mul_f32_e32 v93, 0xbfb8aa3b, v65
	v_mul_f32_e32 v94, 0xbfb8aa3b, v66
	v_mul_f32_e32 v95, 0xbfb8aa3b, v67
	v_mul_f32_e32 v100, 0x3fb8aa3b, v64
	v_mul_f32_e32 v101, 0x3fb8aa3b, v65
	v_mul_f32_e32 v102, 0x3fb8aa3b, v66
	v_mul_f32_e32 v103, 0x3fb8aa3b, v67
	v_exp_f32_e32 v92, v92
	v_exp_f32_e32 v93, v93
	v_exp_f32_e32 v94, v94
	v_exp_f32_e32 v95, v95
	v_exp_f32_e32 v100, v100
	v_exp_f32_e32 v101, v101
	v_exp_f32_e32 v102, v102
	v_exp_f32_e32 v103, v103
	v_sub_f32_e32 v96, 1.0, v96
	v_sub_f32_e32 v97, 1.0, v97
	v_sub_f32_e32 v98, 1.0, v98
; DEV u16 f2bf(float f) { return (u16)(pack2(f, f) & 0xffffu); }
; DEV float bf2f(u16 h) { return __uint_as_float(((unsigned)h) << 16); }
; DEV float sigmoid_f(float x) { return __builtin_amdgcn_rcpf(1.f + __expf(-x)); }
; DEV void phase_p15(const Params& p, int g) {
;     ...
;         for (int e = 0; e < 8; ++e) {
;           const int jj = j8 * 8 + e;
;           const int j = dir ? 63 - jj : jj;
;           const size_t tok = (size_t)cidx * 64 + j;
;           const float f = lb[cc] + (1.f - lb[cc]) * sigmoid_f(bf2f(xr[st][cc][e]));
;           G[cc] += __logf(f);
;           const float eg = __expf(G[cc]), ig = __expf(-G[cc]);
;           Qp[tok * 512 + c] = f2bf(bf2f(qr[st][cc][e]) * eg);
;           const u16 kk = f2bf((1.f - f) * ig);
;           Kp[tok * 512 + c] = kk;
;           kb[e] = kk;
;         }
;     ...
;         w.x = dir ? (kb[7] | (kb[6] << 16)) : (kb[0] | (kb[1] << 16));
;         w.y = dir ? (kb[5] | (kb[4] << 16)) : (kb[2] | (kb[3] << 16));
;         w.z = dir ? (kb[3] | (kb[2] << 16)) : (kb[4] | (kb[5] << 16));
;         w.w = dir ? (kb[1] | (kb[0] << 16)) : (kb[6] | (kb[7] << 16));
	v_sub_f32_e32 v99, 1.0, v99
	v_mul_f32_e32 v96, v96, v92
	v_mul_f32_e32 v97, v97, v93
	v_mul_f32_e32 v98, v98, v94
	v_mul_f32_e32 v99, v99, v95
	v_lshlrev_b32_e32 v92, 16, v50
	v_and_b32_e32 v93, 0xffff0000, v50
	v_lshlrev_b32_e32 v94, 16, v51
	v_and_b32_e32 v95, 0xffff0000, v51
	v_mul_f32_e32 v92, v92, v100
	v_mul_f32_e32 v93, v93, v101
	v_mul_f32_e32 v94, v94, v102
	v_mul_f32_e32 v95, v95, v103
	v_cvt_pk_bf16_f32 v108, v92, v93
	v_cvt_pk_bf16_f32 v109, v94, v95
	v_cvt_pk_bf16_f32 v110, v96, v97
	v_cvt_pk_bf16_f32 v111, v98, v99
	global_store_dwordx2 v112, v[108:109], s[2:3]
	global_store_dwordx2 v114, v[110:111], s[2:3]
	s_sub_u32 s2, s2, 0x400
	s_subb_u32 s3, s3, 0
	v_mov_b32_e32 v104, v96
	v_mov_b32_e32 v105, v97
	v_mov_b32_e32 v106, v98
	v_mov_b32_e32 v107, v99
	v_lshlrev_b32_e32 v92, 16, v52
	v_and_b32_e32 v93, 0xffff0000, v52
	v_lshlrev_b32_e32 v94, 16, v53
	v_and_b32_e32 v95, 0xffff0000, v53
	v_mul_f32_e32 v92, 0xbfb8aa3b, v92
	v_mul_f32_e32 v93, 0xbfb8aa3b, v93
	v_mul_f32_e32 v94, 0xbfb8aa3b, v94
	v_mul_f32_e32 v95, 0xbfb8aa3b, v95
	v_exp_f32_e32 v92, v92
	v_exp_f32_e32 v93, v93
	v_exp_f32_e32 v94, v94
	v_exp_f32_e32 v95, v95
	v_add_f32_e32 v92, 1.0, v92
	v_add_f32_e32 v93, 1.0, v93
	v_add_f32_e32 v94, 1.0, v94
	v_add_f32_e32 v95, 1.0, v95
	v_rcp_f32_e32 v92, v92
	v_rcp_f32_e32 v93, v93
	v_rcp_f32_e32 v94, v94
	v_rcp_f32_e32 v95, v95
	v_fma_f32 v96, v72, v92, v68
	v_fma_f32 v97, v73, v93, v69
	v_fma_f32 v98, v74, v94, v70
	v_fma_f32 v99, v75, v95, v71
	v_cmp_gt_f32_e64 s[22:23], s30, v96
	v_cmp_gt_f32_e64 s[24:25], s30, v97
	v_cmp_gt_f32_e64 s[26:27], s30, v98
	v_cmp_gt_f32_e64 s[28:29], s30, v99
	v_cndmask_b32_e64 v92, 0, 32, s[22:23]
	v_cndmask_b32_e64 v93, 0, 32, s[24:25]
	v_cndmask_b32_e64 v94, 0, 32, s[26:27]
	v_cndmask_b32_e64 v95, 0, 32, s[28:29]
	v_ldexp_f32 v92, v96, v92
	v_ldexp_f32 v93, v97, v93
	v_ldexp_f32 v94, v98, v94
	v_ldexp_f32 v95, v99, v95
	v_log_f32_e32 v92, v92
	v_log_f32_e32 v93, v93
	v_log_f32_e32 v94, v94
	v_log_f32_e32 v95, v95
	v_mul_f32_e32 v100, 0x3f317217, v92
	v_mul_f32_e32 v101, 0x3f317217, v93
	v_mul_f32_e32 v102, 0x3f317217, v94
	v_mul_f32_e32 v103, 0x3f317217, v95
	v_fma_f32 v100, v92, s31, -v100
	v_fma_f32 v101, v93, s31, -v101
	v_fma_f32 v102, v94, s31, -v102
	v_fma_f32 v103, v95, s31, -v103
	v_fmac_f32_e32 v100, 0x3377d1cf, v92
	v_fmac_f32_e32 v101, 0x3377d1cf, v93
	v_fmac_f32_e32 v102, 0x3377d1cf, v94
	v_fmac_f32_e32 v103, 0x3377d1cf, v95
	v_fmac_f32_e32 v100, 0x3f317217, v92
	v_fmac_f32_e32 v101, 0x3f317217, v93
	v_fmac_f32_e32 v102, 0x3f317217, v94
	v_fmac_f32_e32 v103, 0x3f317217, v95
	v_cmp_lt_f32_e64 vcc, |v92|, s34
	v_cndmask_b32_e32 v92, v92, v100, vcc
	v_cmp_lt_f32_e64 vcc, |v93|, s34
	v_cndmask_b32_e32 v93, v93, v101, vcc
	v_cmp_lt_f32_e64 vcc, |v94|, s34
	v_cndmask_b32_e32 v94, v94, v102, vcc
	v_cmp_lt_f32_e64 vcc, |v95|, s34
	v_cndmask_b32_e32 v95, v95, v103, vcc
	v_cndmask_b32_e64 v100, 0, v213, s[22:23]
	v_cndmask_b32_e64 v101, 0, v213, s[24:25]
	v_cndmask_b32_e64 v102, 0, v213, s[26:27]
	v_cndmask_b32_e64 v103, 0, v213, s[28:29]
	v_sub_f32_e32 v92, v92, v100
	v_sub_f32_e32 v93, v93, v101
	v_sub_f32_e32 v94, v94, v102
	v_sub_f32_e32 v95, v95, v103
	v_add_f32_e32 v64, v64, v92
	v_add_f32_e32 v65, v65, v93
	v_add_f32_e32 v66, v66, v94
	v_add_f32_e32 v67, v67, v95
	v_mul_f32_e32 v92, 0xbfb8aa3b, v64
	v_mul_f32_e32 v93, 0xbfb8aa3b, v65
	v_mul_f32_e32 v94, 0xbfb8aa3b, v66
	v_mul_f32_e32 v95, 0xbfb8aa3b, v67
	v_mul_f32_e32 v100, 0x3fb8aa3b, v64
	v_mul_f32_e32 v101, 0x3fb8aa3b, v65
	v_mul_f32_e32 v102, 0x3fb8aa3b, v66
	v_mul_f32_e32 v103, 0x3fb8aa3b, v67
	v_exp_f32_e32 v92, v92
	v_exp_f32_e32 v93, v93
	v_exp_f32_e32 v94, v94
	v_exp_f32_e32 v95, v95
	v_exp_f32_e32 v100, v100
	v_exp_f32_e32 v101, v101
	v_exp_f32_e32 v102, v102
	v_exp_f32_e32 v103, v103
	v_sub_f32_e32 v96, 1.0, v96
	v_sub_f32_e32 v97, 1.0, v97
	v_sub_f32_e32 v98, 1.0, v98
	v_sub_f32_e32 v99, 1.0, v99
	v_mul_f32_e32 v96, v96, v92
	v_mul_f32_e32 v97, v97, v93
	v_mul_f32_e32 v98, v98, v94
	v_mul_f32_e32 v99, v99, v95
	v_lshlrev_b32_e32 v92, 16, v54
	v_and_b32_e32 v93, 0xffff0000, v54
	v_lshlrev_b32_e32 v94, 16, v55
	v_and_b32_e32 v95, 0xffff0000, v55
	v_mul_f32_e32 v92, v92, v100
	v_mul_f32_e32 v93, v93, v101
	v_mul_f32_e32 v94, v94, v102
	v_mul_f32_e32 v95, v95, v103
	v_cvt_pk_bf16_f32 v108, v92, v93
	v_cvt_pk_bf16_f32 v109, v94, v95
	v_cvt_pk_bf16_f32 v110, v96, v97
	v_cvt_pk_bf16_f32 v111, v98, v99
	global_store_dwordx2 v112, v[108:109], s[2:3]
	global_store_dwordx2 v114, v[110:111], s[2:3]
	s_sub_u32 s2, s2, 0x400
	s_subb_u32 s3, s3, 0
	v_cvt_pk_bf16_f32 v117, v96, v104
	v_cvt_pk_bf16_f32 v125, v97, v105
	v_cvt_pk_bf16_f32 v133, v98, v106
	v_cvt_pk_bf16_f32 v141, v99, v107
	v_lshlrev_b32_e32 v92, 16, v56
	v_and_b32_e32 v93, 0xffff0000, v56
	v_lshlrev_b32_e32 v94, 16, v57
	v_and_b32_e32 v95, 0xffff0000, v57
	v_mul_f32_e32 v92, 0xbfb8aa3b, v92
	v_mul_f32_e32 v93, 0xbfb8aa3b, v93
	v_mul_f32_e32 v94, 0xbfb8aa3b, v94
	v_mul_f32_e32 v95, 0xbfb8aa3b, v95
	v_exp_f32_e32 v92, v92
	v_exp_f32_e32 v93, v93
	v_exp_f32_e32 v94, v94
	v_exp_f32_e32 v95, v95
	v_add_f32_e32 v92, 1.0, v92
	v_add_f32_e32 v93, 1.0, v93
	v_add_f32_e32 v94, 1.0, v94
	v_add_f32_e32 v95, 1.0, v95
	v_rcp_f32_e32 v92, v92
	v_rcp_f32_e32 v93, v93
	v_rcp_f32_e32 v94, v94
	v_rcp_f32_e32 v95, v95
	v_fma_f32 v96, v72, v92, v68
	v_fma_f32 v97, v73, v93, v69
	v_fma_f32 v98, v74, v94, v70
	v_fma_f32 v99, v75, v95, v71
	v_cmp_gt_f32_e64 s[22:23], s30, v96
	v_cmp_gt_f32_e64 s[24:25], s30, v97
	v_cmp_gt_f32_e64 s[26:27], s30, v98
	v_cmp_gt_f32_e64 s[28:29], s30, v99
	v_cndmask_b32_e64 v92, 0, 32, s[22:23]
	v_cndmask_b32_e64 v93, 0, 32, s[24:25]
	v_cndmask_b32_e64 v94, 0, 32, s[26:27]
; DEV u16 f2bf(float f) { return (u16)(pack2(f, f) & 0xffffu); }
; DEV float bf2f(u16 h) { return __uint_as_float(((unsigned)h) << 16); }
; DEV float sigmoid_f(float x) { return __builtin_amdgcn_rcpf(1.f + __expf(-x)); }
; DEV void phase_p15(const Params& p, int g) {
;     ...
;         for (int e = 0; e < 8; ++e) {
;           const int jj = j8 * 8 + e;
;           const int j = dir ? 63 - jj : jj;
;           const size_t tok = (size_t)cidx * 64 + j;
;           const float f = lb[cc] + (1.f - lb[cc]) * sigmoid_f(bf2f(xr[st][cc][e]));
;           G[cc] += __logf(f);
;           const float eg = __expf(G[cc]), ig = __expf(-G[cc]);
;           Qp[tok * 512 + c] = f2bf(bf2f(qr[st][cc][e]) * eg);
;           const u16 kk = f2bf((1.f - f) * ig);
;           Kp[tok * 512 + c] = kk;
;           kb[e] = kk;
;         }
	v_cndmask_b32_e64 v95, 0, 32, s[28:29]
	v_ldexp_f32 v92, v96, v92
	v_ldexp_f32 v93, v97, v93
	v_ldexp_f32 v94, v98, v94
	v_ldexp_f32 v95, v99, v95
	v_log_f32_e32 v92, v92
	v_log_f32_e32 v93, v93
	v_log_f32_e32 v94, v94
	v_log_f32_e32 v95, v95
	v_mul_f32_e32 v100, 0x3f317217, v92
	v_mul_f32_e32 v101, 0x3f317217, v93
	v_mul_f32_e32 v102, 0x3f317217, v94
	v_mul_f32_e32 v103, 0x3f317217, v95
	v_fma_f32 v100, v92, s31, -v100
	v_fma_f32 v101, v93, s31, -v101
	v_fma_f32 v102, v94, s31, -v102
	v_fma_f32 v103, v95, s31, -v103
	v_fmac_f32_e32 v100, 0x3377d1cf, v92
	v_fmac_f32_e32 v101, 0x3377d1cf, v93
	v_fmac_f32_e32 v102, 0x3377d1cf, v94
	v_fmac_f32_e32 v103, 0x3377d1cf, v95
	v_fmac_f32_e32 v100, 0x3f317217, v92
	v_fmac_f32_e32 v101, 0x3f317217, v93
	v_fmac_f32_e32 v102, 0x3f317217, v94
	v_fmac_f32_e32 v103, 0x3f317217, v95
	v_cmp_lt_f32_e64 vcc, |v92|, s34
	v_cndmask_b32_e32 v92, v92, v100, vcc
	v_cmp_lt_f32_e64 vcc, |v93|, s34
	v_cndmask_b32_e32 v93, v93, v101, vcc
	v_cmp_lt_f32_e64 vcc, |v94|, s34
	v_cndmask_b32_e32 v94, v94, v102, vcc
	v_cmp_lt_f32_e64 vcc, |v95|, s34
	v_cndmask_b32_e32 v95, v95, v103, vcc
	v_cndmask_b32_e64 v100, 0, v213, s[22:23]
	v_cndmask_b32_e64 v101, 0, v213, s[24:25]
	v_cndmask_b32_e64 v102, 0, v213, s[26:27]
	v_cndmask_b32_e64 v103, 0, v213, s[28:29]
	v_sub_f32_e32 v92, v92, v100
	v_sub_f32_e32 v93, v93, v101
	v_sub_f32_e32 v94, v94, v102
	v_sub_f32_e32 v95, v95, v103
	v_add_f32_e32 v64, v64, v92
	v_add_f32_e32 v65, v65, v93
	v_add_f32_e32 v66, v66, v94
	v_add_f32_e32 v67, v67, v95
	v_mul_f32_e32 v92, 0xbfb8aa3b, v64
	v_mul_f32_e32 v93, 0xbfb8aa3b, v65
	v_mul_f32_e32 v94, 0xbfb8aa3b, v66
	v_mul_f32_e32 v95, 0xbfb8aa3b, v67
	v_mul_f32_e32 v100, 0x3fb8aa3b, v64
	v_mul_f32_e32 v101, 0x3fb8aa3b, v65
	v_mul_f32_e32 v102, 0x3fb8aa3b, v66
	v_mul_f32_e32 v103, 0x3fb8aa3b, v67
	v_exp_f32_e32 v92, v92
	v_exp_f32_e32 v93, v93
	v_exp_f32_e32 v94, v94
	v_exp_f32_e32 v95, v95
	v_exp_f32_e32 v100, v100
	v_exp_f32_e32 v101, v101
	v_exp_f32_e32 v102, v102
	v_exp_f32_e32 v103, v103
	v_sub_f32_e32 v96, 1.0, v96
	v_sub_f32_e32 v97, 1.0, v97
	v_sub_f32_e32 v98, 1.0, v98
	v_sub_f32_e32 v99, 1.0, v99
	v_mul_f32_e32 v96, v96, v92
	v_mul_f32_e32 v97, v97, v93
	v_mul_f32_e32 v98, v98, v94
	v_mul_f32_e32 v99, v99, v95
	v_lshlrev_b32_e32 v92, 16, v58
	v_and_b32_e32 v93, 0xffff0000, v58
	v_lshlrev_b32_e32 v94, 16, v59
	v_and_b32_e32 v95, 0xffff0000, v59
	v_mul_f32_e32 v92, v92, v100
	v_mul_f32_e32 v93, v93, v101
	v_mul_f32_e32 v94, v94, v102
	v_mul_f32_e32 v95, v95, v103
	v_cvt_pk_bf16_f32 v108, v92, v93
	v_cvt_pk_bf16_f32 v109, v94, v95
	v_cvt_pk_bf16_f32 v110, v96, v97
	v_cvt_pk_bf16_f32 v111, v98, v99
	global_store_dwordx2 v112, v[108:109], s[2:3]
	global_store_dwordx2 v114, v[110:111], s[2:3]
	s_sub_u32 s2, s2, 0x400
	s_subb_u32 s3, s3, 0
	v_mov_b32_e32 v104, v96
	v_mov_b32_e32 v105, v97
	v_mov_b32_e32 v106, v98
	v_mov_b32_e32 v107, v99
	v_lshlrev_b32_e32 v92, 16, v60
	v_and_b32_e32 v93, 0xffff0000, v60
	v_lshlrev_b32_e32 v94, 16, v61
	v_and_b32_e32 v95, 0xffff0000, v61
	v_mul_f32_e32 v92, 0xbfb8aa3b, v92
	v_mul_f32_e32 v93, 0xbfb8aa3b, v93
	v_mul_f32_e32 v94, 0xbfb8aa3b, v94
	v_mul_f32_e32 v95, 0xbfb8aa3b, v95
	v_exp_f32_e32 v92, v92
	v_exp_f32_e32 v93, v93
	v_exp_f32_e32 v94, v94
	v_exp_f32_e32 v95, v95
	v_add_f32_e32 v92, 1.0, v92
	v_add_f32_e32 v93, 1.0, v93
	v_add_f32_e32 v94, 1.0, v94
	v_add_f32_e32 v95, 1.0, v95
	v_rcp_f32_e32 v92, v92
	v_rcp_f32_e32 v93, v93
	v_rcp_f32_e32 v94, v94
	v_rcp_f32_e32 v95, v95
	v_fma_f32 v96, v72, v92, v68
	v_fma_f32 v97, v73, v93, v69
	v_fma_f32 v98, v74, v94, v70
	v_fma_f32 v99, v75, v95, v71
	v_cmp_gt_f32_e64 s[22:23], s30, v96
	v_cmp_gt_f32_e64 s[24:25], s30, v97
	v_cmp_gt_f32_e64 s[26:27], s30, v98
	v_cmp_gt_f32_e64 s[28:29], s30, v99
	v_cndmask_b32_e64 v92, 0, 32, s[22:23]
	v_cndmask_b32_e64 v93, 0, 32, s[24:25]
	v_cndmask_b32_e64 v94, 0, 32, s[26:27]
	v_cndmask_b32_e64 v95, 0, 32, s[28:29]
	v_ldexp_f32 v92, v96, v92
	v_ldexp_f32 v93, v97, v93
	v_ldexp_f32 v94, v98, v94
	v_ldexp_f32 v95, v99, v95
	v_log_f32_e32 v92, v92
	v_log_f32_e32 v93, v93
	v_log_f32_e32 v94, v94
	v_log_f32_e32 v95, v95
	v_mul_f32_e32 v100, 0x3f317217, v92
	v_mul_f32_e32 v101, 0x3f317217, v93
	v_mul_f32_e32 v102, 0x3f317217, v94
	v_mul_f32_e32 v103, 0x3f317217, v95
	v_fma_f32 v100, v92, s31, -v100
	v_fma_f32 v101, v93, s31, -v101
	v_fma_f32 v102, v94, s31, -v102
	v_fma_f32 v103, v95, s31, -v103
	v_fmac_f32_e32 v100, 0x3377d1cf, v92
	v_fmac_f32_e32 v101, 0x3377d1cf, v93
	v_fmac_f32_e32 v102, 0x3377d1cf, v94
	v_fmac_f32_e32 v103, 0x3377d1cf, v95
	v_fmac_f32_e32 v100, 0x3f317217, v92
	v_fmac_f32_e32 v101, 0x3f317217, v93
	v_fmac_f32_e32 v102, 0x3f317217, v94
	v_fmac_f32_e32 v103, 0x3f317217, v95
	v_cmp_lt_f32_e64 vcc, |v92|, s34
; DEV void phase_p15(const Params& p, int g) {
;     ...
;         const int s0 = dir ? 56 - 8 * j8 : 8 * j8;
;         uint4 w;
;         w.x = dir ? (kb[7] | (kb[6] << 16)) : (kb[0] | (kb[1] << 16));
;         w.y = dir ? (kb[5] | (kb[4] << 16)) : (kb[2] | (kb[3] << 16));
;         w.z = dir ? (kb[3] | (kb[2] << 16)) : (kb[4] | (kb[5] << 16));
;         w.w = dir ? (kb[1] | (kb[0] << 16)) : (kb[6] | (kb[7] << 16));
;         *(uint4*)(KT + (((size_t)cidx * 2 + dir) * 512 + c) * 64 + s0) = w;
;       }
;     }
;     ...
; #pragma unroll
;     for (int cc = 0; cc < 2; ++cc) DEC[((size_t)dir * 512 + cidx) * 512 + tid + 256 * cc] = __expf(G[cc]);
	v_cndmask_b32_e32 v92, v92, v100, vcc
	v_cmp_lt_f32_e64 vcc, |v93|, s34
	v_cndmask_b32_e32 v93, v93, v101, vcc
	v_cmp_lt_f32_e64 vcc, |v94|, s34
	v_cndmask_b32_e32 v94, v94, v102, vcc
	v_cmp_lt_f32_e64 vcc, |v95|, s34
	v_cndmask_b32_e32 v95, v95, v103, vcc
	v_cndmask_b32_e64 v100, 0, v213, s[22:23]
	v_cndmask_b32_e64 v101, 0, v213, s[24:25]
	v_cndmask_b32_e64 v102, 0, v213, s[26:27]
	v_cndmask_b32_e64 v103, 0, v213, s[28:29]
	v_sub_f32_e32 v92, v92, v100
	v_sub_f32_e32 v93, v93, v101
	v_sub_f32_e32 v94, v94, v102
	v_sub_f32_e32 v95, v95, v103
	v_add_f32_e32 v64, v64, v92
	v_add_f32_e32 v65, v65, v93
	v_add_f32_e32 v66, v66, v94
	v_add_f32_e32 v67, v67, v95
	v_mul_f32_e32 v92, 0xbfb8aa3b, v64
	v_mul_f32_e32 v93, 0xbfb8aa3b, v65
	v_mul_f32_e32 v94, 0xbfb8aa3b, v66
	v_mul_f32_e32 v95, 0xbfb8aa3b, v67
	v_mul_f32_e32 v100, 0x3fb8aa3b, v64
	v_mul_f32_e32 v101, 0x3fb8aa3b, v65
	v_mul_f32_e32 v102, 0x3fb8aa3b, v66
	v_mul_f32_e32 v103, 0x3fb8aa3b, v67
	v_exp_f32_e32 v92, v92
	v_exp_f32_e32 v93, v93
	v_exp_f32_e32 v94, v94
	v_exp_f32_e32 v95, v95
	v_exp_f32_e32 v100, v100
	v_exp_f32_e32 v101, v101
	v_exp_f32_e32 v102, v102
	v_exp_f32_e32 v103, v103
	v_sub_f32_e32 v96, 1.0, v96
	v_sub_f32_e32 v97, 1.0, v97
	v_sub_f32_e32 v98, 1.0, v98
	v_sub_f32_e32 v99, 1.0, v99
	v_mul_f32_e32 v96, v96, v92
	v_mul_f32_e32 v97, v97, v93
	v_mul_f32_e32 v98, v98, v94
	v_mul_f32_e32 v99, v99, v95
	v_lshlrev_b32_e32 v92, 16, v62
	v_and_b32_e32 v93, 0xffff0000, v62
	v_lshlrev_b32_e32 v94, 16, v63
	v_and_b32_e32 v95, 0xffff0000, v63
	v_mul_f32_e32 v92, v92, v100
	v_mul_f32_e32 v93, v93, v101
	v_mul_f32_e32 v94, v94, v102
	v_mul_f32_e32 v95, v95, v103
	v_cvt_pk_bf16_f32 v108, v92, v93
	v_cvt_pk_bf16_f32 v109, v94, v95
	v_cvt_pk_bf16_f32 v110, v96, v97
	v_cvt_pk_bf16_f32 v111, v98, v99
	global_store_dwordx2 v112, v[108:109], s[2:3]
	global_store_dwordx2 v114, v[110:111], s[2:3]
	s_sub_u32 s2, s2, 0x400
	s_subb_u32 s3, s3, 0
	v_cvt_pk_bf16_f32 v116, v96, v104
	v_cvt_pk_bf16_f32 v124, v97, v105
	v_cvt_pk_bf16_f32 v132, v98, v106
	v_cvt_pk_bf16_f32 v140, v99, v107
	global_store_dwordx4 v115, v[116:119], s[4:5]
	global_store_dwordx4 v115, v[120:123], s[4:5] offset:16
	global_store_dwordx4 v115, v[124:127], s[4:5] offset:128
	global_store_dwordx4 v115, v[128:131], s[4:5] offset:144
	global_store_dwordx4 v115, v[132:135], s[4:5] offset:256
	global_store_dwordx4 v115, v[136:139], s[4:5] offset:272
	global_store_dwordx4 v115, v[140:143], s[4:5] offset:384
	global_store_dwordx4 v115, v[144:147], s[4:5] offset:400
	s_sub_u32 s4, s4, 32
	s_subb_u32 s5, s5, 0
	global_load_dwordx2 v[32:33], v113, s[0:1]
	global_load_dwordx2 v[34:35], v112, s[0:1]
	s_sub_u32 s0, s0, 0x1400
	s_subb_u32 s1, s1, 0
	global_load_dwordx2 v[36:37], v113, s[0:1]
	global_load_dwordx2 v[38:39], v112, s[0:1]
	s_sub_u32 s0, s0, 0x1400
	s_subb_u32 s1, s1, 0
	global_load_dwordx2 v[40:41], v113, s[0:1]
	global_load_dwordx2 v[42:43], v112, s[0:1]
	s_sub_u32 s0, s0, 0x1400
	s_subb_u32 s1, s1, 0
	global_load_dwordx2 v[44:45], v113, s[0:1]
	global_load_dwordx2 v[46:47], v112, s[0:1]
	s_sub_u32 s0, s0, 0x1400
	s_subb_u32 s1, s1, 0
	global_load_dwordx2 v[48:49], v113, s[0:1]
	global_load_dwordx2 v[50:51], v112, s[0:1]
	s_sub_u32 s0, s0, 0x1400
	s_subb_u32 s1, s1, 0
	global_load_dwordx2 v[52:53], v113, s[0:1]
	global_load_dwordx2 v[54:55], v112, s[0:1]
	s_sub_u32 s0, s0, 0x1400
	s_subb_u32 s1, s1, 0
	global_load_dwordx2 v[56:57], v113, s[0:1]
	global_load_dwordx2 v[58:59], v112, s[0:1]
	s_sub_u32 s0, s0, 0x1400
	s_subb_u32 s1, s1, 0
	global_load_dwordx2 v[60:61], v113, s[0:1]
	global_load_dwordx2 v[62:63], v112, s[0:1]
	s_sub_u32 s0, s0, 0x1400
	s_subb_u32 s1, s1, 0
	s_add_u32 s35, s35, 1
	s_cmp_lt_u32 s35, 4
	s_cbranch_scc1 .Lp15_d1_loop
.Lp15_done:
	global_store_dwordx4 v164, v[100:103], s[6:7]
	s_waitcnt vmcnt(0)
	v_readlane_b32 s72, v251, 45
	v_readlane_b32 s74, v251, 47
	v_readlane_b32 s75, v251, 48
	v_readlane_b32 s88, v251, 54
	v_readlane_b32 s82, v251, 58
	v_readlane_b32 s86, v251, 60
	v_readlane_b32 s74, v252, 0
	v_readlane_b32 s64, v252, 19
	v_readlane_b32 s66, v252, 21
	v_readlane_b32 s76, v251, 49
	v_readlane_b32 s77, v251, 50
	v_readlane_b32 s78, v251, 51
	v_readlane_b32 s79, v251, 52
	v_readlane_b32 s80, v251, 53
	v_readlane_b32 s89, v251, 55
	v_readlane_b32 s90, v251, 56
	v_readlane_b32 s83, v251, 59
	v_readlane_b32 s87, v251, 61
	v_readlane_b32 s81, v251, 62
	v_readlane_b32 s92, v251, 63
	v_readlane_b32 s75, v252, 1
	v_readlane_b32 s93, v252, 2
	v_readlane_b32 s94, v252, 3
	v_readlane_b32 s95, v252, 4
	v_readlane_b32 s96, v252, 5
	s_movk_i32 s60, 0x90
	s_movk_i32 s61, 0x80
	s_mov_b32 s62, 0x8000
	v_readlane_b32 s65, v252, 20
	v_readlane_b32 s67, v252, 22
	v_readlane_b32 s73, v251, 46
	v_readlane_b32 s91, v251, 57
	v_readlane_b32 s97, v252, 6
